# v21 + redundant post-barrier lgkmcnt(0) before each GEMM MMA segment removed (36 sites)
# baseline (speedup 1.0000x reference)
; #define PG8_STAGE(bufoff, gbase, voff) do { _Pragma("unroll") for (int _i = 0; _i < 2; ++_i) \
;         __builtin_amdgcn_global_load_lds((const unsigned*)((const char*)(gbase) + (voff)[_i]), (PG8_LAS unsigned*)(lds + (bufoff) + ldsw + _i * 8192), 16, 0, 0); } while (0)
; #define PG8_LDA(dst, b, h) do { _Pragma("unroll") for (int m = 0; m < 4; ++m) _Pragma("unroll") for (int k = 0; k < 2; ++k) dst[m][k] = *(const PG8_LAS bf16x8*)(lds + PG8_SA(b, h) + aoff + m * 2048 + k * 1024); } while (0)
; #define PG8_LDB(dst, b, h) do { _Pragma("unroll") for (int n = 0; n < 2; ++n) _Pragma("unroll") for (int k = 0; k < 2; ++k) dst[n][k] = *(const PG8_LAS bf16x8*)(lds + PG8_SB(b, h) + boff + n * 2048 + k * 1024); } while (0)
; #define PG8_WAIT_V(n) asm volatile("s_waitcnt vmcnt(" #n ")" ::: "memory")
; #define PG8_WAIT_L(n) asm volatile("s_waitcnt lgkmcnt(" #n ")" ::: "memory")
; #define PG8_BAR __builtin_amdgcn_s_barrier()
; #define PG8_SCHED __builtin_amdgcn_sched_barrier(0)
; template <class Epi, class Sched, bool ALIGN_EPI = false, bool SP2 = false>
; __device__ __forceinline__ void gemm_phase(PG8_LAS unsigned char* lds, const Gemm g, const Sched& S, const Epi& E) {
;     ...
;         const char* nA = has_next ? (const char*)g.A + (size_t)nxt.pm * tstepA : cA; const char* nB = has_next ? (const char*)g.Bt + (size_t)nxt.pn * tstepB : cB;
;         for (int t = 0; t < nt; t += 2) {
;             const bool last = (t == nt - 2);
;             const char* a1 = cA + (size_t)(t + 1) * kstep;
;             const char* a2 = last ? nA : cA + (size_t)(t + 2) * kstep; const char* b2 = last ? nB : cB + (size_t)(t + 2) * kstep;
;             const char* a3 = a2 + kstep; const char* b3 = b2 + kstep;
;             if (last && has_next) S.a_ready(nxt);
;             if constexpr (SP2) {
;             PG8_LDB(B0, 0, 0); PG8_LDB(B1, 0, 1); PG8_SCHED; PG8_LDA(At, 0, 0); PG8_STAGE(PG8_SA(1, 1), a1 + hstepA, voffA);
;             PG8_WAIT_V(8); PG8_WAIT_L(0); PG8_BAR; PG8_MMA(0, 0, At, B0); PG8_MMA(0, 1, At, B1); PG8_BAR; PG8_SCHED;
;             PG8_LDA(At, 0, 1); PG8_STAGE(PG8_SB(0, 0), b2, voffB); PG8_STAGE(PG8_SB(0, 1), b2 + hstepB, voffB); PG8_STAGE(PG8_SA(0, 0), a2, voffA);
;             PG8_WAIT_V(8); PG8_WAIT_L(0); PG8_BAR; PG8_MMA(1, 0, At, B0); PG8_MMA(1, 1, At, B1); PG8_BAR; PG8_SCHED;
.LBB0_163:
	ds_read_b128 v[0:3], v143
	ds_read_b128 v[4:7], v143 offset:1024
	ds_read_b128 v[8:11], v143 offset:2048
	ds_read_b128 v[12:15], v143 offset:3072
	ds_read_b128 v[16:19], v144
	ds_read_b128 v[20:23], v144 offset:1024
	ds_read_b128 v[24:27], v144 offset:2048
	ds_read_b128 v[28:31], v144 offset:3072
	s_ashr_i32 s31, s30, 31
	s_lshl_b64 s[34:35], s[30:31], 17
	s_add_u32 s34, s54, s34
	s_addc_u32 s35, s55, s35
	s_and_b64 s[36:37], s[0:1], exec
	s_cselect_b32 s51, s35, s39
	s_cselect_b32 s50, s34, s38
	s_ashr_i32 s29, s28, 31
	s_lshl_b64 s[36:37], s[28:29], 17
	s_add_u32 s36, s2, s36
	s_addc_u32 s37, s3, s37
	s_and_b64 s[44:45], s[0:1], exec
	s_cselect_b32 s47, s37, s41
	s_cselect_b32 s46, s36, s40
	s_add_u32 s44, s38, 0x10080
	s_addc_u32 s45, s39, 0
	s_add_i32 s63, s9, 0xc000
	s_mov_b32 m0, s63
	s_add_i32 s29, s9, 0xe000
	ds_read_b128 v[32:35], v145
	ds_read_b128 v[36:39], v145 offset:1024
	ds_read_b128 v[40:43], v145 offset:2048
	ds_read_b128 v[44:47], v145 offset:3072
	ds_read_b128 v[48:51], v145 offset:4096
	ds_read_b128 v[52:55], v145 offset:5120
	ds_read_b128 v[56:59], v145 offset:6144
	ds_read_b128 v[60:63], v145 offset:7168
	global_load_lds_dwordx4 v128, s[44:45]
	s_mov_b32 m0, s29
	s_nop 0
	global_load_lds_dwordx4 v132, s[44:45]
	s_waitcnt vmcnt(8)
	s_waitcnt lgkmcnt(0)
	s_barrier
	v_mfma_f32_16x16x32_bf16 v[64:67], v[0:3], v[32:35], 0
	v_mfma_f32_16x16x32_bf16 v[68:71], v[8:11], v[32:35], 0
	v_mfma_f32_16x16x32_bf16 v[72:75], v[0:3], v[40:43], 0
	v_mfma_f32_16x16x32_bf16 v[76:79], v[8:11], v[40:43], 0
	v_mfma_f32_16x16x32_bf16 v[80:83], v[0:3], v[48:51], 0
	v_mfma_f32_16x16x32_bf16 v[84:87], v[8:11], v[48:51], 0
	v_mfma_f32_16x16x32_bf16 v[88:91], v[0:3], v[56:59], 0
	v_mfma_f32_16x16x32_bf16 v[92:95], v[8:11], v[56:59], 0
	v_mfma_f32_16x16x32_bf16 v[64:67], v[4:7], v[36:39], v[64:67]
	v_mfma_f32_16x16x32_bf16 v[68:71], v[12:15], v[36:39], v[68:71]
	v_mfma_f32_16x16x32_bf16 v[72:75], v[4:7], v[44:47], v[72:75]
	v_mfma_f32_16x16x32_bf16 v[76:79], v[12:15], v[44:47], v[76:79]
	v_mfma_f32_16x16x32_bf16 v[80:83], v[4:7], v[52:55], v[80:83]
	v_mfma_f32_16x16x32_bf16 v[84:87], v[12:15], v[52:55], v[84:87]
	v_mfma_f32_16x16x32_bf16 v[88:91], v[4:7], v[60:63], v[88:91]
	v_mfma_f32_16x16x32_bf16 v[92:95], v[12:15], v[60:63], v[92:95]
	v_mfma_f32_16x16x32_bf16 v[96:99], v[16:19], v[32:35], 0
	v_mfma_f32_16x16x32_bf16 v[32:35], v[24:27], v[32:35], 0
	v_mfma_f32_16x16x32_bf16 v[96:99], v[20:23], v[36:39], v[96:99]
	v_mfma_f32_16x16x32_bf16 v[32:35], v[28:31], v[36:39], v[32:35]
	v_mfma_f32_16x16x32_bf16 v[36:39], v[16:19], v[40:43], 0
	v_mfma_f32_16x16x32_bf16 v[40:43], v[24:27], v[40:43], 0
	v_mfma_f32_16x16x32_bf16 v[36:39], v[20:23], v[44:47], v[36:39]
	v_mfma_f32_16x16x32_bf16 v[40:43], v[28:31], v[44:47], v[40:43]
	v_mfma_f32_16x16x32_bf16 v[44:47], v[16:19], v[48:51], 0
	v_mfma_f32_16x16x32_bf16 v[48:51], v[24:27], v[48:51], 0
	v_mfma_f32_16x16x32_bf16 v[44:47], v[20:23], v[52:55], v[44:47]
	v_mfma_f32_16x16x32_bf16 v[48:51], v[28:31], v[52:55], v[48:51]
	v_mfma_f32_16x16x32_bf16 v[52:55], v[16:19], v[56:59], 0
	v_mfma_f32_16x16x32_bf16 v[56:59], v[24:27], v[56:59], 0
	v_mfma_f32_16x16x32_bf16 v[52:55], v[20:23], v[60:63], v[52:55]
	v_mfma_f32_16x16x32_bf16 v[56:59], v[28:31], v[60:63], v[56:59]
	s_barrier
	s_add_i32 s48, s59, s8
	v_lshl_add_u64 v[190:191], s[40:41], 0, v[130:131]
	s_add_i32 s31, s48, 0x2000
	v_lshl_add_u64 v[146:147], v[190:191], 0, s[22:23]
	s_mov_b32 m0, s48
	v_lshl_add_u64 v[216:217], s[40:41], 0, v[134:135]
	s_add_u32 s64, s40, 0x10100
	ds_read_b128 v[60:63], v145 offset:16384
	ds_read_b128 v[100:103], v145 offset:17408
	ds_read_b128 v[104:107], v145 offset:18432
	ds_read_b128 v[108:111], v145 offset:19456
	ds_read_b128 v[112:115], v145 offset:20480
	ds_read_b128 v[116:119], v145 offset:21504
	ds_read_b128 v[120:123], v145 offset:22528
	ds_read_b128 v[124:127], v145 offset:23552
	global_load_lds_dwordx4 v[146:147], off
	v_lshl_add_u64 v[146:147], v[216:217], 0, s[22:23]
	s_mov_b32 m0, s31
	s_addc_u32 s65, s41, 0
	s_add_i32 s44, s60, s8
	global_load_lds_dwordx4 v[146:147], off
	s_mov_b32 m0, s44
	s_add_i32 s45, s44, 0x2000
	global_load_lds_dwordx4 v130, s[64:65]
	s_mov_b32 m0, s45
	v_lshl_add_u64 v[218:219], s[38:39], 0, v[128:129]
	global_load_lds_dwordx4 v134, s[64:65]
	v_lshl_add_u64 v[146:147], v[218:219], 0, s[22:23]
	s_mov_b32 m0, s9
	v_lshl_add_u64 v[220:221], s[38:39], 0, v[132:133]
	global_load_lds_dwordx4 v[146:147], off
	v_lshl_add_u64 v[146:147], v[220:221], 0, s[22:23]
	s_mov_b32 m0, s27
	s_nop 0
	global_load_lds_dwordx4 v[146:147], off
	s_waitcnt vmcnt(8)
	s_waitcnt lgkmcnt(0)
	s_barrier
; #define PG8_STAGE(bufoff, gbase, voff) do { _Pragma("unroll") for (int _i = 0; _i < 2; ++_i) \
;         __builtin_amdgcn_global_load_lds((const unsigned*)((const char*)(gbase) + (voff)[_i]), (PG8_LAS unsigned*)(lds + (bufoff) + ldsw + _i * 8192), 16, 0, 0); } while (0)
; #define PG8_LDA(dst, b, h) do { _Pragma("unroll") for (int m = 0; m < 4; ++m) _Pragma("unroll") for (int k = 0; k < 2; ++k) dst[m][k] = *(const PG8_LAS bf16x8*)(lds + PG8_SA(b, h) + aoff + m * 2048 + k * 1024); } while (0)
; #define PG8_LDB(dst, b, h) do { _Pragma("unroll") for (int n = 0; n < 2; ++n) _Pragma("unroll") for (int k = 0; k < 2; ++k) dst[n][k] = *(const PG8_LAS bf16x8*)(lds + PG8_SB(b, h) + boff + n * 2048 + k * 1024); } while (0)
; #define PG8_MMA(ai, bj, At, Bt) do { __builtin_amdgcn_s_setprio(1); _Pragma("unroll") for (int m = 0; m < 4; ++m) _Pragma("unroll") for (int n = 0; n < 2; ++n) _Pragma("unroll") for (int k = 0; k < 2; ++k) \
;         acc[ai][bj][m][n] = __builtin_amdgcn_mfma_f32_16x16x32_bf16(Bt[n][k], At[m][k], acc[ai][bj][m][n], 0, 0, 0); __builtin_amdgcn_s_setprio(0); } while (0)
; #define PG8_WAIT_V(n) asm volatile("s_waitcnt vmcnt(" #n ")" ::: "memory")
; #define PG8_WAIT_L(n) asm volatile("s_waitcnt lgkmcnt(" #n ")" ::: "memory")
; #define PG8_BAR __builtin_amdgcn_s_barrier()
; #define PG8_SCHED __builtin_amdgcn_sched_barrier(0)
; template <class Epi, class Sched, bool ALIGN_EPI = false, bool SP2 = false>
; __device__ __forceinline__ void gemm_phase(PG8_LAS unsigned char* lds, const Gemm g, const Sched& S, const Epi& E) {
;     ...
;             PG8_WAIT_V(8); PG8_WAIT_L(0); PG8_BAR; PG8_MMA(1, 0, At, B0); PG8_MMA(1, 1, At, B1); PG8_BAR; PG8_SCHED;
;             PG8_LDB(B0, 1, 0); PG8_LDB(B1, 1, 1); PG8_SCHED; PG8_LDA(At, 1, 0); PG8_STAGE(PG8_SA(0, 1), a2 + hstepA, voffA);
;             PG8_WAIT_V(8); PG8_WAIT_L(0); PG8_BAR; PG8_MMA(0, 0, At, B0); PG8_MMA(0, 1, At, B1); PG8_BAR; PG8_SCHED;
	v_mfma_f32_16x16x32_bf16 v[146:149], v[0:3], v[60:63], 0
	v_mfma_f32_16x16x32_bf16 v[154:157], v[0:3], v[104:107], 0
	v_mfma_f32_16x16x32_bf16 v[162:165], v[0:3], v[112:115], 0
	v_mfma_f32_16x16x32_bf16 v[0:3], v[0:3], v[120:123], 0
	v_mfma_f32_16x16x32_bf16 v[146:149], v[4:7], v[100:103], v[146:149]
	v_mfma_f32_16x16x32_bf16 v[154:157], v[4:7], v[108:111], v[154:157]
	v_mfma_f32_16x16x32_bf16 v[162:165], v[4:7], v[116:119], v[162:165]
	v_mfma_f32_16x16x32_bf16 v[0:3], v[4:7], v[124:127], v[0:3]
	v_mfma_f32_16x16x32_bf16 v[4:7], v[8:11], v[120:123], 0
	v_mfma_f32_16x16x32_bf16 v[150:153], v[8:11], v[60:63], 0
	v_mfma_f32_16x16x32_bf16 v[158:161], v[8:11], v[104:107], 0
	v_mfma_f32_16x16x32_bf16 v[166:169], v[8:11], v[112:115], 0
	v_mfma_f32_16x16x32_bf16 v[4:7], v[12:15], v[124:127], v[4:7]
	v_mfma_f32_16x16x32_bf16 v[150:153], v[12:15], v[100:103], v[150:153]
	v_mfma_f32_16x16x32_bf16 v[158:161], v[12:15], v[108:111], v[158:161]
	v_mfma_f32_16x16x32_bf16 v[166:169], v[12:15], v[116:119], v[166:169]
	v_mfma_f32_16x16x32_bf16 v[8:11], v[16:19], v[60:63], 0
	v_mfma_f32_16x16x32_bf16 v[12:15], v[24:27], v[60:63], 0
	v_mfma_f32_16x16x32_bf16 v[8:11], v[20:23], v[100:103], v[8:11]
	v_mfma_f32_16x16x32_bf16 v[12:15], v[28:31], v[100:103], v[12:15]
	v_mfma_f32_16x16x32_bf16 v[60:63], v[16:19], v[104:107], 0
	v_mfma_f32_16x16x32_bf16 v[100:103], v[24:27], v[104:107], 0
	v_mfma_f32_16x16x32_bf16 v[104:107], v[16:19], v[112:115], 0
	v_mfma_f32_16x16x32_bf16 v[16:19], v[16:19], v[120:123], 0
	v_mfma_f32_16x16x32_bf16 v[60:63], v[20:23], v[108:111], v[60:63]
	v_mfma_f32_16x16x32_bf16 v[100:103], v[28:31], v[108:111], v[100:103]
	v_mfma_f32_16x16x32_bf16 v[104:107], v[20:23], v[116:119], v[104:107]
	v_mfma_f32_16x16x32_bf16 v[108:111], v[24:27], v[112:115], 0
	v_mfma_f32_16x16x32_bf16 v[16:19], v[20:23], v[124:127], v[16:19]
	v_mfma_f32_16x16x32_bf16 v[20:23], v[24:27], v[120:123], 0
	v_mfma_f32_16x16x32_bf16 v[108:111], v[28:31], v[116:119], v[108:111]
	v_mfma_f32_16x16x32_bf16 v[20:23], v[28:31], v[124:127], v[20:23]
	s_barrier
	s_add_i32 s49, 0, 0x18000
	s_add_i32 s68, 0, 0x1c000
	v_add_u32_e32 v224, s49, v142
	v_add_u32_e32 v228, s68, v142
	ds_read_b128 v[24:27], v224
	ds_read_b128 v[28:31], v224 offset:1024
	ds_read_b128 v[112:115], v224 offset:2048
	ds_read_b128 v[116:119], v224 offset:3072
	ds_read_b128 v[120:123], v228
	ds_read_b128 v[124:127], v228 offset:1024
	ds_read_b128 v[170:173], v228 offset:2048
	ds_read_b128 v[174:177], v228 offset:3072
	s_add_u32 s64, s38, 0x10100
	s_addc_u32 s65, s39, 0
	s_mov_b32 m0, s33
	ds_read_b128 v[178:181], v145 offset:32768
	ds_read_b128 v[182:185], v145 offset:33792
	ds_read_b128 v[186:189], v145 offset:34816
	ds_read_b128 v[196:199], v145 offset:35840
	ds_read_b128 v[200:203], v145 offset:36864
	ds_read_b128 v[204:207], v145 offset:37888
	ds_read_b128 v[208:211], v145 offset:38912
	ds_read_b128 v[212:215], v145 offset:39936
	global_load_lds_dwordx4 v128, s[64:65]
	s_mov_b32 m0, s42
	s_nop 0
	global_load_lds_dwordx4 v132, s[64:65]
	s_waitcnt vmcnt(8)
	s_waitcnt lgkmcnt(0)
	s_barrier
	v_mfma_f32_16x16x32_bf16 v[64:67], v[24:27], v[178:181], v[64:67]
	v_mfma_f32_16x16x32_bf16 v[68:71], v[112:115], v[178:181], v[68:71]
	v_mfma_f32_16x16x32_bf16 v[72:75], v[24:27], v[186:189], v[72:75]
	v_mfma_f32_16x16x32_bf16 v[76:79], v[112:115], v[186:189], v[76:79]
	v_mfma_f32_16x16x32_bf16 v[80:83], v[24:27], v[200:203], v[80:83]
	v_mfma_f32_16x16x32_bf16 v[84:87], v[112:115], v[200:203], v[84:87]
	v_mfma_f32_16x16x32_bf16 v[88:91], v[24:27], v[208:211], v[88:91]
	v_mfma_f32_16x16x32_bf16 v[92:95], v[112:115], v[208:211], v[92:95]
	v_mfma_f32_16x16x32_bf16 v[64:67], v[28:31], v[182:185], v[64:67]
	v_mfma_f32_16x16x32_bf16 v[68:71], v[116:119], v[182:185], v[68:71]
	v_mfma_f32_16x16x32_bf16 v[72:75], v[28:31], v[196:199], v[72:75]
	v_mfma_f32_16x16x32_bf16 v[76:79], v[116:119], v[196:199], v[76:79]
	v_mfma_f32_16x16x32_bf16 v[80:83], v[28:31], v[204:207], v[80:83]
	v_mfma_f32_16x16x32_bf16 v[84:87], v[116:119], v[204:207], v[84:87]
	v_mfma_f32_16x16x32_bf16 v[88:91], v[28:31], v[212:215], v[88:91]
	v_mfma_f32_16x16x32_bf16 v[92:95], v[116:119], v[212:215], v[92:95]
	v_mfma_f32_16x16x32_bf16 v[96:99], v[120:123], v[178:181], v[96:99]
	v_mfma_f32_16x16x32_bf16 v[32:35], v[170:173], v[178:181], v[32:35]
	v_mfma_f32_16x16x32_bf16 v[36:39], v[120:123], v[186:189], v[36:39]
	v_mfma_f32_16x16x32_bf16 v[40:43], v[170:173], v[186:189], v[40:43]
	v_mfma_f32_16x16x32_bf16 v[44:47], v[120:123], v[200:203], v[44:47]
	v_mfma_f32_16x16x32_bf16 v[48:51], v[170:173], v[200:203], v[48:51]
	v_mfma_f32_16x16x32_bf16 v[52:55], v[120:123], v[208:211], v[52:55]
	v_mfma_f32_16x16x32_bf16 v[56:59], v[170:173], v[208:211], v[56:59]
	v_mfma_f32_16x16x32_bf16 v[96:99], v[124:127], v[182:185], v[96:99]
	v_mfma_f32_16x16x32_bf16 v[32:35], v[174:177], v[182:185], v[32:35]
	v_mfma_f32_16x16x32_bf16 v[36:39], v[124:127], v[196:199], v[36:39]
	v_mfma_f32_16x16x32_bf16 v[40:43], v[174:177], v[196:199], v[40:43]
	v_mfma_f32_16x16x32_bf16 v[44:47], v[124:127], v[204:207], v[44:47]
	v_mfma_f32_16x16x32_bf16 v[48:51], v[174:177], v[204:207], v[48:51]
	v_mfma_f32_16x16x32_bf16 v[52:55], v[124:127], v[212:215], v[52:55]
	v_mfma_f32_16x16x32_bf16 v[56:59], v[174:177], v[212:215], v[56:59]
	s_barrier
; #define PG8_STAGE(bufoff, gbase, voff) do { _Pragma("unroll") for (int _i = 0; _i < 2; ++_i) \
;         __builtin_amdgcn_global_load_lds((const unsigned*)((const char*)(gbase) + (voff)[_i]), (PG8_LAS unsigned*)(lds + (bufoff) + ldsw + _i * 8192), 16, 0, 0); } while (0)
; #define PG8_LDA(dst, b, h) do { _Pragma("unroll") for (int m = 0; m < 4; ++m) _Pragma("unroll") for (int k = 0; k < 2; ++k) dst[m][k] = *(const PG8_LAS bf16x8*)(lds + PG8_SA(b, h) + aoff + m * 2048 + k * 1024); } while (0)
; #define PG8_LDB(dst, b, h) do { _Pragma("unroll") for (int n = 0; n < 2; ++n) _Pragma("unroll") for (int k = 0; k < 2; ++k) dst[n][k] = *(const PG8_LAS bf16x8*)(lds + PG8_SB(b, h) + boff + n * 2048 + k * 1024); } while (0)
; #define PG8_MMA(ai, bj, At, Bt) do { __builtin_amdgcn_s_setprio(1); _Pragma("unroll") for (int m = 0; m < 4; ++m) _Pragma("unroll") for (int n = 0; n < 2; ++n) _Pragma("unroll") for (int k = 0; k < 2; ++k) \
;         acc[ai][bj][m][n] = __builtin_amdgcn_mfma_f32_16x16x32_bf16(Bt[n][k], At[m][k], acc[ai][bj][m][n], 0, 0, 0); __builtin_amdgcn_s_setprio(0); } while (0)
; #define PG8_WAIT_V(n) asm volatile("s_waitcnt vmcnt(" #n ")" ::: "memory")
; template <class Epi, class Sched, bool ALIGN_EPI = false, bool SP2 = false>
; __device__ __forceinline__ void gemm_phase(PG8_LAS unsigned char* lds, const Gemm g, const Sched& S, const Epi& E) {
;     ...
;             PG8_LDB(B0, 0, 0); PG8_LDB(B1, 0, 1); PG8_SCHED; PG8_LDA(At, 0, 0); PG8_STAGE(PG8_SA(1, 1), a1 + hstepA, voffA);
;             PG8_WAIT_V(8); PG8_WAIT_L(0); PG8_BAR; PG8_MMA(0, 0, At, B0); PG8_MMA(0, 1, At, B1); PG8_BAR; PG8_SCHED;
;             PG8_LDA(At, 0, 1); PG8_STAGE(PG8_SB(0, 0), b2, voffB); PG8_STAGE(PG8_SB(0, 1), b2 + hstepB, voffB); PG8_STAGE(PG8_SA(0, 0), a2, voffA);
;             PG8_WAIT_V(8); PG8_WAIT_L(0); PG8_BAR; PG8_MMA(1, 0, At, B0); PG8_MMA(1, 1, At, B1); PG8_BAR; PG8_SCHED;
;             PG8_LDB(B0, 1, 0); PG8_LDB(B1, 1, 1); PG8_SCHED; PG8_LDA(At, 1, 0); PG8_STAGE(PG8_SA(0, 1), a2 + hstepA, voffA);
;             PG8_WAIT_V(8); PG8_WAIT_L(0); PG8_BAR; PG8_MMA(0, 0, At, B0); PG8_MMA(0, 1, At, B1); PG8_BAR; PG8_SCHED;
;             PG8_LDA(At, 1, 1); PG8_STAGE(PG8_SB(1, 0), b3, voffB); PG8_STAGE(PG8_SB(1, 1), b3 + hstepB, voffB); PG8_STAGE(PG8_SA(1, 0), a3, voffA);
;             PG8_WAIT_V(8); PG8_WAIT_L(0); PG8_BAR; PG8_MMA(1, 0, At, B0); PG8_MMA(1, 1, At, B1); PG8_BAR; PG8_SCHED;
	s_add_i32 s64, s49, s8
	s_add_i32 s49, s64, 0x2000
	v_lshl_add_u64 v[190:191], v[190:191], 0, s[24:25]
	s_mov_b32 m0, s64
	s_add_u32 s66, s40, 0x10180
	ds_read_b128 v[178:181], v145 offset:49152
	ds_read_b128 v[182:185], v145 offset:50176
	ds_read_b128 v[186:189], v145 offset:51200
	ds_read_b128 v[196:199], v145 offset:52224
	ds_read_b128 v[200:203], v145 offset:53248
	ds_read_b128 v[204:207], v145 offset:54272
	ds_read_b128 v[208:211], v145 offset:55296
	ds_read_b128 v[212:215], v145 offset:56320
	global_load_lds_dwordx4 v[190:191], off
	v_lshl_add_u64 v[190:191], v[216:217], 0, s[24:25]
	s_mov_b32 m0, s49
	s_addc_u32 s67, s41, 0
	s_add_i32 s40, s68, s8
	global_load_lds_dwordx4 v[190:191], off
	s_mov_b32 m0, s40
	s_add_i32 s41, s40, 0x2000
	global_load_lds_dwordx4 v130, s[66:67]
	s_mov_b32 m0, s41
	s_nop 0
	global_load_lds_dwordx4 v134, s[66:67]
	v_lshl_add_u64 v[190:191], v[218:219], 0, s[24:25]
	s_mov_b32 m0, s53
	s_nop 0
	global_load_lds_dwordx4 v[190:191], off
	v_lshl_add_u64 v[190:191], v[220:221], 0, s[24:25]
	s_mov_b32 m0, s56
	s_nop 0
	global_load_lds_dwordx4 v[190:191], off
	s_waitcnt vmcnt(8)
	s_waitcnt lgkmcnt(0)
	s_barrier
	v_mfma_f32_16x16x32_bf16 v[0:3], v[24:27], v[208:211], v[0:3]
	v_mfma_f32_16x16x32_bf16 v[4:7], v[112:115], v[208:211], v[4:7]
	v_mfma_f32_16x16x32_bf16 v[146:149], v[24:27], v[178:181], v[146:149]
	v_mfma_f32_16x16x32_bf16 v[150:153], v[112:115], v[178:181], v[150:153]
	v_mfma_f32_16x16x32_bf16 v[154:157], v[24:27], v[186:189], v[154:157]
	v_mfma_f32_16x16x32_bf16 v[158:161], v[112:115], v[186:189], v[158:161]
	v_mfma_f32_16x16x32_bf16 v[162:165], v[24:27], v[200:203], v[162:165]
	v_mfma_f32_16x16x32_bf16 v[166:169], v[112:115], v[200:203], v[166:169]
	v_mfma_f32_16x16x32_bf16 v[0:3], v[28:31], v[212:215], v[0:3]
	v_mfma_f32_16x16x32_bf16 v[4:7], v[116:119], v[212:215], v[4:7]
	v_mfma_f32_16x16x32_bf16 v[146:149], v[28:31], v[182:185], v[146:149]
	v_mfma_f32_16x16x32_bf16 v[150:153], v[116:119], v[182:185], v[150:153]
	v_mfma_f32_16x16x32_bf16 v[154:157], v[28:31], v[196:199], v[154:157]
	v_mfma_f32_16x16x32_bf16 v[158:161], v[116:119], v[196:199], v[158:161]
	v_mfma_f32_16x16x32_bf16 v[162:165], v[28:31], v[204:207], v[162:165]
	v_mfma_f32_16x16x32_bf16 v[166:169], v[116:119], v[204:207], v[166:169]
	v_mfma_f32_16x16x32_bf16 v[8:11], v[120:123], v[178:181], v[8:11]
	v_mfma_f32_16x16x32_bf16 v[12:15], v[170:173], v[178:181], v[12:15]
	v_mfma_f32_16x16x32_bf16 v[24:27], v[120:123], v[186:189], v[60:63]
	v_mfma_f32_16x16x32_bf16 v[28:31], v[170:173], v[186:189], v[100:103]
	v_mfma_f32_16x16x32_bf16 v[60:63], v[120:123], v[200:203], v[104:107]
	v_mfma_f32_16x16x32_bf16 v[100:103], v[170:173], v[200:203], v[108:111]
	v_mfma_f32_16x16x32_bf16 v[16:19], v[120:123], v[208:211], v[16:19]
	v_mfma_f32_16x16x32_bf16 v[20:23], v[170:173], v[208:211], v[20:23]
	v_mfma_f32_16x16x32_bf16 v[8:11], v[124:127], v[182:185], v[8:11]
	v_mfma_f32_16x16x32_bf16 v[12:15], v[174:177], v[182:185], v[12:15]
	v_mfma_f32_16x16x32_bf16 v[24:27], v[124:127], v[196:199], v[24:27]
	v_mfma_f32_16x16x32_bf16 v[28:31], v[174:177], v[196:199], v[28:31]
	v_mfma_f32_16x16x32_bf16 v[60:63], v[124:127], v[204:207], v[60:63]
	v_mfma_f32_16x16x32_bf16 v[100:103], v[174:177], v[204:207], v[100:103]
	v_mfma_f32_16x16x32_bf16 v[16:19], v[124:127], v[212:215], v[16:19]
	v_mfma_f32_16x16x32_bf16 v[20:23], v[174:177], v[212:215], v[20:23]
	s_barrier
	ds_read_b128 v[104:107], v143
	ds_read_b128 v[108:111], v143 offset:1024
	ds_read_b128 v[112:115], v143 offset:2048
	ds_read_b128 v[116:119], v143 offset:3072
	ds_read_b128 v[120:123], v144
	ds_read_b128 v[124:127], v144 offset:1024
	ds_read_b128 v[170:173], v144 offset:2048
	ds_read_b128 v[174:177], v144 offset:3072
	s_add_u32 s38, s38, 0x10180
	s_addc_u32 s39, s39, 0
	s_mov_b32 m0, s63
	ds_read_b128 v[178:181], v145
	ds_read_b128 v[182:185], v145 offset:1024
	ds_read_b128 v[186:189], v145 offset:2048
	ds_read_b128 v[196:199], v145 offset:3072
	ds_read_b128 v[200:203], v145 offset:4096
	ds_read_b128 v[204:207], v145 offset:5120
	ds_read_b128 v[208:211], v145 offset:6144
	ds_read_b128 v[212:215], v145 offset:7168
	global_load_lds_dwordx4 v128, s[38:39]
	s_mov_b32 m0, s29
	s_nop 0
	global_load_lds_dwordx4 v132, s[38:39]
	s_waitcnt vmcnt(8)
	s_waitcnt lgkmcnt(0)
	s_barrier
	v_mfma_f32_16x16x32_bf16 v[64:67], v[104:107], v[178:181], v[64:67]
	v_mfma_f32_16x16x32_bf16 v[68:71], v[112:115], v[178:181], v[68:71]
	v_mfma_f32_16x16x32_bf16 v[72:75], v[104:107], v[186:189], v[72:75]
	v_mfma_f32_16x16x32_bf16 v[76:79], v[112:115], v[186:189], v[76:79]
	v_mfma_f32_16x16x32_bf16 v[80:83], v[104:107], v[200:203], v[80:83]
	v_mfma_f32_16x16x32_bf16 v[84:87], v[112:115], v[200:203], v[84:87]
	v_mfma_f32_16x16x32_bf16 v[88:91], v[104:107], v[208:211], v[88:91]
	v_mfma_f32_16x16x32_bf16 v[92:95], v[112:115], v[208:211], v[92:95]
	v_mfma_f32_16x16x32_bf16 v[64:67], v[108:111], v[182:185], v[64:67]
	v_mfma_f32_16x16x32_bf16 v[68:71], v[116:119], v[182:185], v[68:71]
	v_mfma_f32_16x16x32_bf16 v[72:75], v[108:111], v[196:199], v[72:75]
	v_mfma_f32_16x16x32_bf16 v[76:79], v[116:119], v[196:199], v[76:79]
	v_mfma_f32_16x16x32_bf16 v[80:83], v[108:111], v[204:207], v[80:83]
	v_mfma_f32_16x16x32_bf16 v[84:87], v[116:119], v[204:207], v[84:87]
	v_mfma_f32_16x16x32_bf16 v[88:91], v[108:111], v[212:215], v[88:91]
	v_mfma_f32_16x16x32_bf16 v[92:95], v[116:119], v[212:215], v[92:95]
	v_mfma_f32_16x16x32_bf16 v[32:35], v[170:173], v[178:181], v[32:35]
	v_mfma_f32_16x16x32_bf16 v[96:99], v[120:123], v[178:181], v[96:99]
	v_mfma_f32_16x16x32_bf16 v[178:181], v[174:177], v[182:185], v[32:35]
	v_mfma_f32_16x16x32_bf16 v[32:35], v[120:123], v[186:189], v[36:39]
	v_mfma_f32_16x16x32_bf16 v[216:219], v[124:127], v[182:185], v[96:99]
	v_mfma_f32_16x16x32_bf16 v[182:185], v[124:127], v[196:199], v[32:35]
	v_mfma_f32_16x16x32_bf16 v[32:35], v[170:173], v[186:189], v[40:43]
	v_mfma_f32_16x16x32_bf16 v[40:43], v[174:177], v[196:199], v[32:35]
	v_mfma_f32_16x16x32_bf16 v[32:35], v[120:123], v[200:203], v[44:47]
	v_mfma_f32_16x16x32_bf16 v[44:47], v[124:127], v[204:207], v[32:35]
	v_mfma_f32_16x16x32_bf16 v[32:35], v[170:173], v[200:203], v[48:51]
	v_mfma_f32_16x16x32_bf16 v[48:51], v[174:177], v[204:207], v[32:35]
	v_mfma_f32_16x16x32_bf16 v[32:35], v[120:123], v[208:211], v[52:55]
	v_mfma_f32_16x16x32_bf16 v[52:55], v[124:127], v[212:215], v[32:35]
	v_mfma_f32_16x16x32_bf16 v[32:35], v[170:173], v[208:211], v[56:59]
	v_mfma_f32_16x16x32_bf16 v[56:59], v[174:177], v[212:215], v[32:35]
	s_barrier
; #define PG8_STAGE(bufoff, gbase, voff) do { _Pragma("unroll") for (int _i = 0; _i < 2; ++_i) \
;         __builtin_amdgcn_global_load_lds((const unsigned*)((const char*)(gbase) + (voff)[_i]), (PG8_LAS unsigned*)(lds + (bufoff) + ldsw + _i * 8192), 16, 0, 0); } while (0)
; #define PG8_LDA(dst, b, h) do { _Pragma("unroll") for (int m = 0; m < 4; ++m) _Pragma("unroll") for (int k = 0; k < 2; ++k) dst[m][k] = *(const PG8_LAS bf16x8*)(lds + PG8_SA(b, h) + aoff + m * 2048 + k * 1024); } while (0)
; #define PG8_LDB(dst, b, h) do { _Pragma("unroll") for (int n = 0; n < 2; ++n) _Pragma("unroll") for (int k = 0; k < 2; ++k) dst[n][k] = *(const PG8_LAS bf16x8*)(lds + PG8_SB(b, h) + boff + n * 2048 + k * 1024); } while (0)
; #define PG8_MMA(ai, bj, At, Bt) do { __builtin_amdgcn_s_setprio(1); _Pragma("unroll") for (int m = 0; m < 4; ++m) _Pragma("unroll") for (int n = 0; n < 2; ++n) _Pragma("unroll") for (int k = 0; k < 2; ++k) \
;         acc[ai][bj][m][n] = __builtin_amdgcn_mfma_f32_16x16x32_bf16(Bt[n][k], At[m][k], acc[ai][bj][m][n], 0, 0, 0); __builtin_amdgcn_s_setprio(0); } while (0)
; #define PG8_WAIT_V(n) asm volatile("s_waitcnt vmcnt(" #n ")" ::: "memory")
; #define PG8_WAIT_L(n) asm volatile("s_waitcnt lgkmcnt(" #n ")" ::: "memory")
; #define PG8_BAR __builtin_amdgcn_s_barrier()
; #define PG8_SCHED __builtin_amdgcn_sched_barrier(0)
; template <class Epi, class Sched, bool ALIGN_EPI = false, bool SP2 = false>
; __device__ __forceinline__ void gemm_phase(PG8_LAS unsigned char* lds, const Gemm g, const Sched& S, const Epi& E) {
;     ...
;             PG8_LDA(At, 0, 1); PG8_STAGE(PG8_SB(0, 0), b2, voffB); PG8_STAGE(PG8_SB(0, 1), b2 + hstepB, voffB); PG8_STAGE(PG8_SA(0, 0), a2, voffA);
;             PG8_WAIT_V(8); PG8_WAIT_L(0); PG8_BAR; PG8_MMA(1, 0, At, B0); PG8_MMA(1, 1, At, B1); PG8_BAR; PG8_SCHED;
;             PG8_LDB(B0, 1, 0); PG8_LDB(B1, 1, 1); PG8_SCHED; PG8_LDA(At, 1, 0); PG8_STAGE(PG8_SA(0, 1), a2 + hstepA, voffA);
;             PG8_WAIT_V(8); PG8_WAIT_L(0); PG8_BAR; PG8_MMA(0, 0, At, B0); PG8_MMA(0, 1, At, B1); PG8_BAR; PG8_SCHED;
	s_mov_b32 m0, s48
	s_add_u32 s98, s46, s16
	s_addc_u32 s99, s47, s17
	s_add_u32 s38, s46, 0x10000
	s_nop 1
	ds_read_b128 v[32:35], v145 offset:16384
	ds_read_b128 v[36:39], v145 offset:17408
	ds_read_b128 v[96:99], v145 offset:18432
	ds_read_b128 v[186:189], v145 offset:19456
	ds_read_b128 v[196:199], v145 offset:20480
	ds_read_b128 v[200:203], v145 offset:21504
	ds_read_b128 v[204:207], v145 offset:22528
	ds_read_b128 v[208:211], v145 offset:23552
	global_load_lds_dwordx4 v130, s[46:47]
	s_mov_b32 m0, s31
	s_addc_u32 s39, s47, 0
	global_load_lds_dwordx4 v134, s[46:47]
	s_mov_b32 m0, s44
	global_load_lds_dwordx4 v130, s[38:39]
	s_mov_b32 m0, s45
	global_load_lds_dwordx4 v134, s[38:39]
	s_mov_b32 m0, s9
	s_nop 0
	s_add_u32 s100, s50, s16
	s_addc_u32 s101, s51, s17
	global_load_lds_dwordx4 v128, s[50:51]
	s_mov_b32 m0, s27
	s_nop 0
	global_load_lds_dwordx4 v132, s[50:51]
	s_waitcnt vmcnt(8)
	s_waitcnt lgkmcnt(0)
	s_barrier
	v_mfma_f32_16x16x32_bf16 v[0:3], v[104:107], v[204:207], v[0:3]
	v_mfma_f32_16x16x32_bf16 v[4:7], v[112:115], v[204:207], v[4:7]
	v_mfma_f32_16x16x32_bf16 v[146:149], v[104:107], v[32:35], v[146:149]
	v_mfma_f32_16x16x32_bf16 v[150:153], v[112:115], v[32:35], v[150:153]
	v_mfma_f32_16x16x32_bf16 v[154:157], v[104:107], v[96:99], v[154:157]
	v_mfma_f32_16x16x32_bf16 v[158:161], v[112:115], v[96:99], v[158:161]
	v_mfma_f32_16x16x32_bf16 v[162:165], v[104:107], v[196:199], v[162:165]
	v_mfma_f32_16x16x32_bf16 v[166:169], v[112:115], v[196:199], v[166:169]
	v_mfma_f32_16x16x32_bf16 v[0:3], v[108:111], v[208:211], v[0:3]
	v_mfma_f32_16x16x32_bf16 v[4:7], v[116:119], v[208:211], v[4:7]
	v_mfma_f32_16x16x32_bf16 v[146:149], v[108:111], v[36:39], v[146:149]
	v_mfma_f32_16x16x32_bf16 v[150:153], v[116:119], v[36:39], v[150:153]
	v_mfma_f32_16x16x32_bf16 v[154:157], v[108:111], v[186:189], v[154:157]
	v_mfma_f32_16x16x32_bf16 v[158:161], v[116:119], v[186:189], v[158:161]
	v_mfma_f32_16x16x32_bf16 v[162:165], v[108:111], v[200:203], v[162:165]
	v_mfma_f32_16x16x32_bf16 v[166:169], v[116:119], v[200:203], v[166:169]
	v_mfma_f32_16x16x32_bf16 v[8:11], v[120:123], v[32:35], v[8:11]
	v_mfma_f32_16x16x32_bf16 v[12:15], v[170:173], v[32:35], v[12:15]
	v_mfma_f32_16x16x32_bf16 v[24:27], v[120:123], v[96:99], v[24:27]
	v_mfma_f32_16x16x32_bf16 v[28:31], v[170:173], v[96:99], v[28:31]
	v_mfma_f32_16x16x32_bf16 v[32:35], v[120:123], v[196:199], v[60:63]
	v_mfma_f32_16x16x32_bf16 v[24:27], v[124:127], v[186:189], v[24:27]
	v_mfma_f32_16x16x32_bf16 v[28:31], v[174:177], v[186:189], v[28:31]
	v_mfma_f32_16x16x32_bf16 v[186:189], v[124:127], v[200:203], v[32:35]
	v_mfma_f32_16x16x32_bf16 v[32:35], v[170:173], v[196:199], v[100:103]
	v_mfma_f32_16x16x32_bf16 v[16:19], v[120:123], v[204:207], v[16:19]
	v_mfma_f32_16x16x32_bf16 v[8:11], v[124:127], v[36:39], v[8:11]
	v_mfma_f32_16x16x32_bf16 v[12:15], v[174:177], v[36:39], v[12:15]
	v_mfma_f32_16x16x32_bf16 v[196:199], v[174:177], v[200:203], v[32:35]
	v_mfma_f32_16x16x32_bf16 v[200:203], v[124:127], v[208:211], v[16:19]
	v_mfma_f32_16x16x32_bf16 v[16:19], v[170:173], v[204:207], v[20:23]
	v_mfma_f32_16x16x32_bf16 v[170:173], v[174:177], v[208:211], v[16:19]
	s_barrier
	ds_read_b128 v[60:63], v224
	ds_read_b128 v[174:177], v224 offset:1024
	ds_read_b128 v[204:207], v224 offset:2048
	ds_read_b128 v[208:211], v224 offset:3072
	ds_read_b128 v[212:215], v228
	ds_read_b128 v[220:223], v228 offset:1024
	ds_read_b128 v[224:227], v228 offset:2048
	ds_read_b128 v[228:231], v228 offset:3072
	s_add_u32 s38, s50, 0x10000
	s_addc_u32 s39, s51, 0
	s_mov_b32 m0, s33
	ds_read_b128 v[16:19], v145 offset:32768
	ds_read_b128 v[20:23], v145 offset:33792
	ds_read_b128 v[108:111], v145 offset:34816
	ds_read_b128 v[232:235], v145 offset:35840
	ds_read_b128 v[236:239], v145 offset:36864
	ds_read_b128 v[240:243], v145 offset:37888
	ds_read_b128 v[244:247], v145 offset:38912
	ds_read_b128 v[248:251], v145 offset:39936
	global_load_lds_dwordx4 v128, s[38:39]
	s_mov_b32 m0, s42
	s_nop 0
	global_load_lds_dwordx4 v132, s[38:39]
	s_waitcnt vmcnt(8)
	s_waitcnt lgkmcnt(0)
	s_barrier
; #define PG8_STAGE(bufoff, gbase, voff) do { _Pragma("unroll") for (int _i = 0; _i < 2; ++_i) \
;         __builtin_amdgcn_global_load_lds((const unsigned*)((const char*)(gbase) + (voff)[_i]), (PG8_LAS unsigned*)(lds + (bufoff) + ldsw + _i * 8192), 16, 0, 0); } while (0)
; #define PG8_LDA(dst, b, h) do { _Pragma("unroll") for (int m = 0; m < 4; ++m) _Pragma("unroll") for (int k = 0; k < 2; ++k) dst[m][k] = *(const PG8_LAS bf16x8*)(lds + PG8_SA(b, h) + aoff + m * 2048 + k * 1024); } while (0)
; #define PG8_MMA(ai, bj, At, Bt) do { __builtin_amdgcn_s_setprio(1); _Pragma("unroll") for (int m = 0; m < 4; ++m) _Pragma("unroll") for (int n = 0; n < 2; ++n) _Pragma("unroll") for (int k = 0; k < 2; ++k) \
;         acc[ai][bj][m][n] = __builtin_amdgcn_mfma_f32_16x16x32_bf16(Bt[n][k], At[m][k], acc[ai][bj][m][n], 0, 0, 0); __builtin_amdgcn_s_setprio(0); } while (0)
; #define PG8_WAIT_V(n) asm volatile("s_waitcnt vmcnt(" #n ")" ::: "memory")
; #define PG8_WAIT_L(n) asm volatile("s_waitcnt lgkmcnt(" #n ")" ::: "memory")
; #define PG8_BAR __builtin_amdgcn_s_barrier()
; #define PG8_SCHED __builtin_amdgcn_sched_barrier(0)
; template <class Epi, class Sched, bool ALIGN_EPI = false, bool SP2 = false>
; __device__ __forceinline__ void gemm_phase(PG8_LAS unsigned char* lds, const Gemm g, const Sched& S, const Epi& E) {
;     ...
;             PG8_WAIT_V(8); PG8_WAIT_L(0); PG8_BAR; PG8_MMA(0, 0, At, B0); PG8_MMA(0, 1, At, B1); PG8_BAR; PG8_SCHED;
;             PG8_LDA(At, 1, 1); PG8_STAGE(PG8_SB(1, 0), b3, voffB); PG8_STAGE(PG8_SB(1, 1), b3 + hstepB, voffB); PG8_STAGE(PG8_SA(1, 0), a3, voffA);
;             PG8_WAIT_V(8); PG8_WAIT_L(0); PG8_BAR; PG8_MMA(1, 0, At, B0); PG8_MMA(1, 1, At, B1); PG8_BAR; PG8_SCHED;
;     ...
;         if constexpr (ALIGN_EPI) { if (wr == 0) PG8_BAR; }
	v_mfma_f32_16x16x32_bf16 v[32:35], v[60:63], v[16:19], v[64:67]
	v_mfma_f32_16x16x32_bf16 v[112:115], v[174:177], v[20:23], v[32:35]
	v_mfma_f32_16x16x32_bf16 v[32:35], v[204:207], v[16:19], v[68:71]
	v_mfma_f32_16x16x32_bf16 v[116:119], v[208:211], v[20:23], v[32:35]
	v_mfma_f32_16x16x32_bf16 v[32:35], v[60:63], v[108:111], v[72:75]
	v_mfma_f32_16x16x32_bf16 v[96:99], v[174:177], v[232:235], v[32:35]
	v_mfma_f32_16x16x32_bf16 v[32:35], v[204:207], v[108:111], v[76:79]
	v_mfma_f32_16x16x32_bf16 v[100:103], v[208:211], v[232:235], v[32:35]
	v_mfma_f32_16x16x32_bf16 v[32:35], v[60:63], v[236:239], v[80:83]
	v_mfma_f32_16x16x32_bf16 v[64:67], v[174:177], v[240:243], v[32:35]
	v_mfma_f32_16x16x32_bf16 v[32:35], v[204:207], v[236:239], v[84:87]
	v_mfma_f32_16x16x32_bf16 v[68:71], v[208:211], v[240:243], v[32:35]
	v_mfma_f32_16x16x32_bf16 v[32:35], v[60:63], v[244:247], v[88:91]
	v_mfma_f32_16x16x32_bf16 v[36:39], v[204:207], v[244:247], v[92:95]
	v_mfma_f32_16x16x32_bf16 v[32:35], v[174:177], v[248:251], v[32:35]
	v_mfma_f32_16x16x32_bf16 v[36:39], v[208:211], v[248:251], v[36:39]
	v_mfma_f32_16x16x32_bf16 v[72:75], v[212:215], v[16:19], v[216:219]
	v_mfma_f32_16x16x32_bf16 v[16:19], v[224:227], v[16:19], v[178:181]
	v_mfma_f32_16x16x32_bf16 v[124:127], v[228:231], v[20:23], v[16:19]
	v_mfma_f32_16x16x32_bf16 v[16:19], v[212:215], v[108:111], v[182:185]
	v_mfma_f32_16x16x32_bf16 v[104:107], v[220:223], v[232:235], v[16:19]
	v_mfma_f32_16x16x32_bf16 v[16:19], v[224:227], v[108:111], v[40:43]
	v_mfma_f32_16x16x32_bf16 v[108:111], v[228:231], v[232:235], v[16:19]
	v_mfma_f32_16x16x32_bf16 v[16:19], v[212:215], v[236:239], v[44:47]
	v_mfma_f32_16x16x32_bf16 v[120:123], v[220:223], v[20:23], v[72:75]
	v_mfma_f32_16x16x32_bf16 v[72:75], v[220:223], v[240:243], v[16:19]
	v_mfma_f32_16x16x32_bf16 v[16:19], v[224:227], v[236:239], v[48:51]
	v_mfma_f32_16x16x32_bf16 v[76:79], v[228:231], v[240:243], v[16:19]
	v_mfma_f32_16x16x32_bf16 v[16:19], v[212:215], v[244:247], v[52:55]
	v_mfma_f32_16x16x32_bf16 v[40:43], v[220:223], v[248:251], v[16:19]
	v_mfma_f32_16x16x32_bf16 v[16:19], v[224:227], v[244:247], v[56:59]
	v_mfma_f32_16x16x32_bf16 v[44:47], v[228:231], v[248:251], v[16:19]
	s_barrier
	s_mov_b32 m0, s64
	s_nop 3
	s_add_u32 s38, s46, 0x10080
	ds_read_b128 v[56:59], v145 offset:49152
	ds_read_b128 v[92:95], v145 offset:50176
	ds_read_b128 v[178:181], v145 offset:51200
	ds_read_b128 v[182:185], v145 offset:52224
	ds_read_b128 v[216:219], v145 offset:53248
	ds_read_b128 v[232:235], v145 offset:54272
	ds_read_b128 v[236:239], v145 offset:55296
	ds_read_b128 v[240:243], v145 offset:56320
	global_load_lds_dwordx4 v130, s[98:99]
	s_mov_b32 m0, s49
	s_addc_u32 s39, s47, 0
	global_load_lds_dwordx4 v134, s[98:99]
	s_mov_b32 m0, s40
	s_nop 0
	global_load_lds_dwordx4 v130, s[38:39]
	s_mov_b32 m0, s41
	s_nop 0
	global_load_lds_dwordx4 v134, s[38:39]
	s_mov_b32 m0, s53
	s_nop 0
	global_load_lds_dwordx4 v128, s[100:101]
	s_mov_b32 m0, s56
	s_nop 0
	global_load_lds_dwordx4 v132, s[100:101]
	s_waitcnt vmcnt(8)
	s_waitcnt lgkmcnt(0)
	s_barrier
	v_mfma_f32_16x16x32_bf16 v[16:19], v[60:63], v[56:59], v[146:149]
	v_mfma_f32_16x16x32_bf16 v[80:83], v[174:177], v[92:95], v[16:19]
	v_mfma_f32_16x16x32_bf16 v[16:19], v[204:207], v[56:59], v[150:153]
	v_mfma_f32_16x16x32_bf16 v[84:87], v[208:211], v[92:95], v[16:19]
	v_mfma_f32_16x16x32_bf16 v[16:19], v[60:63], v[178:181], v[154:157]
	v_mfma_f32_16x16x32_bf16 v[48:51], v[174:177], v[182:185], v[16:19]
	v_mfma_f32_16x16x32_bf16 v[16:19], v[204:207], v[178:181], v[158:161]
	v_mfma_f32_16x16x32_bf16 v[52:55], v[208:211], v[182:185], v[16:19]
	v_mfma_f32_16x16x32_bf16 v[16:19], v[60:63], v[216:219], v[162:165]
	v_mfma_f32_16x16x32_bf16 v[20:23], v[204:207], v[216:219], v[166:169]
	v_mfma_f32_16x16x32_bf16 v[0:3], v[60:63], v[236:239], v[0:3]
	v_mfma_f32_16x16x32_bf16 v[4:7], v[204:207], v[236:239], v[4:7]
	v_mfma_f32_16x16x32_bf16 v[16:19], v[174:177], v[232:235], v[16:19]
	v_mfma_f32_16x16x32_bf16 v[20:23], v[208:211], v[232:235], v[20:23]
	v_mfma_f32_16x16x32_bf16 v[0:3], v[174:177], v[240:243], v[0:3]
	v_mfma_f32_16x16x32_bf16 v[4:7], v[208:211], v[240:243], v[4:7]
	v_mfma_f32_16x16x32_bf16 v[8:11], v[212:215], v[56:59], v[8:11]
	v_mfma_f32_16x16x32_bf16 v[88:91], v[220:223], v[92:95], v[8:11]
	v_mfma_f32_16x16x32_bf16 v[8:11], v[224:227], v[56:59], v[12:15]
	v_mfma_f32_16x16x32_bf16 v[92:95], v[228:231], v[92:95], v[8:11]
	v_mfma_f32_16x16x32_bf16 v[8:11], v[212:215], v[178:181], v[24:27]
	v_mfma_f32_16x16x32_bf16 v[56:59], v[220:223], v[182:185], v[8:11]
	v_mfma_f32_16x16x32_bf16 v[8:11], v[224:227], v[178:181], v[28:31]
	v_mfma_f32_16x16x32_bf16 v[60:63], v[228:231], v[182:185], v[8:11]
	v_mfma_f32_16x16x32_bf16 v[8:11], v[212:215], v[216:219], v[186:189]
	v_mfma_f32_16x16x32_bf16 v[24:27], v[220:223], v[232:235], v[8:11]
	v_mfma_f32_16x16x32_bf16 v[8:11], v[224:227], v[216:219], v[196:199]
	v_mfma_f32_16x16x32_bf16 v[28:31], v[228:231], v[232:235], v[8:11]
	v_mfma_f32_16x16x32_bf16 v[8:11], v[212:215], v[236:239], v[200:203]
	v_mfma_f32_16x16x32_bf16 v[12:15], v[224:227], v[236:239], v[170:173]
	v_mfma_f32_16x16x32_bf16 v[8:11], v[220:223], v[240:243], v[8:11]
	v_mfma_f32_16x16x32_bf16 v[12:15], v[228:231], v[240:243], v[12:15]
	s_barrier
	s_andn2_b64 vcc, exec, s[18:19]
	s_cbranch_vccnz .LBB0_165
	s_barrier

; #define PG8_STAGE(bufoff, gbase, voff) do { _Pragma("unroll") for (int _i = 0; _i < 2; ++_i) \
;         __builtin_amdgcn_global_load_lds((const unsigned*)((const char*)(gbase) + (voff)[_i]), (PG8_LAS unsigned*)(lds + (bufoff) + ldsw + _i * 8192), 16, 0, 0); } while (0)
; #define PG8_LDA(dst, b, h) do { _Pragma("unroll") for (int m = 0; m < 4; ++m) _Pragma("unroll") for (int k = 0; k < 2; ++k) dst[m][k] = *(const PG8_LAS bf16x8*)(lds + PG8_SA(b, h) + aoff + m * 2048 + k * 1024); } while (0)
; #define PG8_LDB(dst, b, h) do { _Pragma("unroll") for (int n = 0; n < 2; ++n) _Pragma("unroll") for (int k = 0; k < 2; ++k) dst[n][k] = *(const PG8_LAS bf16x8*)(lds + PG8_SB(b, h) + boff + n * 2048 + k * 1024); } while (0)
; #define PG8_MMA(ai, bj, At, Bt) do { __builtin_amdgcn_s_setprio(1); _Pragma("unroll") for (int m = 0; m < 4; ++m) _Pragma("unroll") for (int n = 0; n < 2; ++n) _Pragma("unroll") for (int k = 0; k < 2; ++k) \
;         acc[ai][bj][m][n] = __builtin_amdgcn_mfma_f32_16x16x32_bf16(Bt[n][k], At[m][k], acc[ai][bj][m][n], 0, 0, 0); __builtin_amdgcn_s_setprio(0); } while (0)
; #define PG8_WAIT_V(n) asm volatile("s_waitcnt vmcnt(" #n ")" ::: "memory")
; #define PG8_WAIT_L(n) asm volatile("s_waitcnt lgkmcnt(" #n ")" ::: "memory")
; #define PG8_BAR __builtin_amdgcn_s_barrier()
; template <class Epi, class Sched, bool ALIGN_EPI = false, bool SP2 = false>
; __device__ __forceinline__ void gemm_phase(PG8_LAS unsigned char* lds, const Gemm g, const Sched& S, const Epi& E) {
;     ...
;             const char* a1 = cA + (size_t)(t + 1) * kstep;
;             const char* a2 = last ? nA : cA + (size_t)(t + 2) * kstep; const char* b2 = last ? nB : cB + (size_t)(t + 2) * kstep;
;             const char* a3 = a2 + kstep; const char* b3 = b2 + kstep;
;             if (last && has_next) S.a_ready(nxt);
;             if constexpr (SP2) {
;             PG8_LDB(B0, 0, 0); PG8_LDB(B1, 0, 1); PG8_SCHED; PG8_LDA(At, 0, 0); PG8_STAGE(PG8_SA(1, 1), a1 + hstepA, voffA);
;             PG8_WAIT_V(8); PG8_WAIT_L(0); PG8_BAR; PG8_MMA(0, 0, At, B0); PG8_MMA(0, 1, At, B1); PG8_BAR; PG8_SCHED;
;             PG8_LDA(At, 0, 1); PG8_STAGE(PG8_SB(0, 0), b2, voffB); PG8_STAGE(PG8_SB(0, 1), b2 + hstepB, voffB); PG8_STAGE(PG8_SA(0, 0), a2, voffA);
;             PG8_WAIT_V(8); PG8_WAIT_L(0); PG8_BAR; PG8_MMA(1, 0, At, B0); PG8_MMA(1, 1, At, B1); PG8_BAR; PG8_SCHED;
.LBB0_186:
	ds_read_b128 v[150:153], v147
	ds_read_b128 v[154:157], v147 offset:1024
	ds_read_b128 v[158:161], v147 offset:2048
	ds_read_b128 v[162:165], v147 offset:3072
	ds_read_b128 v[166:169], v148
	ds_read_b128 v[170:173], v148 offset:1024
	ds_read_b128 v[174:177], v148 offset:2048
	ds_read_b128 v[178:181], v148 offset:3072
	s_add_u32 s36, s34, 0xfffc0080
	s_addc_u32 s37, s35, -1
	s_cmp_eq_u32 s64, 12
	s_cselect_b32 s39, s27, s37
	s_cselect_b32 s38, s60, s36
	s_cselect_b32 s37, s25, s63
	s_cselect_b32 s36, s61, s62
	s_add_i32 m0, s8, 0xc000
	ds_read_b128 v[182:185], v149
	ds_read_b128 v[186:189], v149 offset:1024
	ds_read_b128 v[196:199], v149 offset:2048
	ds_read_b128 v[200:203], v149 offset:3072
	ds_read_b128 v[204:207], v149 offset:4096
	ds_read_b128 v[208:211], v149 offset:5120
	ds_read_b128 v[212:215], v149 offset:6144
	ds_read_b128 v[216:219], v149 offset:7168
	global_load_lds_dwordx4 v136, s[34:35]
	s_add_i32 m0, s8, 0xe000
	s_nop 0
	global_load_lds_dwordx4 v138, s[34:35]
	s_waitcnt vmcnt(8)
	s_waitcnt lgkmcnt(0)
	s_barrier
	v_mfma_f32_16x16x32_bf16 v[124:127], v[150:153], v[182:185], v[124:127]
	v_mfma_f32_16x16x32_bf16 v[120:123], v[158:161], v[182:185], v[120:123]
	v_mfma_f32_16x16x32_bf16 v[116:119], v[150:153], v[196:199], v[116:119]
	v_mfma_f32_16x16x32_bf16 v[112:115], v[158:161], v[196:199], v[112:115]
	v_mfma_f32_16x16x32_bf16 v[100:103], v[150:153], v[204:207], v[100:103]
	v_mfma_f32_16x16x32_bf16 v[96:99], v[158:161], v[204:207], v[96:99]
	v_mfma_f32_16x16x32_bf16 v[84:87], v[150:153], v[212:215], v[84:87]
	v_mfma_f32_16x16x32_bf16 v[80:83], v[158:161], v[212:215], v[80:83]
	v_mfma_f32_16x16x32_bf16 v[124:127], v[154:157], v[186:189], v[124:127]
	v_mfma_f32_16x16x32_bf16 v[120:123], v[162:165], v[186:189], v[120:123]
	v_mfma_f32_16x16x32_bf16 v[116:119], v[154:157], v[200:203], v[116:119]
	v_mfma_f32_16x16x32_bf16 v[112:115], v[162:165], v[200:203], v[112:115]
	v_mfma_f32_16x16x32_bf16 v[100:103], v[154:157], v[208:211], v[100:103]
	v_mfma_f32_16x16x32_bf16 v[96:99], v[162:165], v[208:211], v[96:99]
	v_mfma_f32_16x16x32_bf16 v[84:87], v[154:157], v[216:219], v[84:87]
	v_mfma_f32_16x16x32_bf16 v[80:83], v[162:165], v[216:219], v[80:83]
	v_mfma_f32_16x16x32_bf16 v[108:111], v[166:169], v[182:185], v[108:111]
	v_mfma_f32_16x16x32_bf16 v[104:107], v[174:177], v[182:185], v[104:107]
	v_mfma_f32_16x16x32_bf16 v[92:95], v[166:169], v[196:199], v[92:95]
	v_mfma_f32_16x16x32_bf16 v[88:91], v[174:177], v[196:199], v[88:91]
	v_mfma_f32_16x16x32_bf16 v[76:79], v[166:169], v[204:207], v[76:79]
	v_mfma_f32_16x16x32_bf16 v[72:75], v[174:177], v[204:207], v[72:75]
	v_mfma_f32_16x16x32_bf16 v[68:71], v[166:169], v[212:215], v[68:71]
	v_mfma_f32_16x16x32_bf16 v[64:67], v[174:177], v[212:215], v[64:67]
	v_mfma_f32_16x16x32_bf16 v[108:111], v[170:173], v[186:189], v[108:111]
	v_mfma_f32_16x16x32_bf16 v[104:107], v[178:181], v[186:189], v[104:107]
	v_mfma_f32_16x16x32_bf16 v[92:95], v[170:173], v[200:203], v[92:95]
	v_mfma_f32_16x16x32_bf16 v[88:91], v[178:181], v[200:203], v[88:91]
	v_mfma_f32_16x16x32_bf16 v[76:79], v[170:173], v[208:211], v[76:79]
	v_mfma_f32_16x16x32_bf16 v[72:75], v[178:181], v[208:211], v[72:75]
	v_mfma_f32_16x16x32_bf16 v[68:71], v[170:173], v[216:219], v[68:71]
	v_mfma_f32_16x16x32_bf16 v[64:67], v[178:181], v[216:219], v[64:67]
	s_barrier
	s_add_i32 s44, s53, s3
	s_add_u32 s98, s36, s16
	s_addc_u32 s99, s37, s17
	s_mov_b32 m0, s44
	ds_read_b128 v[182:185], v149 offset:16384
	ds_read_b128 v[186:189], v149 offset:17408
	ds_read_b128 v[196:199], v149 offset:18432
	ds_read_b128 v[200:203], v149 offset:19456
	ds_read_b128 v[204:207], v149 offset:20480
	ds_read_b128 v[208:211], v149 offset:21504
	ds_read_b128 v[212:215], v149 offset:22528
	ds_read_b128 v[216:219], v149 offset:23552
	global_load_lds_dwordx4 v130, s[36:37]
	s_add_i32 m0, s44, 0x2000
	s_add_u32 s44, s36, 0x40000
	s_addc_u32 s45, s37, 0
	s_add_u32 s98, s36, s16
	s_addc_u32 s99, s37, s17
	s_add_i32 s48, s56, s3
	global_load_lds_dwordx4 v134, s[36:37]
	s_mov_b32 m0, s48
	v_lshl_add_u64 v[220:221], s[38:39], 0, v[132:133]
	global_load_lds_dwordx4 v130, s[44:45]
	s_add_i32 m0, s48, 0x2000
	s_nop 0
	global_load_lds_dwordx4 v134, s[44:45]
	s_add_u32 s100, s38, s16
	s_addc_u32 s101, s39, s17
	s_mov_b32 m0, s8
	s_nop 0
	global_load_lds_dwordx4 v128, s[38:39]
	s_mov_b32 m0, s9
	s_nop 0
	global_load_lds_dwordx4 v[220:221], off
	s_waitcnt vmcnt(8)
	s_waitcnt lgkmcnt(0)
	s_barrier
	v_mfma_f32_16x16x32_bf16 v[60:63], v[150:153], v[182:185], v[60:63]
	v_mfma_f32_16x16x32_bf16 v[56:59], v[158:161], v[182:185], v[56:59]
	v_mfma_f32_16x16x32_bf16 v[52:55], v[150:153], v[196:199], v[52:55]
	v_mfma_f32_16x16x32_bf16 v[48:51], v[158:161], v[196:199], v[48:51]
	v_mfma_f32_16x16x32_bf16 v[36:39], v[150:153], v[204:207], v[36:39]
	v_mfma_f32_16x16x32_bf16 v[32:35], v[158:161], v[204:207], v[32:35]
	v_mfma_f32_16x16x32_bf16 v[20:23], v[150:153], v[212:215], v[20:23]
	v_mfma_f32_16x16x32_bf16 v[16:19], v[158:161], v[212:215], v[16:19]
	v_mfma_f32_16x16x32_bf16 v[60:63], v[154:157], v[186:189], v[60:63]
	v_mfma_f32_16x16x32_bf16 v[56:59], v[162:165], v[186:189], v[56:59]
	v_mfma_f32_16x16x32_bf16 v[52:55], v[154:157], v[200:203], v[52:55]
	v_mfma_f32_16x16x32_bf16 v[48:51], v[162:165], v[200:203], v[48:51]
	v_mfma_f32_16x16x32_bf16 v[36:39], v[154:157], v[208:211], v[36:39]
	v_mfma_f32_16x16x32_bf16 v[32:35], v[162:165], v[208:211], v[32:35]
	v_mfma_f32_16x16x32_bf16 v[20:23], v[154:157], v[216:219], v[20:23]
	v_mfma_f32_16x16x32_bf16 v[16:19], v[162:165], v[216:219], v[16:19]
	v_mfma_f32_16x16x32_bf16 v[44:47], v[166:169], v[182:185], v[44:47]
	v_mfma_f32_16x16x32_bf16 v[40:43], v[174:177], v[182:185], v[40:43]
	v_mfma_f32_16x16x32_bf16 v[28:31], v[166:169], v[196:199], v[28:31]
	v_mfma_f32_16x16x32_bf16 v[24:27], v[174:177], v[196:199], v[24:27]
	v_mfma_f32_16x16x32_bf16 v[12:15], v[166:169], v[204:207], v[12:15]
	v_mfma_f32_16x16x32_bf16 v[8:11], v[174:177], v[204:207], v[8:11]
	v_mfma_f32_16x16x32_bf16 v[4:7], v[166:169], v[212:215], v[4:7]
	v_mfma_f32_16x16x32_bf16 v[0:3], v[174:177], v[212:215], v[0:3]
	v_mfma_f32_16x16x32_bf16 v[44:47], v[170:173], v[186:189], v[44:47]
	v_mfma_f32_16x16x32_bf16 v[40:43], v[178:181], v[186:189], v[40:43]
	v_mfma_f32_16x16x32_bf16 v[28:31], v[170:173], v[200:203], v[28:31]
	v_mfma_f32_16x16x32_bf16 v[24:27], v[178:181], v[200:203], v[24:27]
	v_mfma_f32_16x16x32_bf16 v[12:15], v[170:173], v[208:211], v[12:15]
	v_mfma_f32_16x16x32_bf16 v[8:11], v[178:181], v[208:211], v[8:11]
	v_mfma_f32_16x16x32_bf16 v[4:7], v[170:173], v[216:219], v[4:7]
	v_mfma_f32_16x16x32_bf16 v[0:3], v[178:181], v[216:219], v[0:3]
	s_barrier
; #define PG8_STAGE(bufoff, gbase, voff) do { _Pragma("unroll") for (int _i = 0; _i < 2; ++_i) \
;         __builtin_amdgcn_global_load_lds((const unsigned*)((const char*)(gbase) + (voff)[_i]), (PG8_LAS unsigned*)(lds + (bufoff) + ldsw + _i * 8192), 16, 0, 0); } while (0)
; #define PG8_LDA(dst, b, h) do { _Pragma("unroll") for (int m = 0; m < 4; ++m) _Pragma("unroll") for (int k = 0; k < 2; ++k) dst[m][k] = *(const PG8_LAS bf16x8*)(lds + PG8_SA(b, h) + aoff + m * 2048 + k * 1024); } while (0)
; #define PG8_LDB(dst, b, h) do { _Pragma("unroll") for (int n = 0; n < 2; ++n) _Pragma("unroll") for (int k = 0; k < 2; ++k) dst[n][k] = *(const PG8_LAS bf16x8*)(lds + PG8_SB(b, h) + boff + n * 2048 + k * 1024); } while (0)
; #define PG8_MMA(ai, bj, At, Bt) do { __builtin_amdgcn_s_setprio(1); _Pragma("unroll") for (int m = 0; m < 4; ++m) _Pragma("unroll") for (int n = 0; n < 2; ++n) _Pragma("unroll") for (int k = 0; k < 2; ++k) \
;         acc[ai][bj][m][n] = __builtin_amdgcn_mfma_f32_16x16x32_bf16(Bt[n][k], At[m][k], acc[ai][bj][m][n], 0, 0, 0); __builtin_amdgcn_s_setprio(0); } while (0)
; #define PG8_WAIT_V(n) asm volatile("s_waitcnt vmcnt(" #n ")" ::: "memory")
; #define PG8_WAIT_L(n) asm volatile("s_waitcnt lgkmcnt(" #n ")" ::: "memory")
; #define PG8_BAR __builtin_amdgcn_s_barrier()
; #define PG8_SCHED __builtin_amdgcn_sched_barrier(0)
; template <class Epi, class Sched, bool ALIGN_EPI = false, bool SP2 = false>
; __device__ __forceinline__ void gemm_phase(PG8_LAS unsigned char* lds, const Gemm g, const Sched& S, const Epi& E) {
;     ...
;             PG8_LDB(B0, 1, 0); PG8_LDB(B1, 1, 1); PG8_SCHED; PG8_LDA(At, 1, 0); PG8_STAGE(PG8_SA(0, 1), a2 + hstepA, voffA);
;             PG8_WAIT_V(8); PG8_WAIT_L(0); PG8_BAR; PG8_MMA(0, 0, At, B0); PG8_MMA(0, 1, At, B1); PG8_BAR; PG8_SCHED;
;             PG8_LDA(At, 1, 1); PG8_STAGE(PG8_SB(1, 0), b3, voffB); PG8_STAGE(PG8_SB(1, 1), b3 + hstepB, voffB); PG8_STAGE(PG8_SA(1, 0), a3, voffA);
;             PG8_WAIT_V(8); PG8_WAIT_L(0); PG8_BAR; PG8_MMA(1, 0, At, B0); PG8_MMA(1, 1, At, B1); PG8_BAR; PG8_SCHED;
	s_add_i32 s44, 0, 0x18000
	s_add_i32 s45, 0, 0x1c000
	v_add_u32_e32 v162, s44, v146
	v_add_u32_e32 v178, s45, v146
	ds_read_b128 v[150:153], v162
	ds_read_b128 v[154:157], v162 offset:1024
	ds_read_b128 v[158:161], v162 offset:2048
	ds_read_b128 v[162:165], v162 offset:3072
	ds_read_b128 v[166:169], v178
	ds_read_b128 v[170:173], v178 offset:1024
	ds_read_b128 v[174:177], v178 offset:2048
	ds_read_b128 v[178:181], v178 offset:3072
	s_add_u32 s38, s38, 0x40000
	s_addc_u32 s39, s39, 0
	s_mov_b32 m0, s23
	ds_read_b128 v[182:185], v149 offset:32768
	ds_read_b128 v[186:189], v149 offset:33792
	ds_read_b128 v[196:199], v149 offset:34816
	ds_read_b128 v[200:203], v149 offset:35840
	ds_read_b128 v[204:207], v149 offset:36864
	ds_read_b128 v[208:211], v149 offset:37888
	ds_read_b128 v[212:215], v149 offset:38912
	ds_read_b128 v[216:219], v149 offset:39936
	global_load_lds_dwordx4 v128, s[38:39]
	s_mov_b32 m0, s33
	s_nop 0
	global_load_lds_dwordx4 v132, s[38:39]
	s_waitcnt vmcnt(8)
	s_waitcnt lgkmcnt(0)
	s_barrier
	v_mfma_f32_16x16x32_bf16 v[124:127], v[150:153], v[182:185], v[124:127]
	v_mfma_f32_16x16x32_bf16 v[120:123], v[158:161], v[182:185], v[120:123]
	v_mfma_f32_16x16x32_bf16 v[116:119], v[150:153], v[196:199], v[116:119]
	v_mfma_f32_16x16x32_bf16 v[112:115], v[158:161], v[196:199], v[112:115]
	v_mfma_f32_16x16x32_bf16 v[100:103], v[150:153], v[204:207], v[100:103]
	v_mfma_f32_16x16x32_bf16 v[96:99], v[158:161], v[204:207], v[96:99]
	v_mfma_f32_16x16x32_bf16 v[84:87], v[150:153], v[212:215], v[84:87]
	v_mfma_f32_16x16x32_bf16 v[80:83], v[158:161], v[212:215], v[80:83]
	v_mfma_f32_16x16x32_bf16 v[124:127], v[154:157], v[186:189], v[124:127]
	v_mfma_f32_16x16x32_bf16 v[120:123], v[162:165], v[186:189], v[120:123]
	v_mfma_f32_16x16x32_bf16 v[116:119], v[154:157], v[200:203], v[116:119]
	v_mfma_f32_16x16x32_bf16 v[112:115], v[162:165], v[200:203], v[112:115]
	v_mfma_f32_16x16x32_bf16 v[100:103], v[154:157], v[208:211], v[100:103]
	v_mfma_f32_16x16x32_bf16 v[96:99], v[162:165], v[208:211], v[96:99]
	v_mfma_f32_16x16x32_bf16 v[84:87], v[154:157], v[216:219], v[84:87]
	v_mfma_f32_16x16x32_bf16 v[80:83], v[162:165], v[216:219], v[80:83]
	v_mfma_f32_16x16x32_bf16 v[108:111], v[166:169], v[182:185], v[108:111]
	v_mfma_f32_16x16x32_bf16 v[104:107], v[174:177], v[182:185], v[104:107]
	v_mfma_f32_16x16x32_bf16 v[92:95], v[166:169], v[196:199], v[92:95]
	v_mfma_f32_16x16x32_bf16 v[88:91], v[174:177], v[196:199], v[88:91]
	v_mfma_f32_16x16x32_bf16 v[76:79], v[166:169], v[204:207], v[76:79]
	v_mfma_f32_16x16x32_bf16 v[72:75], v[174:177], v[204:207], v[72:75]
	v_mfma_f32_16x16x32_bf16 v[68:71], v[166:169], v[212:215], v[68:71]
	v_mfma_f32_16x16x32_bf16 v[64:67], v[174:177], v[212:215], v[64:67]
	v_mfma_f32_16x16x32_bf16 v[108:111], v[170:173], v[186:189], v[108:111]
	v_mfma_f32_16x16x32_bf16 v[104:107], v[178:181], v[186:189], v[104:107]
	v_mfma_f32_16x16x32_bf16 v[92:95], v[170:173], v[200:203], v[92:95]
	v_mfma_f32_16x16x32_bf16 v[88:91], v[178:181], v[200:203], v[88:91]
	v_mfma_f32_16x16x32_bf16 v[76:79], v[170:173], v[208:211], v[76:79]
	v_mfma_f32_16x16x32_bf16 v[72:75], v[178:181], v[208:211], v[72:75]
	v_mfma_f32_16x16x32_bf16 v[68:71], v[170:173], v[216:219], v[68:71]
	v_mfma_f32_16x16x32_bf16 v[64:67], v[178:181], v[216:219], v[64:67]
	s_barrier
	s_add_i32 s38, s44, s3
	s_mov_b32 m0, s38
	ds_read_b128 v[182:185], v149 offset:49152
	ds_read_b128 v[186:189], v149 offset:50176
	ds_read_b128 v[196:199], v149 offset:51200
	ds_read_b128 v[200:203], v149 offset:52224
	ds_read_b128 v[204:207], v149 offset:53248
	ds_read_b128 v[208:211], v149 offset:54272
	ds_read_b128 v[212:215], v149 offset:55296
	ds_read_b128 v[216:219], v149 offset:56320
	global_load_lds_dwordx4 v130, s[98:99]
	s_add_i32 m0, s38, 0x2000
	s_add_u32 s36, s36, 0x40080
	s_addc_u32 s37, s37, 0
	s_add_i32 s38, s45, s3
	global_load_lds_dwordx4 v134, s[98:99]
	s_mov_b32 m0, s38
	s_nop 0
	global_load_lds_dwordx4 v130, s[36:37]
	s_add_i32 m0, s38, 0x2000
	s_nop 0
	global_load_lds_dwordx4 v134, s[36:37]
	s_mov_b32 m0, s43
	s_nop 0
	global_load_lds_dwordx4 v128, s[100:101]
	v_lshl_add_u64 v[190:191], v[220:221], 0, s[16:17]
	s_mov_b32 m0, s50
	s_nop 0
	global_load_lds_dwordx4 v[190:191], off
	s_waitcnt vmcnt(8)
	s_waitcnt lgkmcnt(0)
	s_barrier
	v_mfma_f32_16x16x32_bf16 v[60:63], v[150:153], v[182:185], v[60:63]
	v_mfma_f32_16x16x32_bf16 v[56:59], v[158:161], v[182:185], v[56:59]
	v_mfma_f32_16x16x32_bf16 v[52:55], v[150:153], v[196:199], v[52:55]
	v_mfma_f32_16x16x32_bf16 v[48:51], v[158:161], v[196:199], v[48:51]
	v_mfma_f32_16x16x32_bf16 v[36:39], v[150:153], v[204:207], v[36:39]
	v_mfma_f32_16x16x32_bf16 v[32:35], v[158:161], v[204:207], v[32:35]
	v_mfma_f32_16x16x32_bf16 v[20:23], v[150:153], v[212:215], v[20:23]
	v_mfma_f32_16x16x32_bf16 v[16:19], v[158:161], v[212:215], v[16:19]
	v_mfma_f32_16x16x32_bf16 v[60:63], v[154:157], v[186:189], v[60:63]
	v_mfma_f32_16x16x32_bf16 v[56:59], v[162:165], v[186:189], v[56:59]
	v_mfma_f32_16x16x32_bf16 v[52:55], v[154:157], v[200:203], v[52:55]
	v_mfma_f32_16x16x32_bf16 v[48:51], v[162:165], v[200:203], v[48:51]
	v_mfma_f32_16x16x32_bf16 v[36:39], v[154:157], v[208:211], v[36:39]
	v_mfma_f32_16x16x32_bf16 v[32:35], v[162:165], v[208:211], v[32:35]
	v_mfma_f32_16x16x32_bf16 v[20:23], v[154:157], v[216:219], v[20:23]
	v_mfma_f32_16x16x32_bf16 v[16:19], v[162:165], v[216:219], v[16:19]
	v_mfma_f32_16x16x32_bf16 v[44:47], v[166:169], v[182:185], v[44:47]
	v_mfma_f32_16x16x32_bf16 v[40:43], v[174:177], v[182:185], v[40:43]
	v_mfma_f32_16x16x32_bf16 v[28:31], v[166:169], v[196:199], v[28:31]
	v_mfma_f32_16x16x32_bf16 v[24:27], v[174:177], v[196:199], v[24:27]
	v_mfma_f32_16x16x32_bf16 v[12:15], v[166:169], v[204:207], v[12:15]
	v_mfma_f32_16x16x32_bf16 v[8:11], v[174:177], v[204:207], v[8:11]
	v_mfma_f32_16x16x32_bf16 v[4:7], v[166:169], v[212:215], v[4:7]
	v_mfma_f32_16x16x32_bf16 v[0:3], v[174:177], v[212:215], v[0:3]
	v_mfma_f32_16x16x32_bf16 v[44:47], v[170:173], v[186:189], v[44:47]
	v_mfma_f32_16x16x32_bf16 v[40:43], v[178:181], v[186:189], v[40:43]
	v_mfma_f32_16x16x32_bf16 v[28:31], v[170:173], v[200:203], v[28:31]
	v_mfma_f32_16x16x32_bf16 v[24:27], v[178:181], v[200:203], v[24:27]
	v_mfma_f32_16x16x32_bf16 v[12:15], v[170:173], v[208:211], v[12:15]
	v_mfma_f32_16x16x32_bf16 v[8:11], v[178:181], v[208:211], v[8:11]
	v_mfma_f32_16x16x32_bf16 v[4:7], v[170:173], v[216:219], v[4:7]
	v_mfma_f32_16x16x32_bf16 v[0:3], v[178:181], v[216:219], v[0:3]
	s_barrier
	s_add_i32 s64, s64, 2
	s_add_u32 s34, s34, 0x100
	s_addc_u32 s35, s35, 0
	s_add_u32 s62, s62, 0x100
	s_addc_u32 s63, s63, 0
	s_cmp_gt_u32 s64, 13
	s_cbranch_scc0 .LBB0_186
	s_and_b64 vcc, exec, s[18:19]
	s_cbranch_vccz .LBB0_189
	s_barrier

; #define PG8_STAGE(bufoff, gbase, voff) do { _Pragma("unroll") for (int _i = 0; _i < 2; ++_i) \
;         __builtin_amdgcn_global_load_lds((const unsigned*)((const char*)(gbase) + (voff)[_i]), (PG8_LAS unsigned*)(lds + (bufoff) + ldsw + _i * 8192), 16, 0, 0); } while (0)
; #define PG8_LDA(dst, b, h) do { _Pragma("unroll") for (int m = 0; m < 4; ++m) _Pragma("unroll") for (int k = 0; k < 2; ++k) dst[m][k] = *(const PG8_LAS bf16x8*)(lds + PG8_SA(b, h) + aoff + m * 2048 + k * 1024); } while (0)
; #define PG8_LDB(dst, b, h) do { _Pragma("unroll") for (int n = 0; n < 2; ++n) _Pragma("unroll") for (int k = 0; k < 2; ++k) dst[n][k] = *(const PG8_LAS bf16x8*)(lds + PG8_SB(b, h) + boff + n * 2048 + k * 1024); } while (0)
; #define PG8_MMA(ai, bj, At, Bt) do { __builtin_amdgcn_s_setprio(1); _Pragma("unroll") for (int m = 0; m < 4; ++m) _Pragma("unroll") for (int n = 0; n < 2; ++n) _Pragma("unroll") for (int k = 0; k < 2; ++k) \
;         acc[ai][bj][m][n] = __builtin_amdgcn_mfma_f32_16x16x32_bf16(Bt[n][k], At[m][k], acc[ai][bj][m][n], 0, 0, 0); __builtin_amdgcn_s_setprio(0); } while (0)
; #define PG8_WAIT_V(n) asm volatile("s_waitcnt vmcnt(" #n ")" ::: "memory")
; #define PG8_WAIT_L(n) asm volatile("s_waitcnt lgkmcnt(" #n ")" ::: "memory")
; #define PG8_BAR __builtin_amdgcn_s_barrier()
; template <class Epi, class Sched, bool ALIGN_EPI = false, bool SP2 = false>
; __device__ __forceinline__ void gemm_phase(PG8_LAS unsigned char* lds, const Gemm g, const Sched& S, const Epi& E) {
;     ...
;             const char* a1 = cA + (size_t)(t + 1) * kstep;
;             const char* a2 = last ? nA : cA + (size_t)(t + 2) * kstep; const char* b2 = last ? nB : cB + (size_t)(t + 2) * kstep;
;             const char* a3 = a2 + kstep; const char* b3 = b2 + kstep;
;             if (last && has_next) S.a_ready(nxt);
;             if constexpr (SP2) {
;             PG8_LDB(B0, 0, 0); PG8_LDB(B1, 0, 1); PG8_SCHED; PG8_LDA(At, 0, 0); PG8_STAGE(PG8_SA(1, 1), a1 + hstepA, voffA);
;             PG8_WAIT_V(8); PG8_WAIT_L(0); PG8_BAR; PG8_MMA(0, 0, At, B0); PG8_MMA(0, 1, At, B1); PG8_BAR; PG8_SCHED;
;             PG8_LDA(At, 0, 1); PG8_STAGE(PG8_SB(0, 0), b2, voffB); PG8_STAGE(PG8_SB(0, 1), b2 + hstepB, voffB); PG8_STAGE(PG8_SA(0, 0), a2, voffA);
;             PG8_WAIT_V(8); PG8_WAIT_L(0); PG8_BAR; PG8_MMA(1, 0, At, B0); PG8_MMA(1, 1, At, B1); PG8_BAR; PG8_SCHED;
.LBB0_210:
	ds_read_b128 v[146:149], v143
	ds_read_b128 v[150:153], v143 offset:1024
	ds_read_b128 v[154:157], v143 offset:2048
	ds_read_b128 v[158:161], v143 offset:3072
	ds_read_b128 v[162:165], v144
	ds_read_b128 v[166:169], v144 offset:1024
	ds_read_b128 v[170:173], v144 offset:2048
	ds_read_b128 v[174:177], v144 offset:3072
	s_add_u32 s36, s34, 0xfffc0080
	s_addc_u32 s37, s35, -1
	s_cmp_eq_u32 s64, 12
	s_cselect_b32 s39, s25, s37
	s_cselect_b32 s38, s60, s36
	s_cselect_b32 s37, s23, s63
	s_cselect_b32 s36, s61, s62
	s_add_i32 m0, s31, 0xc000
	ds_read_b128 v[178:181], v145
	ds_read_b128 v[182:185], v145 offset:1024
	ds_read_b128 v[186:189], v145 offset:2048
	ds_read_b128 v[196:199], v145 offset:3072
	ds_read_b128 v[200:203], v145 offset:4096
	ds_read_b128 v[204:207], v145 offset:5120
	ds_read_b128 v[208:211], v145 offset:6144
	ds_read_b128 v[212:215], v145 offset:7168
	global_load_lds_dwordx4 v132, s[34:35]
	s_add_i32 m0, s31, 0xe000
	s_nop 0
	global_load_lds_dwordx4 v134, s[34:35]
	s_waitcnt vmcnt(8)
	s_waitcnt lgkmcnt(0)
	s_barrier
	v_mfma_f32_16x16x32_bf16 v[124:127], v[146:149], v[178:181], v[124:127]
	v_mfma_f32_16x16x32_bf16 v[120:123], v[154:157], v[178:181], v[120:123]
	v_mfma_f32_16x16x32_bf16 v[108:111], v[146:149], v[186:189], v[108:111]
	v_mfma_f32_16x16x32_bf16 v[104:107], v[154:157], v[186:189], v[104:107]
	v_mfma_f32_16x16x32_bf16 v[92:95], v[146:149], v[200:203], v[92:95]
	v_mfma_f32_16x16x32_bf16 v[88:91], v[154:157], v[200:203], v[88:91]
	v_mfma_f32_16x16x32_bf16 v[76:79], v[146:149], v[208:211], v[76:79]
	v_mfma_f32_16x16x32_bf16 v[72:75], v[154:157], v[208:211], v[72:75]
	v_mfma_f32_16x16x32_bf16 v[124:127], v[150:153], v[182:185], v[124:127]
	v_mfma_f32_16x16x32_bf16 v[120:123], v[158:161], v[182:185], v[120:123]
	v_mfma_f32_16x16x32_bf16 v[108:111], v[150:153], v[196:199], v[108:111]
	v_mfma_f32_16x16x32_bf16 v[104:107], v[158:161], v[196:199], v[104:107]
	v_mfma_f32_16x16x32_bf16 v[92:95], v[150:153], v[204:207], v[92:95]
	v_mfma_f32_16x16x32_bf16 v[88:91], v[158:161], v[204:207], v[88:91]
	v_mfma_f32_16x16x32_bf16 v[76:79], v[150:153], v[212:215], v[76:79]
	v_mfma_f32_16x16x32_bf16 v[72:75], v[158:161], v[212:215], v[72:75]
	v_mfma_f32_16x16x32_bf16 v[116:119], v[162:165], v[178:181], v[116:119]
	v_mfma_f32_16x16x32_bf16 v[112:115], v[170:173], v[178:181], v[112:115]
	v_mfma_f32_16x16x32_bf16 v[100:103], v[162:165], v[186:189], v[100:103]
	v_mfma_f32_16x16x32_bf16 v[96:99], v[170:173], v[186:189], v[96:99]
	v_mfma_f32_16x16x32_bf16 v[84:87], v[162:165], v[200:203], v[84:87]
	v_mfma_f32_16x16x32_bf16 v[80:83], v[170:173], v[200:203], v[80:83]
	v_mfma_f32_16x16x32_bf16 v[68:71], v[162:165], v[208:211], v[68:71]
	v_mfma_f32_16x16x32_bf16 v[64:67], v[170:173], v[208:211], v[64:67]
	v_mfma_f32_16x16x32_bf16 v[116:119], v[166:169], v[182:185], v[116:119]
	v_mfma_f32_16x16x32_bf16 v[112:115], v[174:177], v[182:185], v[112:115]
	v_mfma_f32_16x16x32_bf16 v[100:103], v[166:169], v[196:199], v[100:103]
	v_mfma_f32_16x16x32_bf16 v[96:99], v[174:177], v[196:199], v[96:99]
	v_mfma_f32_16x16x32_bf16 v[84:87], v[166:169], v[204:207], v[84:87]
	v_mfma_f32_16x16x32_bf16 v[80:83], v[174:177], v[204:207], v[80:83]
	v_mfma_f32_16x16x32_bf16 v[68:71], v[166:169], v[212:215], v[68:71]
	v_mfma_f32_16x16x32_bf16 v[64:67], v[174:177], v[212:215], v[64:67]
	s_barrier
	s_add_i32 s44, s57, s9
	s_add_u32 s98, s36, s16
	s_addc_u32 s99, s37, s17
	s_mov_b32 m0, s44
	ds_read_b128 v[178:181], v145 offset:16384
	ds_read_b128 v[182:185], v145 offset:17408
	ds_read_b128 v[186:189], v145 offset:18432
	ds_read_b128 v[196:199], v145 offset:19456
	ds_read_b128 v[200:203], v145 offset:20480
	ds_read_b128 v[204:207], v145 offset:21504
	ds_read_b128 v[208:211], v145 offset:22528
	ds_read_b128 v[212:215], v145 offset:23552
	global_load_lds_dwordx4 v128, s[36:37]
	s_add_i32 m0, s44, 0x2000
	s_add_u32 s44, s36, 0x40000
	s_addc_u32 s45, s37, 0
	s_add_u32 s98, s36, s16
	s_addc_u32 s99, s37, s17
	s_add_i32 s48, s58, s9
	global_load_lds_dwordx4 v130, s[36:37]
	s_mov_b32 m0, s48
	v_lshl_add_u64 v[216:217], s[38:39], 0, v[130:131]
	global_load_lds_dwordx4 v128, s[44:45]
	s_add_i32 m0, s48, 0x2000
	s_nop 0
	global_load_lds_dwordx4 v130, s[44:45]
	s_add_u32 s100, s38, s16
	s_addc_u32 s101, s39, s17
	s_mov_b32 m0, s31
	s_nop 0
	global_load_lds_dwordx4 v128, s[38:39]
	s_mov_b32 m0, s33
	s_nop 0
	global_load_lds_dwordx4 v[216:217], off
	s_waitcnt vmcnt(8)
	s_waitcnt lgkmcnt(0)
	s_barrier
	v_mfma_f32_16x16x32_bf16 v[60:63], v[146:149], v[178:181], v[60:63]
	v_mfma_f32_16x16x32_bf16 v[56:59], v[154:157], v[178:181], v[56:59]
	v_mfma_f32_16x16x32_bf16 v[44:47], v[146:149], v[186:189], v[44:47]
	v_mfma_f32_16x16x32_bf16 v[40:43], v[154:157], v[186:189], v[40:43]
	v_mfma_f32_16x16x32_bf16 v[28:31], v[146:149], v[200:203], v[28:31]
	v_mfma_f32_16x16x32_bf16 v[24:27], v[154:157], v[200:203], v[24:27]
	v_mfma_f32_16x16x32_bf16 v[12:15], v[146:149], v[208:211], v[12:15]
	v_mfma_f32_16x16x32_bf16 v[8:11], v[154:157], v[208:211], v[8:11]
	v_mfma_f32_16x16x32_bf16 v[60:63], v[150:153], v[182:185], v[60:63]
	v_mfma_f32_16x16x32_bf16 v[56:59], v[158:161], v[182:185], v[56:59]
	v_mfma_f32_16x16x32_bf16 v[44:47], v[150:153], v[196:199], v[44:47]
	v_mfma_f32_16x16x32_bf16 v[40:43], v[158:161], v[196:199], v[40:43]
	v_mfma_f32_16x16x32_bf16 v[28:31], v[150:153], v[204:207], v[28:31]
	v_mfma_f32_16x16x32_bf16 v[24:27], v[158:161], v[204:207], v[24:27]
	v_mfma_f32_16x16x32_bf16 v[12:15], v[150:153], v[212:215], v[12:15]
	v_mfma_f32_16x16x32_bf16 v[8:11], v[158:161], v[212:215], v[8:11]
	v_mfma_f32_16x16x32_bf16 v[52:55], v[162:165], v[178:181], v[52:55]
	v_mfma_f32_16x16x32_bf16 v[48:51], v[170:173], v[178:181], v[48:51]
	v_mfma_f32_16x16x32_bf16 v[36:39], v[162:165], v[186:189], v[36:39]
	v_mfma_f32_16x16x32_bf16 v[32:35], v[170:173], v[186:189], v[32:35]
	v_mfma_f32_16x16x32_bf16 v[20:23], v[162:165], v[200:203], v[20:23]
	v_mfma_f32_16x16x32_bf16 v[16:19], v[170:173], v[200:203], v[16:19]
	v_mfma_f32_16x16x32_bf16 v[4:7], v[162:165], v[208:211], v[4:7]
	v_mfma_f32_16x16x32_bf16 v[0:3], v[170:173], v[208:211], v[0:3]
	v_mfma_f32_16x16x32_bf16 v[52:55], v[166:169], v[182:185], v[52:55]
	v_mfma_f32_16x16x32_bf16 v[48:51], v[174:177], v[182:185], v[48:51]
	v_mfma_f32_16x16x32_bf16 v[36:39], v[166:169], v[196:199], v[36:39]
	v_mfma_f32_16x16x32_bf16 v[32:35], v[174:177], v[196:199], v[32:35]
	v_mfma_f32_16x16x32_bf16 v[20:23], v[166:169], v[204:207], v[20:23]
	v_mfma_f32_16x16x32_bf16 v[16:19], v[174:177], v[204:207], v[16:19]
	v_mfma_f32_16x16x32_bf16 v[4:7], v[166:169], v[212:215], v[4:7]
	v_mfma_f32_16x16x32_bf16 v[0:3], v[174:177], v[212:215], v[0:3]
	s_barrier
; #define PG8_STAGE(bufoff, gbase, voff) do { _Pragma("unroll") for (int _i = 0; _i < 2; ++_i) \
;         __builtin_amdgcn_global_load_lds((const unsigned*)((const char*)(gbase) + (voff)[_i]), (PG8_LAS unsigned*)(lds + (bufoff) + ldsw + _i * 8192), 16, 0, 0); } while (0)
; #define PG8_LDA(dst, b, h) do { _Pragma("unroll") for (int m = 0; m < 4; ++m) _Pragma("unroll") for (int k = 0; k < 2; ++k) dst[m][k] = *(const PG8_LAS bf16x8*)(lds + PG8_SA(b, h) + aoff + m * 2048 + k * 1024); } while (0)
; #define PG8_LDB(dst, b, h) do { _Pragma("unroll") for (int n = 0; n < 2; ++n) _Pragma("unroll") for (int k = 0; k < 2; ++k) dst[n][k] = *(const PG8_LAS bf16x8*)(lds + PG8_SB(b, h) + boff + n * 2048 + k * 1024); } while (0)
; #define PG8_MMA(ai, bj, At, Bt) do { __builtin_amdgcn_s_setprio(1); _Pragma("unroll") for (int m = 0; m < 4; ++m) _Pragma("unroll") for (int n = 0; n < 2; ++n) _Pragma("unroll") for (int k = 0; k < 2; ++k) \
;         acc[ai][bj][m][n] = __builtin_amdgcn_mfma_f32_16x16x32_bf16(Bt[n][k], At[m][k], acc[ai][bj][m][n], 0, 0, 0); __builtin_amdgcn_s_setprio(0); } while (0)
; #define PG8_WAIT_V(n) asm volatile("s_waitcnt vmcnt(" #n ")" ::: "memory")
; #define PG8_WAIT_L(n) asm volatile("s_waitcnt lgkmcnt(" #n ")" ::: "memory")
; #define PG8_BAR __builtin_amdgcn_s_barrier()
; #define PG8_SCHED __builtin_amdgcn_sched_barrier(0)
; template <class Epi, class Sched, bool ALIGN_EPI = false, bool SP2 = false>
; __device__ __forceinline__ void gemm_phase(PG8_LAS unsigned char* lds, const Gemm g, const Sched& S, const Epi& E) {
;     ...
;             PG8_LDB(B0, 1, 0); PG8_LDB(B1, 1, 1); PG8_SCHED; PG8_LDA(At, 1, 0); PG8_STAGE(PG8_SA(0, 1), a2 + hstepA, voffA);
;             PG8_WAIT_V(8); PG8_WAIT_L(0); PG8_BAR; PG8_MMA(0, 0, At, B0); PG8_MMA(0, 1, At, B1); PG8_BAR; PG8_SCHED;
;             PG8_LDA(At, 1, 1); PG8_STAGE(PG8_SB(1, 0), b3, voffB); PG8_STAGE(PG8_SB(1, 1), b3 + hstepB, voffB); PG8_STAGE(PG8_SA(1, 0), a3, voffA);
;             PG8_WAIT_V(8); PG8_WAIT_L(0); PG8_BAR; PG8_MMA(1, 0, At, B0); PG8_MMA(1, 1, At, B1); PG8_BAR; PG8_SCHED;
	s_add_i32 s44, 0, 0x18000
	s_add_i32 s45, 0, 0x1c000
	v_add_u32_e32 v158, s44, v142
	v_add_u32_e32 v174, s45, v142
	ds_read_b128 v[146:149], v158
	ds_read_b128 v[150:153], v158 offset:1024
	ds_read_b128 v[154:157], v158 offset:2048
	ds_read_b128 v[158:161], v158 offset:3072
	ds_read_b128 v[162:165], v174
	ds_read_b128 v[166:169], v174 offset:1024
	ds_read_b128 v[170:173], v174 offset:2048
	ds_read_b128 v[174:177], v174 offset:3072
	s_add_u32 s38, s38, 0x40000
	s_addc_u32 s39, s39, 0
	s_mov_b32 m0, s40
	ds_read_b128 v[178:181], v145 offset:32768
	ds_read_b128 v[182:185], v145 offset:33792
	ds_read_b128 v[186:189], v145 offset:34816
	ds_read_b128 v[196:199], v145 offset:35840
	ds_read_b128 v[200:203], v145 offset:36864
	ds_read_b128 v[204:207], v145 offset:37888
	ds_read_b128 v[208:211], v145 offset:38912
	ds_read_b128 v[212:215], v145 offset:39936
	global_load_lds_dwordx4 v128, s[38:39]
	s_mov_b32 m0, s41
	s_nop 0
	global_load_lds_dwordx4 v130, s[38:39]
	s_waitcnt vmcnt(8)
	s_waitcnt lgkmcnt(0)
	s_barrier
	v_mfma_f32_16x16x32_bf16 v[124:127], v[146:149], v[178:181], v[124:127]
	v_mfma_f32_16x16x32_bf16 v[120:123], v[154:157], v[178:181], v[120:123]
	v_mfma_f32_16x16x32_bf16 v[108:111], v[146:149], v[186:189], v[108:111]
	v_mfma_f32_16x16x32_bf16 v[104:107], v[154:157], v[186:189], v[104:107]
	v_mfma_f32_16x16x32_bf16 v[92:95], v[146:149], v[200:203], v[92:95]
	v_mfma_f32_16x16x32_bf16 v[88:91], v[154:157], v[200:203], v[88:91]
	v_mfma_f32_16x16x32_bf16 v[76:79], v[146:149], v[208:211], v[76:79]
	v_mfma_f32_16x16x32_bf16 v[72:75], v[154:157], v[208:211], v[72:75]
	v_mfma_f32_16x16x32_bf16 v[124:127], v[150:153], v[182:185], v[124:127]
	v_mfma_f32_16x16x32_bf16 v[120:123], v[158:161], v[182:185], v[120:123]
	v_mfma_f32_16x16x32_bf16 v[108:111], v[150:153], v[196:199], v[108:111]
	v_mfma_f32_16x16x32_bf16 v[104:107], v[158:161], v[196:199], v[104:107]
	v_mfma_f32_16x16x32_bf16 v[92:95], v[150:153], v[204:207], v[92:95]
	v_mfma_f32_16x16x32_bf16 v[88:91], v[158:161], v[204:207], v[88:91]
	v_mfma_f32_16x16x32_bf16 v[76:79], v[150:153], v[212:215], v[76:79]
	v_mfma_f32_16x16x32_bf16 v[72:75], v[158:161], v[212:215], v[72:75]
	v_mfma_f32_16x16x32_bf16 v[116:119], v[162:165], v[178:181], v[116:119]
	v_mfma_f32_16x16x32_bf16 v[112:115], v[170:173], v[178:181], v[112:115]
	v_mfma_f32_16x16x32_bf16 v[100:103], v[162:165], v[186:189], v[100:103]
	v_mfma_f32_16x16x32_bf16 v[96:99], v[170:173], v[186:189], v[96:99]
	v_mfma_f32_16x16x32_bf16 v[84:87], v[162:165], v[200:203], v[84:87]
	v_mfma_f32_16x16x32_bf16 v[80:83], v[170:173], v[200:203], v[80:83]
	v_mfma_f32_16x16x32_bf16 v[68:71], v[162:165], v[208:211], v[68:71]
	v_mfma_f32_16x16x32_bf16 v[64:67], v[170:173], v[208:211], v[64:67]
	v_mfma_f32_16x16x32_bf16 v[116:119], v[166:169], v[182:185], v[116:119]
	v_mfma_f32_16x16x32_bf16 v[112:115], v[174:177], v[182:185], v[112:115]
	v_mfma_f32_16x16x32_bf16 v[100:103], v[166:169], v[196:199], v[100:103]
	v_mfma_f32_16x16x32_bf16 v[96:99], v[174:177], v[196:199], v[96:99]
	v_mfma_f32_16x16x32_bf16 v[84:87], v[166:169], v[204:207], v[84:87]
	v_mfma_f32_16x16x32_bf16 v[80:83], v[174:177], v[204:207], v[80:83]
	v_mfma_f32_16x16x32_bf16 v[68:71], v[166:169], v[212:215], v[68:71]
	v_mfma_f32_16x16x32_bf16 v[64:67], v[174:177], v[212:215], v[64:67]
	s_barrier
	s_add_i32 s38, s44, s9
	s_mov_b32 m0, s38
	ds_read_b128 v[178:181], v145 offset:49152
	ds_read_b128 v[182:185], v145 offset:50176
	ds_read_b128 v[186:189], v145 offset:51200
	ds_read_b128 v[196:199], v145 offset:52224
	ds_read_b128 v[200:203], v145 offset:53248
	ds_read_b128 v[204:207], v145 offset:54272
	ds_read_b128 v[208:211], v145 offset:55296
	ds_read_b128 v[212:215], v145 offset:56320
	global_load_lds_dwordx4 v128, s[98:99]
	s_add_i32 m0, s38, 0x2000
	s_add_u32 s36, s36, 0x40080
	s_addc_u32 s37, s37, 0
	s_add_i32 s38, s45, s9
	global_load_lds_dwordx4 v130, s[98:99]
	s_mov_b32 m0, s38
	s_nop 0
	global_load_lds_dwordx4 v128, s[36:37]
	s_add_i32 m0, s38, 0x2000
	s_nop 0
	global_load_lds_dwordx4 v130, s[36:37]
	s_mov_b32 m0, s50
	s_nop 0
	global_load_lds_dwordx4 v128, s[100:101]
	v_lshl_add_u64 v[190:191], v[216:217], 0, s[16:17]
	s_mov_b32 m0, s51
	s_nop 0
	global_load_lds_dwordx4 v[190:191], off
	s_waitcnt vmcnt(8)
	s_waitcnt lgkmcnt(0)
	s_barrier
	v_mfma_f32_16x16x32_bf16 v[60:63], v[146:149], v[178:181], v[60:63]
	v_mfma_f32_16x16x32_bf16 v[56:59], v[154:157], v[178:181], v[56:59]
	v_mfma_f32_16x16x32_bf16 v[44:47], v[146:149], v[186:189], v[44:47]
	v_mfma_f32_16x16x32_bf16 v[40:43], v[154:157], v[186:189], v[40:43]
	v_mfma_f32_16x16x32_bf16 v[28:31], v[146:149], v[200:203], v[28:31]
	v_mfma_f32_16x16x32_bf16 v[24:27], v[154:157], v[200:203], v[24:27]
	v_mfma_f32_16x16x32_bf16 v[12:15], v[146:149], v[208:211], v[12:15]
	v_mfma_f32_16x16x32_bf16 v[8:11], v[154:157], v[208:211], v[8:11]
	v_mfma_f32_16x16x32_bf16 v[60:63], v[150:153], v[182:185], v[60:63]
	v_mfma_f32_16x16x32_bf16 v[56:59], v[158:161], v[182:185], v[56:59]
	v_mfma_f32_16x16x32_bf16 v[44:47], v[150:153], v[196:199], v[44:47]
	v_mfma_f32_16x16x32_bf16 v[40:43], v[158:161], v[196:199], v[40:43]
	v_mfma_f32_16x16x32_bf16 v[28:31], v[150:153], v[204:207], v[28:31]
	v_mfma_f32_16x16x32_bf16 v[24:27], v[158:161], v[204:207], v[24:27]
	v_mfma_f32_16x16x32_bf16 v[12:15], v[150:153], v[212:215], v[12:15]
	v_mfma_f32_16x16x32_bf16 v[8:11], v[158:161], v[212:215], v[8:11]
	v_mfma_f32_16x16x32_bf16 v[52:55], v[162:165], v[178:181], v[52:55]
	v_mfma_f32_16x16x32_bf16 v[48:51], v[170:173], v[178:181], v[48:51]
	v_mfma_f32_16x16x32_bf16 v[36:39], v[162:165], v[186:189], v[36:39]
	v_mfma_f32_16x16x32_bf16 v[32:35], v[170:173], v[186:189], v[32:35]
	v_mfma_f32_16x16x32_bf16 v[20:23], v[162:165], v[200:203], v[20:23]
	v_mfma_f32_16x16x32_bf16 v[16:19], v[170:173], v[200:203], v[16:19]
	v_mfma_f32_16x16x32_bf16 v[4:7], v[162:165], v[208:211], v[4:7]
	v_mfma_f32_16x16x32_bf16 v[0:3], v[170:173], v[208:211], v[0:3]
	v_mfma_f32_16x16x32_bf16 v[52:55], v[166:169], v[182:185], v[52:55]
	v_mfma_f32_16x16x32_bf16 v[48:51], v[174:177], v[182:185], v[48:51]
	v_mfma_f32_16x16x32_bf16 v[36:39], v[166:169], v[196:199], v[36:39]
	v_mfma_f32_16x16x32_bf16 v[32:35], v[174:177], v[196:199], v[32:35]
	v_mfma_f32_16x16x32_bf16 v[20:23], v[166:169], v[204:207], v[20:23]
	v_mfma_f32_16x16x32_bf16 v[16:19], v[174:177], v[204:207], v[16:19]
	v_mfma_f32_16x16x32_bf16 v[4:7], v[166:169], v[212:215], v[4:7]
	v_mfma_f32_16x16x32_bf16 v[0:3], v[174:177], v[212:215], v[0:3]
	s_barrier
	s_add_i32 s64, s64, 2
	s_add_u32 s34, s34, 0x100
	s_addc_u32 s35, s35, 0
	s_add_u32 s62, s62, 0x100
	s_addc_u32 s63, s63, 0
	s_cmp_gt_u32 s64, 13
	s_cbranch_scc0 .LBB0_210
	s_and_b64 vcc, exec, s[18:19]
	s_cbranch_vccz .LBB0_213
	s_barrier

; #define PG8_STAGE(bufoff, gbase, voff) do { _Pragma("unroll") for (int _i = 0; _i < 2; ++_i) \
;         __builtin_amdgcn_global_load_lds((const unsigned*)((const char*)(gbase) + (voff)[_i]), (PG8_LAS unsigned*)(lds + (bufoff) + ldsw + _i * 8192), 16, 0, 0); } while (0)
; #define PG8_LDA(dst, b, h) do { _Pragma("unroll") for (int m = 0; m < 4; ++m) _Pragma("unroll") for (int k = 0; k < 2; ++k) dst[m][k] = *(const PG8_LAS bf16x8*)(lds + PG8_SA(b, h) + aoff + m * 2048 + k * 1024); } while (0)
; #define PG8_LDB(dst, b, h) do { _Pragma("unroll") for (int n = 0; n < 2; ++n) _Pragma("unroll") for (int k = 0; k < 2; ++k) dst[n][k] = *(const PG8_LAS bf16x8*)(lds + PG8_SB(b, h) + boff + n * 2048 + k * 1024); } while (0)
; #define PG8_WAIT_V(n) asm volatile("s_waitcnt vmcnt(" #n ")" ::: "memory")
; #define PG8_WAIT_L(n) asm volatile("s_waitcnt lgkmcnt(" #n ")" ::: "memory")
; #define PG8_BAR __builtin_amdgcn_s_barrier()
; #define PG8_SCHED __builtin_amdgcn_sched_barrier(0)
; template <class Epi, class Sched, bool ALIGN_EPI = false, bool SP2 = false>
; __device__ __forceinline__ void gemm_phase(PG8_LAS unsigned char* lds, const Gemm g, const Sched& S, const Epi& E) {
;     ...
;         const char* nA = has_next ? (const char*)g.A + (size_t)nxt.pm * tstepA : cA; const char* nB = has_next ? (const char*)g.Bt + (size_t)nxt.pn * tstepB : cB;
;         for (int t = 0; t < nt; t += 2) {
;             const bool last = (t == nt - 2);
;             const char* a1 = cA + (size_t)(t + 1) * kstep;
;             const char* a2 = last ? nA : cA + (size_t)(t + 2) * kstep; const char* b2 = last ? nB : cB + (size_t)(t + 2) * kstep;
;             const char* a3 = a2 + kstep; const char* b3 = b2 + kstep;
;             if (last && has_next) S.a_ready(nxt);
;             if constexpr (SP2) {
;             PG8_LDB(B0, 0, 0); PG8_LDB(B1, 0, 1); PG8_SCHED; PG8_LDA(At, 0, 0); PG8_STAGE(PG8_SA(1, 1), a1 + hstepA, voffA);
;             PG8_WAIT_V(8); PG8_WAIT_L(0); PG8_BAR; PG8_MMA(0, 0, At, B0); PG8_MMA(0, 1, At, B1); PG8_BAR; PG8_SCHED;
;             PG8_LDA(At, 0, 1); PG8_STAGE(PG8_SB(0, 0), b2, voffB); PG8_STAGE(PG8_SB(0, 1), b2 + hstepB, voffB); PG8_STAGE(PG8_SA(0, 0), a2, voffA);
;             PG8_WAIT_V(8); PG8_WAIT_L(0); PG8_BAR; PG8_MMA(1, 0, At, B0); PG8_MMA(1, 1, At, B1); PG8_BAR; PG8_SCHED;
.LBB0_234:
	ds_read_b128 v[0:3], v143
	ds_read_b128 v[4:7], v143 offset:1024
	ds_read_b128 v[8:11], v143 offset:2048
	ds_read_b128 v[12:15], v143 offset:3072
	ds_read_b128 v[16:19], v144
	ds_read_b128 v[20:23], v144 offset:1024
	ds_read_b128 v[24:27], v144 offset:2048
	ds_read_b128 v[28:31], v144 offset:3072
	s_ashr_i32 s31, s30, 31
	s_lshl_b64 s[34:35], s[30:31], 17
	s_add_u32 s34, s54, s34
	s_addc_u32 s35, s55, s35
	s_and_b64 s[36:37], s[4:5], exec
	s_cselect_b32 s53, s35, s39
	s_cselect_b32 s52, s34, s38
	s_ashr_i32 s29, s28, 31
	s_lshl_b64 s[36:37], s[28:29], 17
	s_add_u32 s36, s2, s36
	s_addc_u32 s37, s3, s37
	s_and_b64 s[44:45], s[4:5], exec
	s_cselect_b32 s51, s37, s41
	s_cselect_b32 s50, s36, s40
	s_add_u32 s44, s38, 0x10080
	s_addc_u32 s45, s39, 0
	s_add_i32 s62, s9, 0xc000
	s_mov_b32 m0, s62
	s_add_i32 s29, s9, 0xe000
	ds_read_b128 v[32:35], v145
	ds_read_b128 v[36:39], v145 offset:1024
	ds_read_b128 v[40:43], v145 offset:2048
	ds_read_b128 v[44:47], v145 offset:3072
	ds_read_b128 v[48:51], v145 offset:4096
	ds_read_b128 v[52:55], v145 offset:5120
	ds_read_b128 v[56:59], v145 offset:6144
	ds_read_b128 v[60:63], v145 offset:7168
	global_load_lds_dwordx4 v128, s[44:45]
	s_mov_b32 m0, s29
	s_nop 0
	global_load_lds_dwordx4 v132, s[44:45]
	s_waitcnt vmcnt(8)
	s_waitcnt lgkmcnt(0)
	s_barrier
	v_mfma_f32_16x16x32_bf16 v[64:67], v[0:3], v[32:35], 0
	v_mfma_f32_16x16x32_bf16 v[68:71], v[8:11], v[32:35], 0
	v_mfma_f32_16x16x32_bf16 v[72:75], v[0:3], v[40:43], 0
	v_mfma_f32_16x16x32_bf16 v[76:79], v[8:11], v[40:43], 0
	v_mfma_f32_16x16x32_bf16 v[80:83], v[0:3], v[48:51], 0
	v_mfma_f32_16x16x32_bf16 v[84:87], v[8:11], v[48:51], 0
	v_mfma_f32_16x16x32_bf16 v[88:91], v[0:3], v[56:59], 0
	v_mfma_f32_16x16x32_bf16 v[92:95], v[8:11], v[56:59], 0
	v_mfma_f32_16x16x32_bf16 v[64:67], v[4:7], v[36:39], v[64:67]
	v_mfma_f32_16x16x32_bf16 v[68:71], v[12:15], v[36:39], v[68:71]
	v_mfma_f32_16x16x32_bf16 v[72:75], v[4:7], v[44:47], v[72:75]
	v_mfma_f32_16x16x32_bf16 v[76:79], v[12:15], v[44:47], v[76:79]
	v_mfma_f32_16x16x32_bf16 v[80:83], v[4:7], v[52:55], v[80:83]
	v_mfma_f32_16x16x32_bf16 v[84:87], v[12:15], v[52:55], v[84:87]
	v_mfma_f32_16x16x32_bf16 v[88:91], v[4:7], v[60:63], v[88:91]
	v_mfma_f32_16x16x32_bf16 v[92:95], v[12:15], v[60:63], v[92:95]
	v_mfma_f32_16x16x32_bf16 v[96:99], v[16:19], v[32:35], 0
	v_mfma_f32_16x16x32_bf16 v[32:35], v[24:27], v[32:35], 0
	v_mfma_f32_16x16x32_bf16 v[96:99], v[20:23], v[36:39], v[96:99]
	v_mfma_f32_16x16x32_bf16 v[32:35], v[28:31], v[36:39], v[32:35]
	v_mfma_f32_16x16x32_bf16 v[36:39], v[16:19], v[40:43], 0
	v_mfma_f32_16x16x32_bf16 v[40:43], v[24:27], v[40:43], 0
	v_mfma_f32_16x16x32_bf16 v[36:39], v[20:23], v[44:47], v[36:39]
	v_mfma_f32_16x16x32_bf16 v[40:43], v[28:31], v[44:47], v[40:43]
	v_mfma_f32_16x16x32_bf16 v[44:47], v[16:19], v[48:51], 0
	v_mfma_f32_16x16x32_bf16 v[48:51], v[24:27], v[48:51], 0
	v_mfma_f32_16x16x32_bf16 v[44:47], v[20:23], v[52:55], v[44:47]
	v_mfma_f32_16x16x32_bf16 v[48:51], v[28:31], v[52:55], v[48:51]
	v_mfma_f32_16x16x32_bf16 v[52:55], v[16:19], v[56:59], 0
	v_mfma_f32_16x16x32_bf16 v[56:59], v[24:27], v[56:59], 0
	v_mfma_f32_16x16x32_bf16 v[52:55], v[20:23], v[60:63], v[52:55]
	v_mfma_f32_16x16x32_bf16 v[56:59], v[28:31], v[60:63], v[56:59]
	s_barrier
	s_add_i32 s48, s59, s8
	v_lshl_add_u64 v[190:191], s[40:41], 0, v[130:131]
	s_add_i32 s31, s48, 0x2000
	v_lshl_add_u64 v[146:147], v[190:191], 0, s[22:23]
	s_mov_b32 m0, s48
	v_lshl_add_u64 v[192:193], s[40:41], 0, v[134:135]
	s_add_u32 s64, s40, 0x10100
	ds_read_b128 v[60:63], v145 offset:16384
	ds_read_b128 v[100:103], v145 offset:17408
	ds_read_b128 v[104:107], v145 offset:18432
	ds_read_b128 v[108:111], v145 offset:19456
	ds_read_b128 v[112:115], v145 offset:20480
	ds_read_b128 v[116:119], v145 offset:21504
	ds_read_b128 v[120:123], v145 offset:22528
	ds_read_b128 v[124:127], v145 offset:23552
	global_load_lds_dwordx4 v[146:147], off
	v_lshl_add_u64 v[146:147], v[192:193], 0, s[22:23]
	s_mov_b32 m0, s31
	s_addc_u32 s65, s41, 0
	s_add_i32 s44, s60, s8
	global_load_lds_dwordx4 v[146:147], off
	s_mov_b32 m0, s44
	s_add_i32 s45, s44, 0x2000
	global_load_lds_dwordx4 v130, s[64:65]
	s_mov_b32 m0, s45
	v_lshl_add_u64 v[194:195], s[38:39], 0, v[128:129]
	global_load_lds_dwordx4 v134, s[64:65]
	v_lshl_add_u64 v[146:147], v[194:195], 0, s[22:23]
	s_mov_b32 m0, s9
	v_lshl_add_u64 v[216:217], s[38:39], 0, v[132:133]
	global_load_lds_dwordx4 v[146:147], off
	v_lshl_add_u64 v[146:147], v[216:217], 0, s[22:23]
	s_mov_b32 m0, s10
	s_nop 0
	global_load_lds_dwordx4 v[146:147], off
	s_waitcnt vmcnt(8)
	s_waitcnt lgkmcnt(0)
	s_barrier
; #define PG8_STAGE(bufoff, gbase, voff) do { _Pragma("unroll") for (int _i = 0; _i < 2; ++_i) \
;         __builtin_amdgcn_global_load_lds((const unsigned*)((const char*)(gbase) + (voff)[_i]), (PG8_LAS unsigned*)(lds + (bufoff) + ldsw + _i * 8192), 16, 0, 0); } while (0)
; #define PG8_LDA(dst, b, h) do { _Pragma("unroll") for (int m = 0; m < 4; ++m) _Pragma("unroll") for (int k = 0; k < 2; ++k) dst[m][k] = *(const PG8_LAS bf16x8*)(lds + PG8_SA(b, h) + aoff + m * 2048 + k * 1024); } while (0)
; #define PG8_LDB(dst, b, h) do { _Pragma("unroll") for (int n = 0; n < 2; ++n) _Pragma("unroll") for (int k = 0; k < 2; ++k) dst[n][k] = *(const PG8_LAS bf16x8*)(lds + PG8_SB(b, h) + boff + n * 2048 + k * 1024); } while (0)
; #define PG8_MMA(ai, bj, At, Bt) do { __builtin_amdgcn_s_setprio(1); _Pragma("unroll") for (int m = 0; m < 4; ++m) _Pragma("unroll") for (int n = 0; n < 2; ++n) _Pragma("unroll") for (int k = 0; k < 2; ++k) \
;         acc[ai][bj][m][n] = __builtin_amdgcn_mfma_f32_16x16x32_bf16(Bt[n][k], At[m][k], acc[ai][bj][m][n], 0, 0, 0); __builtin_amdgcn_s_setprio(0); } while (0)
; #define PG8_WAIT_V(n) asm volatile("s_waitcnt vmcnt(" #n ")" ::: "memory")
; #define PG8_WAIT_L(n) asm volatile("s_waitcnt lgkmcnt(" #n ")" ::: "memory")
; #define PG8_BAR __builtin_amdgcn_s_barrier()
; #define PG8_SCHED __builtin_amdgcn_sched_barrier(0)
; template <class Epi, class Sched, bool ALIGN_EPI = false, bool SP2 = false>
; __device__ __forceinline__ void gemm_phase(PG8_LAS unsigned char* lds, const Gemm g, const Sched& S, const Epi& E) {
;     ...
;             PG8_WAIT_V(8); PG8_WAIT_L(0); PG8_BAR; PG8_MMA(1, 0, At, B0); PG8_MMA(1, 1, At, B1); PG8_BAR; PG8_SCHED;
;             PG8_LDB(B0, 1, 0); PG8_LDB(B1, 1, 1); PG8_SCHED; PG8_LDA(At, 1, 0); PG8_STAGE(PG8_SA(0, 1), a2 + hstepA, voffA);
;             PG8_WAIT_V(8); PG8_WAIT_L(0); PG8_BAR; PG8_MMA(0, 0, At, B0); PG8_MMA(0, 1, At, B1); PG8_BAR; PG8_SCHED;
	v_mfma_f32_16x16x32_bf16 v[146:149], v[0:3], v[60:63], 0
	v_mfma_f32_16x16x32_bf16 v[154:157], v[0:3], v[104:107], 0
	v_mfma_f32_16x16x32_bf16 v[162:165], v[0:3], v[112:115], 0
	v_mfma_f32_16x16x32_bf16 v[0:3], v[0:3], v[120:123], 0
	v_mfma_f32_16x16x32_bf16 v[146:149], v[4:7], v[100:103], v[146:149]
	v_mfma_f32_16x16x32_bf16 v[154:157], v[4:7], v[108:111], v[154:157]
	v_mfma_f32_16x16x32_bf16 v[162:165], v[4:7], v[116:119], v[162:165]
	v_mfma_f32_16x16x32_bf16 v[0:3], v[4:7], v[124:127], v[0:3]
	v_mfma_f32_16x16x32_bf16 v[4:7], v[8:11], v[120:123], 0
	v_mfma_f32_16x16x32_bf16 v[150:153], v[8:11], v[60:63], 0
	v_mfma_f32_16x16x32_bf16 v[158:161], v[8:11], v[104:107], 0
	v_mfma_f32_16x16x32_bf16 v[166:169], v[8:11], v[112:115], 0
	v_mfma_f32_16x16x32_bf16 v[4:7], v[12:15], v[124:127], v[4:7]
	v_mfma_f32_16x16x32_bf16 v[150:153], v[12:15], v[100:103], v[150:153]
	v_mfma_f32_16x16x32_bf16 v[158:161], v[12:15], v[108:111], v[158:161]
	v_mfma_f32_16x16x32_bf16 v[166:169], v[12:15], v[116:119], v[166:169]
	v_mfma_f32_16x16x32_bf16 v[8:11], v[16:19], v[60:63], 0
	v_mfma_f32_16x16x32_bf16 v[12:15], v[24:27], v[60:63], 0
	v_mfma_f32_16x16x32_bf16 v[8:11], v[20:23], v[100:103], v[8:11]
	v_mfma_f32_16x16x32_bf16 v[12:15], v[28:31], v[100:103], v[12:15]
	v_mfma_f32_16x16x32_bf16 v[60:63], v[16:19], v[104:107], 0
	v_mfma_f32_16x16x32_bf16 v[100:103], v[24:27], v[104:107], 0
	v_mfma_f32_16x16x32_bf16 v[104:107], v[16:19], v[112:115], 0
	v_mfma_f32_16x16x32_bf16 v[16:19], v[16:19], v[120:123], 0
	v_mfma_f32_16x16x32_bf16 v[60:63], v[20:23], v[108:111], v[60:63]
	v_mfma_f32_16x16x32_bf16 v[100:103], v[28:31], v[108:111], v[100:103]
	v_mfma_f32_16x16x32_bf16 v[104:107], v[20:23], v[116:119], v[104:107]
	v_mfma_f32_16x16x32_bf16 v[108:111], v[24:27], v[112:115], 0
	v_mfma_f32_16x16x32_bf16 v[16:19], v[20:23], v[124:127], v[16:19]
	v_mfma_f32_16x16x32_bf16 v[20:23], v[24:27], v[120:123], 0
	v_mfma_f32_16x16x32_bf16 v[108:111], v[28:31], v[116:119], v[108:111]
	v_mfma_f32_16x16x32_bf16 v[20:23], v[28:31], v[124:127], v[20:23]
	s_barrier
	s_add_i32 s63, 0, 0x18000
	s_add_i32 s66, 0, 0x1c000
	v_add_u32_e32 v220, s63, v142
	v_add_u32_e32 v228, s66, v142
	ds_read_b128 v[24:27], v220
	ds_read_b128 v[28:31], v220 offset:1024
	ds_read_b128 v[112:115], v220 offset:2048
	ds_read_b128 v[116:119], v220 offset:3072
	ds_read_b128 v[120:123], v228
	ds_read_b128 v[124:127], v228 offset:1024
	ds_read_b128 v[170:173], v228 offset:2048
	ds_read_b128 v[174:177], v228 offset:3072
	s_add_u32 s64, s38, 0x10100
	s_addc_u32 s65, s39, 0
	s_mov_b32 m0, s11
	ds_read_b128 v[178:181], v145 offset:32768
	ds_read_b128 v[182:185], v145 offset:33792
	ds_read_b128 v[186:189], v145 offset:34816
	ds_read_b128 v[196:199], v145 offset:35840
	ds_read_b128 v[200:203], v145 offset:36864
	ds_read_b128 v[204:207], v145 offset:37888
	ds_read_b128 v[208:211], v145 offset:38912
	ds_read_b128 v[212:215], v145 offset:39936
	global_load_lds_dwordx4 v128, s[64:65]
	s_mov_b32 m0, s27
	s_nop 0
	global_load_lds_dwordx4 v132, s[64:65]
	s_waitcnt vmcnt(8)
	s_waitcnt lgkmcnt(0)
	s_barrier
	v_mfma_f32_16x16x32_bf16 v[64:67], v[24:27], v[178:181], v[64:67]
	v_mfma_f32_16x16x32_bf16 v[68:71], v[112:115], v[178:181], v[68:71]
	v_mfma_f32_16x16x32_bf16 v[72:75], v[24:27], v[186:189], v[72:75]
	v_mfma_f32_16x16x32_bf16 v[76:79], v[112:115], v[186:189], v[76:79]
	v_mfma_f32_16x16x32_bf16 v[80:83], v[24:27], v[200:203], v[80:83]
	v_mfma_f32_16x16x32_bf16 v[84:87], v[112:115], v[200:203], v[84:87]
	v_mfma_f32_16x16x32_bf16 v[88:91], v[24:27], v[208:211], v[88:91]
	v_mfma_f32_16x16x32_bf16 v[92:95], v[112:115], v[208:211], v[92:95]
	v_mfma_f32_16x16x32_bf16 v[64:67], v[28:31], v[182:185], v[64:67]
	v_mfma_f32_16x16x32_bf16 v[68:71], v[116:119], v[182:185], v[68:71]
	v_mfma_f32_16x16x32_bf16 v[72:75], v[28:31], v[196:199], v[72:75]
	v_mfma_f32_16x16x32_bf16 v[76:79], v[116:119], v[196:199], v[76:79]
	v_mfma_f32_16x16x32_bf16 v[80:83], v[28:31], v[204:207], v[80:83]
	v_mfma_f32_16x16x32_bf16 v[84:87], v[116:119], v[204:207], v[84:87]
	v_mfma_f32_16x16x32_bf16 v[88:91], v[28:31], v[212:215], v[88:91]
	v_mfma_f32_16x16x32_bf16 v[92:95], v[116:119], v[212:215], v[92:95]
	v_mfma_f32_16x16x32_bf16 v[96:99], v[120:123], v[178:181], v[96:99]
	v_mfma_f32_16x16x32_bf16 v[32:35], v[170:173], v[178:181], v[32:35]
	v_mfma_f32_16x16x32_bf16 v[36:39], v[120:123], v[186:189], v[36:39]
	v_mfma_f32_16x16x32_bf16 v[40:43], v[170:173], v[186:189], v[40:43]
	v_mfma_f32_16x16x32_bf16 v[44:47], v[120:123], v[200:203], v[44:47]
	v_mfma_f32_16x16x32_bf16 v[48:51], v[170:173], v[200:203], v[48:51]
	v_mfma_f32_16x16x32_bf16 v[52:55], v[120:123], v[208:211], v[52:55]
	v_mfma_f32_16x16x32_bf16 v[56:59], v[170:173], v[208:211], v[56:59]
	v_mfma_f32_16x16x32_bf16 v[96:99], v[124:127], v[182:185], v[96:99]
	v_mfma_f32_16x16x32_bf16 v[32:35], v[174:177], v[182:185], v[32:35]
	v_mfma_f32_16x16x32_bf16 v[36:39], v[124:127], v[196:199], v[36:39]
	v_mfma_f32_16x16x32_bf16 v[40:43], v[174:177], v[196:199], v[40:43]
	v_mfma_f32_16x16x32_bf16 v[44:47], v[124:127], v[204:207], v[44:47]
	v_mfma_f32_16x16x32_bf16 v[48:51], v[174:177], v[204:207], v[48:51]
	v_mfma_f32_16x16x32_bf16 v[52:55], v[124:127], v[212:215], v[52:55]
	v_mfma_f32_16x16x32_bf16 v[56:59], v[174:177], v[212:215], v[56:59]
	s_barrier
; #define PG8_STAGE(bufoff, gbase, voff) do { _Pragma("unroll") for (int _i = 0; _i < 2; ++_i) \
;         __builtin_amdgcn_global_load_lds((const unsigned*)((const char*)(gbase) + (voff)[_i]), (PG8_LAS unsigned*)(lds + (bufoff) + ldsw + _i * 8192), 16, 0, 0); } while (0)
; #define PG8_LDA(dst, b, h) do { _Pragma("unroll") for (int m = 0; m < 4; ++m) _Pragma("unroll") for (int k = 0; k < 2; ++k) dst[m][k] = *(const PG8_LAS bf16x8*)(lds + PG8_SA(b, h) + aoff + m * 2048 + k * 1024); } while (0)
; #define PG8_LDB(dst, b, h) do { _Pragma("unroll") for (int n = 0; n < 2; ++n) _Pragma("unroll") for (int k = 0; k < 2; ++k) dst[n][k] = *(const PG8_LAS bf16x8*)(lds + PG8_SB(b, h) + boff + n * 2048 + k * 1024); } while (0)
; #define PG8_MMA(ai, bj, At, Bt) do { __builtin_amdgcn_s_setprio(1); _Pragma("unroll") for (int m = 0; m < 4; ++m) _Pragma("unroll") for (int n = 0; n < 2; ++n) _Pragma("unroll") for (int k = 0; k < 2; ++k) \
;         acc[ai][bj][m][n] = __builtin_amdgcn_mfma_f32_16x16x32_bf16(Bt[n][k], At[m][k], acc[ai][bj][m][n], 0, 0, 0); __builtin_amdgcn_s_setprio(0); } while (0)
; #define PG8_WAIT_V(n) asm volatile("s_waitcnt vmcnt(" #n ")" ::: "memory")
; template <class Epi, class Sched, bool ALIGN_EPI = false, bool SP2 = false>
; __device__ __forceinline__ void gemm_phase(PG8_LAS unsigned char* lds, const Gemm g, const Sched& S, const Epi& E) {
;     ...
;             PG8_LDB(B0, 0, 0); PG8_LDB(B1, 0, 1); PG8_SCHED; PG8_LDA(At, 0, 0); PG8_STAGE(PG8_SA(1, 1), a1 + hstepA, voffA);
;             PG8_WAIT_V(8); PG8_WAIT_L(0); PG8_BAR; PG8_MMA(0, 0, At, B0); PG8_MMA(0, 1, At, B1); PG8_BAR; PG8_SCHED;
;             PG8_LDA(At, 0, 1); PG8_STAGE(PG8_SB(0, 0), b2, voffB); PG8_STAGE(PG8_SB(0, 1), b2 + hstepB, voffB); PG8_STAGE(PG8_SA(0, 0), a2, voffA);
;             PG8_WAIT_V(8); PG8_WAIT_L(0); PG8_BAR; PG8_MMA(1, 0, At, B0); PG8_MMA(1, 1, At, B1); PG8_BAR; PG8_SCHED;
;             PG8_LDB(B0, 1, 0); PG8_LDB(B1, 1, 1); PG8_SCHED; PG8_LDA(At, 1, 0); PG8_STAGE(PG8_SA(0, 1), a2 + hstepA, voffA);
;             PG8_WAIT_V(8); PG8_WAIT_L(0); PG8_BAR; PG8_MMA(0, 0, At, B0); PG8_MMA(0, 1, At, B1); PG8_BAR; PG8_SCHED;
;             PG8_LDA(At, 1, 1); PG8_STAGE(PG8_SB(1, 0), b3, voffB); PG8_STAGE(PG8_SB(1, 1), b3 + hstepB, voffB); PG8_STAGE(PG8_SA(1, 0), a3, voffA);
;             PG8_WAIT_V(8); PG8_WAIT_L(0); PG8_BAR; PG8_MMA(1, 0, At, B0); PG8_MMA(1, 1, At, B1); PG8_BAR; PG8_SCHED;
	s_add_i32 s63, s63, s8
	s_add_i32 s49, s63, 0x2000
	v_lshl_add_u64 v[190:191], v[190:191], 0, s[24:25]
	s_mov_b32 m0, s63
	s_add_u32 s64, s40, 0x10180
	ds_read_b128 v[178:181], v145 offset:49152
	ds_read_b128 v[182:185], v145 offset:50176
	ds_read_b128 v[186:189], v145 offset:51200
	ds_read_b128 v[196:199], v145 offset:52224
	ds_read_b128 v[200:203], v145 offset:53248
	ds_read_b128 v[204:207], v145 offset:54272
	ds_read_b128 v[208:211], v145 offset:55296
	ds_read_b128 v[212:215], v145 offset:56320
	global_load_lds_dwordx4 v[190:191], off
	v_lshl_add_u64 v[190:191], v[192:193], 0, s[24:25]
	s_mov_b32 m0, s49
	s_addc_u32 s65, s41, 0
	s_add_i32 s40, s66, s8
	global_load_lds_dwordx4 v[190:191], off
	s_mov_b32 m0, s40
	s_add_i32 s41, s40, 0x2000
	global_load_lds_dwordx4 v130, s[64:65]
	s_mov_b32 m0, s41
	s_nop 0
	global_load_lds_dwordx4 v134, s[64:65]
	v_lshl_add_u64 v[190:191], v[194:195], 0, s[24:25]
	s_mov_b32 m0, s43
	s_nop 0
	global_load_lds_dwordx4 v[190:191], off
	v_lshl_add_u64 v[190:191], v[216:217], 0, s[24:25]
	s_mov_b32 m0, s56
	s_nop 0
	global_load_lds_dwordx4 v[190:191], off
	s_waitcnt vmcnt(8)
	s_waitcnt lgkmcnt(0)
	s_barrier
	v_mfma_f32_16x16x32_bf16 v[0:3], v[24:27], v[208:211], v[0:3]
	v_mfma_f32_16x16x32_bf16 v[4:7], v[112:115], v[208:211], v[4:7]
	v_mfma_f32_16x16x32_bf16 v[146:149], v[24:27], v[178:181], v[146:149]
	v_mfma_f32_16x16x32_bf16 v[150:153], v[112:115], v[178:181], v[150:153]
	v_mfma_f32_16x16x32_bf16 v[154:157], v[24:27], v[186:189], v[154:157]
	v_mfma_f32_16x16x32_bf16 v[158:161], v[112:115], v[186:189], v[158:161]
	v_mfma_f32_16x16x32_bf16 v[162:165], v[24:27], v[200:203], v[162:165]
	v_mfma_f32_16x16x32_bf16 v[166:169], v[112:115], v[200:203], v[166:169]
	v_mfma_f32_16x16x32_bf16 v[0:3], v[28:31], v[212:215], v[0:3]
	v_mfma_f32_16x16x32_bf16 v[4:7], v[116:119], v[212:215], v[4:7]
	v_mfma_f32_16x16x32_bf16 v[146:149], v[28:31], v[182:185], v[146:149]
	v_mfma_f32_16x16x32_bf16 v[150:153], v[116:119], v[182:185], v[150:153]
	v_mfma_f32_16x16x32_bf16 v[154:157], v[28:31], v[196:199], v[154:157]
	v_mfma_f32_16x16x32_bf16 v[158:161], v[116:119], v[196:199], v[158:161]
	v_mfma_f32_16x16x32_bf16 v[162:165], v[28:31], v[204:207], v[162:165]
	v_mfma_f32_16x16x32_bf16 v[166:169], v[116:119], v[204:207], v[166:169]
	v_mfma_f32_16x16x32_bf16 v[8:11], v[120:123], v[178:181], v[8:11]
	v_mfma_f32_16x16x32_bf16 v[12:15], v[170:173], v[178:181], v[12:15]
	v_mfma_f32_16x16x32_bf16 v[24:27], v[120:123], v[186:189], v[60:63]
	v_mfma_f32_16x16x32_bf16 v[28:31], v[170:173], v[186:189], v[100:103]
	v_mfma_f32_16x16x32_bf16 v[60:63], v[120:123], v[200:203], v[104:107]
	v_mfma_f32_16x16x32_bf16 v[100:103], v[170:173], v[200:203], v[108:111]
	v_mfma_f32_16x16x32_bf16 v[16:19], v[120:123], v[208:211], v[16:19]
	v_mfma_f32_16x16x32_bf16 v[20:23], v[170:173], v[208:211], v[20:23]
	v_mfma_f32_16x16x32_bf16 v[8:11], v[124:127], v[182:185], v[8:11]
	v_mfma_f32_16x16x32_bf16 v[12:15], v[174:177], v[182:185], v[12:15]
	v_mfma_f32_16x16x32_bf16 v[24:27], v[124:127], v[196:199], v[24:27]
	v_mfma_f32_16x16x32_bf16 v[28:31], v[174:177], v[196:199], v[28:31]
	v_mfma_f32_16x16x32_bf16 v[60:63], v[124:127], v[204:207], v[60:63]
	v_mfma_f32_16x16x32_bf16 v[100:103], v[174:177], v[204:207], v[100:103]
	v_mfma_f32_16x16x32_bf16 v[16:19], v[124:127], v[212:215], v[16:19]
	v_mfma_f32_16x16x32_bf16 v[20:23], v[174:177], v[212:215], v[20:23]
	s_barrier
	ds_read_b128 v[104:107], v143
	ds_read_b128 v[108:111], v143 offset:1024
	ds_read_b128 v[112:115], v143 offset:2048
	ds_read_b128 v[116:119], v143 offset:3072
	ds_read_b128 v[120:123], v144
	ds_read_b128 v[124:127], v144 offset:1024
	ds_read_b128 v[170:173], v144 offset:2048
	ds_read_b128 v[174:177], v144 offset:3072
	s_add_u32 s38, s38, 0x10180
	s_addc_u32 s39, s39, 0
	s_mov_b32 m0, s62
	ds_read_b128 v[178:181], v145
	ds_read_b128 v[182:185], v145 offset:1024
	ds_read_b128 v[186:189], v145 offset:2048
	ds_read_b128 v[196:199], v145 offset:3072
	ds_read_b128 v[200:203], v145 offset:4096
	ds_read_b128 v[204:207], v145 offset:5120
	ds_read_b128 v[208:211], v145 offset:6144
	ds_read_b128 v[212:215], v145 offset:7168
	global_load_lds_dwordx4 v128, s[38:39]
	s_mov_b32 m0, s29
	s_nop 0
	global_load_lds_dwordx4 v132, s[38:39]
	s_waitcnt vmcnt(8)
	s_waitcnt lgkmcnt(0)
	s_barrier
	v_mfma_f32_16x16x32_bf16 v[64:67], v[104:107], v[178:181], v[64:67]
	v_mfma_f32_16x16x32_bf16 v[68:71], v[112:115], v[178:181], v[68:71]
	v_mfma_f32_16x16x32_bf16 v[72:75], v[104:107], v[186:189], v[72:75]
	v_mfma_f32_16x16x32_bf16 v[76:79], v[112:115], v[186:189], v[76:79]
	v_mfma_f32_16x16x32_bf16 v[80:83], v[104:107], v[200:203], v[80:83]
	v_mfma_f32_16x16x32_bf16 v[84:87], v[112:115], v[200:203], v[84:87]
	v_mfma_f32_16x16x32_bf16 v[88:91], v[104:107], v[208:211], v[88:91]
	v_mfma_f32_16x16x32_bf16 v[92:95], v[112:115], v[208:211], v[92:95]
	v_mfma_f32_16x16x32_bf16 v[64:67], v[108:111], v[182:185], v[64:67]
	v_mfma_f32_16x16x32_bf16 v[68:71], v[116:119], v[182:185], v[68:71]
	v_mfma_f32_16x16x32_bf16 v[72:75], v[108:111], v[196:199], v[72:75]
	v_mfma_f32_16x16x32_bf16 v[76:79], v[116:119], v[196:199], v[76:79]
	v_mfma_f32_16x16x32_bf16 v[80:83], v[108:111], v[204:207], v[80:83]
	v_mfma_f32_16x16x32_bf16 v[84:87], v[116:119], v[204:207], v[84:87]
	v_mfma_f32_16x16x32_bf16 v[88:91], v[108:111], v[212:215], v[88:91]
	v_mfma_f32_16x16x32_bf16 v[92:95], v[116:119], v[212:215], v[92:95]
	v_mfma_f32_16x16x32_bf16 v[32:35], v[170:173], v[178:181], v[32:35]
	v_mfma_f32_16x16x32_bf16 v[96:99], v[120:123], v[178:181], v[96:99]
	v_mfma_f32_16x16x32_bf16 v[178:181], v[174:177], v[182:185], v[32:35]
	v_mfma_f32_16x16x32_bf16 v[32:35], v[120:123], v[186:189], v[36:39]
	v_mfma_f32_16x16x32_bf16 v[216:219], v[124:127], v[182:185], v[96:99]
	v_mfma_f32_16x16x32_bf16 v[182:185], v[124:127], v[196:199], v[32:35]
	v_mfma_f32_16x16x32_bf16 v[32:35], v[170:173], v[186:189], v[40:43]
	v_mfma_f32_16x16x32_bf16 v[40:43], v[174:177], v[196:199], v[32:35]
	v_mfma_f32_16x16x32_bf16 v[32:35], v[120:123], v[200:203], v[44:47]
	v_mfma_f32_16x16x32_bf16 v[44:47], v[124:127], v[204:207], v[32:35]
	v_mfma_f32_16x16x32_bf16 v[32:35], v[170:173], v[200:203], v[48:51]
	v_mfma_f32_16x16x32_bf16 v[48:51], v[174:177], v[204:207], v[32:35]
	v_mfma_f32_16x16x32_bf16 v[32:35], v[120:123], v[208:211], v[52:55]
	v_mfma_f32_16x16x32_bf16 v[52:55], v[124:127], v[212:215], v[32:35]
	v_mfma_f32_16x16x32_bf16 v[32:35], v[170:173], v[208:211], v[56:59]
	v_mfma_f32_16x16x32_bf16 v[56:59], v[174:177], v[212:215], v[32:35]
	s_barrier
; #define PG8_STAGE(bufoff, gbase, voff) do { _Pragma("unroll") for (int _i = 0; _i < 2; ++_i) \
;         __builtin_amdgcn_global_load_lds((const unsigned*)((const char*)(gbase) + (voff)[_i]), (PG8_LAS unsigned*)(lds + (bufoff) + ldsw + _i * 8192), 16, 0, 0); } while (0)
; #define PG8_LDA(dst, b, h) do { _Pragma("unroll") for (int m = 0; m < 4; ++m) _Pragma("unroll") for (int k = 0; k < 2; ++k) dst[m][k] = *(const PG8_LAS bf16x8*)(lds + PG8_SA(b, h) + aoff + m * 2048 + k * 1024); } while (0)
; #define PG8_LDB(dst, b, h) do { _Pragma("unroll") for (int n = 0; n < 2; ++n) _Pragma("unroll") for (int k = 0; k < 2; ++k) dst[n][k] = *(const PG8_LAS bf16x8*)(lds + PG8_SB(b, h) + boff + n * 2048 + k * 1024); } while (0)
; #define PG8_MMA(ai, bj, At, Bt) do { __builtin_amdgcn_s_setprio(1); _Pragma("unroll") for (int m = 0; m < 4; ++m) _Pragma("unroll") for (int n = 0; n < 2; ++n) _Pragma("unroll") for (int k = 0; k < 2; ++k) \
;         acc[ai][bj][m][n] = __builtin_amdgcn_mfma_f32_16x16x32_bf16(Bt[n][k], At[m][k], acc[ai][bj][m][n], 0, 0, 0); __builtin_amdgcn_s_setprio(0); } while (0)
; #define PG8_WAIT_V(n) asm volatile("s_waitcnt vmcnt(" #n ")" ::: "memory")
; #define PG8_WAIT_L(n) asm volatile("s_waitcnt lgkmcnt(" #n ")" ::: "memory")
; #define PG8_BAR __builtin_amdgcn_s_barrier()
; #define PG8_SCHED __builtin_amdgcn_sched_barrier(0)
; template <class Epi, class Sched, bool ALIGN_EPI = false, bool SP2 = false>
; __device__ __forceinline__ void gemm_phase(PG8_LAS unsigned char* lds, const Gemm g, const Sched& S, const Epi& E) {
;     ...
;             PG8_LDA(At, 0, 1); PG8_STAGE(PG8_SB(0, 0), b2, voffB); PG8_STAGE(PG8_SB(0, 1), b2 + hstepB, voffB); PG8_STAGE(PG8_SA(0, 0), a2, voffA);
;             PG8_WAIT_V(8); PG8_WAIT_L(0); PG8_BAR; PG8_MMA(1, 0, At, B0); PG8_MMA(1, 1, At, B1); PG8_BAR; PG8_SCHED;
;             PG8_LDB(B0, 1, 0); PG8_LDB(B1, 1, 1); PG8_SCHED; PG8_LDA(At, 1, 0); PG8_STAGE(PG8_SA(0, 1), a2 + hstepA, voffA);
;             PG8_WAIT_V(8); PG8_WAIT_L(0); PG8_BAR; PG8_MMA(0, 0, At, B0); PG8_MMA(0, 1, At, B1); PG8_BAR; PG8_SCHED;
	s_mov_b32 m0, s48
	s_add_u32 s98, s50, s16
	s_addc_u32 s99, s51, s17
	s_add_u32 s38, s50, 0x10000
	s_nop 1
	ds_read_b128 v[32:35], v145 offset:16384
	ds_read_b128 v[36:39], v145 offset:17408
	ds_read_b128 v[96:99], v145 offset:18432
	ds_read_b128 v[186:189], v145 offset:19456
	ds_read_b128 v[196:199], v145 offset:20480
	ds_read_b128 v[200:203], v145 offset:21504
	ds_read_b128 v[204:207], v145 offset:22528
	ds_read_b128 v[208:211], v145 offset:23552
	global_load_lds_dwordx4 v130, s[50:51]
	s_mov_b32 m0, s31
	s_addc_u32 s39, s51, 0
	global_load_lds_dwordx4 v134, s[50:51]
	s_mov_b32 m0, s44
	global_load_lds_dwordx4 v130, s[38:39]
	s_mov_b32 m0, s45
	s_nop 0
	global_load_lds_dwordx4 v134, s[38:39]
	s_mov_b32 m0, s9
	s_nop 0
	s_add_u32 s100, s52, s16
	s_addc_u32 s101, s53, s17
	global_load_lds_dwordx4 v128, s[52:53]
	s_mov_b32 m0, s10
	s_nop 0
	global_load_lds_dwordx4 v132, s[52:53]
	s_waitcnt vmcnt(8)
	s_waitcnt lgkmcnt(0)
	s_barrier
	v_mfma_f32_16x16x32_bf16 v[0:3], v[104:107], v[204:207], v[0:3]
	v_mfma_f32_16x16x32_bf16 v[4:7], v[112:115], v[204:207], v[4:7]
	v_mfma_f32_16x16x32_bf16 v[146:149], v[104:107], v[32:35], v[146:149]
	v_mfma_f32_16x16x32_bf16 v[150:153], v[112:115], v[32:35], v[150:153]
	v_mfma_f32_16x16x32_bf16 v[154:157], v[104:107], v[96:99], v[154:157]
	v_mfma_f32_16x16x32_bf16 v[158:161], v[112:115], v[96:99], v[158:161]
	v_mfma_f32_16x16x32_bf16 v[162:165], v[104:107], v[196:199], v[162:165]
	v_mfma_f32_16x16x32_bf16 v[166:169], v[112:115], v[196:199], v[166:169]
	v_mfma_f32_16x16x32_bf16 v[0:3], v[108:111], v[208:211], v[0:3]
	v_mfma_f32_16x16x32_bf16 v[4:7], v[116:119], v[208:211], v[4:7]
	v_mfma_f32_16x16x32_bf16 v[146:149], v[108:111], v[36:39], v[146:149]
	v_mfma_f32_16x16x32_bf16 v[150:153], v[116:119], v[36:39], v[150:153]
	v_mfma_f32_16x16x32_bf16 v[154:157], v[108:111], v[186:189], v[154:157]
	v_mfma_f32_16x16x32_bf16 v[158:161], v[116:119], v[186:189], v[158:161]
	v_mfma_f32_16x16x32_bf16 v[162:165], v[108:111], v[200:203], v[162:165]
	v_mfma_f32_16x16x32_bf16 v[166:169], v[116:119], v[200:203], v[166:169]
	v_mfma_f32_16x16x32_bf16 v[8:11], v[120:123], v[32:35], v[8:11]
	v_mfma_f32_16x16x32_bf16 v[12:15], v[170:173], v[32:35], v[12:15]
	v_mfma_f32_16x16x32_bf16 v[24:27], v[120:123], v[96:99], v[24:27]
	v_mfma_f32_16x16x32_bf16 v[28:31], v[170:173], v[96:99], v[28:31]
	v_mfma_f32_16x16x32_bf16 v[32:35], v[120:123], v[196:199], v[60:63]
	v_mfma_f32_16x16x32_bf16 v[24:27], v[124:127], v[186:189], v[24:27]
	v_mfma_f32_16x16x32_bf16 v[28:31], v[174:177], v[186:189], v[28:31]
	v_mfma_f32_16x16x32_bf16 v[186:189], v[124:127], v[200:203], v[32:35]
	v_mfma_f32_16x16x32_bf16 v[32:35], v[170:173], v[196:199], v[100:103]
	v_mfma_f32_16x16x32_bf16 v[16:19], v[120:123], v[204:207], v[16:19]
	v_mfma_f32_16x16x32_bf16 v[8:11], v[124:127], v[36:39], v[8:11]
	v_mfma_f32_16x16x32_bf16 v[12:15], v[174:177], v[36:39], v[12:15]
	v_mfma_f32_16x16x32_bf16 v[196:199], v[174:177], v[200:203], v[32:35]
	v_mfma_f32_16x16x32_bf16 v[200:203], v[124:127], v[208:211], v[16:19]
	v_mfma_f32_16x16x32_bf16 v[16:19], v[170:173], v[204:207], v[20:23]
	v_mfma_f32_16x16x32_bf16 v[170:173], v[174:177], v[208:211], v[16:19]
	s_barrier
	ds_read_b128 v[60:63], v220
	ds_read_b128 v[174:177], v220 offset:1024
	ds_read_b128 v[204:207], v220 offset:2048
	ds_read_b128 v[208:211], v220 offset:3072
	ds_read_b128 v[212:215], v228
	ds_read_b128 v[220:223], v228 offset:1024
	ds_read_b128 v[224:227], v228 offset:2048
	ds_read_b128 v[228:231], v228 offset:3072
	s_add_u32 s38, s52, 0x10000
	s_addc_u32 s39, s53, 0
	s_mov_b32 m0, s11
	ds_read_b128 v[16:19], v145 offset:32768
	ds_read_b128 v[20:23], v145 offset:33792
	ds_read_b128 v[108:111], v145 offset:34816
	ds_read_b128 v[232:235], v145 offset:35840
	ds_read_b128 v[236:239], v145 offset:36864
	ds_read_b128 v[240:243], v145 offset:37888
	ds_read_b128 v[244:247], v145 offset:38912
	ds_read_b128 v[248:251], v145 offset:39936
	global_load_lds_dwordx4 v128, s[38:39]
	s_mov_b32 m0, s27
	s_nop 0
	global_load_lds_dwordx4 v132, s[38:39]
	s_waitcnt vmcnt(8)
	s_waitcnt lgkmcnt(0)
	s_barrier
; #define PG8_STAGE(bufoff, gbase, voff) do { _Pragma("unroll") for (int _i = 0; _i < 2; ++_i) \
;         __builtin_amdgcn_global_load_lds((const unsigned*)((const char*)(gbase) + (voff)[_i]), (PG8_LAS unsigned*)(lds + (bufoff) + ldsw + _i * 8192), 16, 0, 0); } while (0)
; #define PG8_LDA(dst, b, h) do { _Pragma("unroll") for (int m = 0; m < 4; ++m) _Pragma("unroll") for (int k = 0; k < 2; ++k) dst[m][k] = *(const PG8_LAS bf16x8*)(lds + PG8_SA(b, h) + aoff + m * 2048 + k * 1024); } while (0)
; #define PG8_MMA(ai, bj, At, Bt) do { __builtin_amdgcn_s_setprio(1); _Pragma("unroll") for (int m = 0; m < 4; ++m) _Pragma("unroll") for (int n = 0; n < 2; ++n) _Pragma("unroll") for (int k = 0; k < 2; ++k) \
;         acc[ai][bj][m][n] = __builtin_amdgcn_mfma_f32_16x16x32_bf16(Bt[n][k], At[m][k], acc[ai][bj][m][n], 0, 0, 0); __builtin_amdgcn_s_setprio(0); } while (0)
; #define PG8_WAIT_V(n) asm volatile("s_waitcnt vmcnt(" #n ")" ::: "memory")
; #define PG8_WAIT_L(n) asm volatile("s_waitcnt lgkmcnt(" #n ")" ::: "memory")
; #define PG8_BAR __builtin_amdgcn_s_barrier()
; #define PG8_SCHED __builtin_amdgcn_sched_barrier(0)
; template <class Epi, class Sched, bool ALIGN_EPI = false, bool SP2 = false>
; __device__ __forceinline__ void gemm_phase(PG8_LAS unsigned char* lds, const Gemm g, const Sched& S, const Epi& E) {
;     ...
;             PG8_WAIT_V(8); PG8_WAIT_L(0); PG8_BAR; PG8_MMA(0, 0, At, B0); PG8_MMA(0, 1, At, B1); PG8_BAR; PG8_SCHED;
;             PG8_LDA(At, 1, 1); PG8_STAGE(PG8_SB(1, 0), b3, voffB); PG8_STAGE(PG8_SB(1, 1), b3 + hstepB, voffB); PG8_STAGE(PG8_SA(1, 0), a3, voffA);
;             PG8_WAIT_V(8); PG8_WAIT_L(0); PG8_BAR; PG8_MMA(1, 0, At, B0); PG8_MMA(1, 1, At, B1); PG8_BAR; PG8_SCHED;
;     ...
;         if constexpr (ALIGN_EPI) { if (wr == 0) PG8_BAR; }
	v_mfma_f32_16x16x32_bf16 v[32:35], v[60:63], v[16:19], v[64:67]
	v_mfma_f32_16x16x32_bf16 v[112:115], v[174:177], v[20:23], v[32:35]
	v_mfma_f32_16x16x32_bf16 v[32:35], v[204:207], v[16:19], v[68:71]
	v_mfma_f32_16x16x32_bf16 v[116:119], v[208:211], v[20:23], v[32:35]
	v_mfma_f32_16x16x32_bf16 v[32:35], v[60:63], v[108:111], v[72:75]
	v_mfma_f32_16x16x32_bf16 v[96:99], v[174:177], v[232:235], v[32:35]
	v_mfma_f32_16x16x32_bf16 v[32:35], v[204:207], v[108:111], v[76:79]
	v_mfma_f32_16x16x32_bf16 v[100:103], v[208:211], v[232:235], v[32:35]
	v_mfma_f32_16x16x32_bf16 v[32:35], v[60:63], v[236:239], v[80:83]
	v_mfma_f32_16x16x32_bf16 v[64:67], v[174:177], v[240:243], v[32:35]
	v_mfma_f32_16x16x32_bf16 v[32:35], v[204:207], v[236:239], v[84:87]
	v_mfma_f32_16x16x32_bf16 v[68:71], v[208:211], v[240:243], v[32:35]
	v_mfma_f32_16x16x32_bf16 v[32:35], v[60:63], v[244:247], v[88:91]
	v_mfma_f32_16x16x32_bf16 v[36:39], v[204:207], v[244:247], v[92:95]
	v_mfma_f32_16x16x32_bf16 v[32:35], v[174:177], v[248:251], v[32:35]
	v_mfma_f32_16x16x32_bf16 v[36:39], v[208:211], v[248:251], v[36:39]
	v_mfma_f32_16x16x32_bf16 v[72:75], v[212:215], v[16:19], v[216:219]
	v_mfma_f32_16x16x32_bf16 v[16:19], v[224:227], v[16:19], v[178:181]
	v_mfma_f32_16x16x32_bf16 v[124:127], v[228:231], v[20:23], v[16:19]
	v_mfma_f32_16x16x32_bf16 v[16:19], v[212:215], v[108:111], v[182:185]
	v_mfma_f32_16x16x32_bf16 v[104:107], v[220:223], v[232:235], v[16:19]
	v_mfma_f32_16x16x32_bf16 v[16:19], v[224:227], v[108:111], v[40:43]
	v_mfma_f32_16x16x32_bf16 v[108:111], v[228:231], v[232:235], v[16:19]
	v_mfma_f32_16x16x32_bf16 v[16:19], v[212:215], v[236:239], v[44:47]
	v_mfma_f32_16x16x32_bf16 v[120:123], v[220:223], v[20:23], v[72:75]
	v_mfma_f32_16x16x32_bf16 v[72:75], v[220:223], v[240:243], v[16:19]
	v_mfma_f32_16x16x32_bf16 v[16:19], v[224:227], v[236:239], v[48:51]
	v_mfma_f32_16x16x32_bf16 v[76:79], v[228:231], v[240:243], v[16:19]
	v_mfma_f32_16x16x32_bf16 v[16:19], v[212:215], v[244:247], v[52:55]
	v_mfma_f32_16x16x32_bf16 v[40:43], v[220:223], v[248:251], v[16:19]
	v_mfma_f32_16x16x32_bf16 v[16:19], v[224:227], v[244:247], v[56:59]
	v_mfma_f32_16x16x32_bf16 v[44:47], v[228:231], v[248:251], v[16:19]
	s_barrier
	s_mov_b32 m0, s63
	s_nop 3
	s_add_u32 s38, s50, 0x10080
	ds_read_b128 v[56:59], v145 offset:49152
	ds_read_b128 v[92:95], v145 offset:50176
	ds_read_b128 v[178:181], v145 offset:51200
	ds_read_b128 v[182:185], v145 offset:52224
	ds_read_b128 v[216:219], v145 offset:53248
	ds_read_b128 v[232:235], v145 offset:54272
	ds_read_b128 v[236:239], v145 offset:55296
	ds_read_b128 v[240:243], v145 offset:56320
	global_load_lds_dwordx4 v130, s[98:99]
	s_mov_b32 m0, s49
	s_addc_u32 s39, s51, 0
	global_load_lds_dwordx4 v134, s[98:99]
	s_mov_b32 m0, s40
	s_nop 0
	global_load_lds_dwordx4 v130, s[38:39]
	s_mov_b32 m0, s41
	s_nop 0
	global_load_lds_dwordx4 v134, s[38:39]
	s_mov_b32 m0, s43
	s_nop 0
	global_load_lds_dwordx4 v128, s[100:101]
	s_mov_b32 m0, s56
	s_nop 0
	global_load_lds_dwordx4 v132, s[100:101]
	s_waitcnt vmcnt(8)
	s_waitcnt lgkmcnt(0)
	s_barrier
	v_mfma_f32_16x16x32_bf16 v[16:19], v[60:63], v[56:59], v[146:149]
	v_mfma_f32_16x16x32_bf16 v[80:83], v[174:177], v[92:95], v[16:19]
	v_mfma_f32_16x16x32_bf16 v[16:19], v[204:207], v[56:59], v[150:153]
	v_mfma_f32_16x16x32_bf16 v[84:87], v[208:211], v[92:95], v[16:19]
	v_mfma_f32_16x16x32_bf16 v[16:19], v[60:63], v[178:181], v[154:157]
	v_mfma_f32_16x16x32_bf16 v[48:51], v[174:177], v[182:185], v[16:19]
	v_mfma_f32_16x16x32_bf16 v[16:19], v[204:207], v[178:181], v[158:161]
	v_mfma_f32_16x16x32_bf16 v[52:55], v[208:211], v[182:185], v[16:19]
	v_mfma_f32_16x16x32_bf16 v[16:19], v[60:63], v[216:219], v[162:165]
	v_mfma_f32_16x16x32_bf16 v[20:23], v[204:207], v[216:219], v[166:169]
	v_mfma_f32_16x16x32_bf16 v[0:3], v[60:63], v[236:239], v[0:3]
	v_mfma_f32_16x16x32_bf16 v[4:7], v[204:207], v[236:239], v[4:7]
	v_mfma_f32_16x16x32_bf16 v[16:19], v[174:177], v[232:235], v[16:19]
	v_mfma_f32_16x16x32_bf16 v[20:23], v[208:211], v[232:235], v[20:23]
	v_mfma_f32_16x16x32_bf16 v[0:3], v[174:177], v[240:243], v[0:3]
	v_mfma_f32_16x16x32_bf16 v[4:7], v[208:211], v[240:243], v[4:7]
	v_mfma_f32_16x16x32_bf16 v[8:11], v[212:215], v[56:59], v[8:11]
	v_mfma_f32_16x16x32_bf16 v[88:91], v[220:223], v[92:95], v[8:11]
	v_mfma_f32_16x16x32_bf16 v[8:11], v[224:227], v[56:59], v[12:15]
	v_mfma_f32_16x16x32_bf16 v[92:95], v[228:231], v[92:95], v[8:11]
	v_mfma_f32_16x16x32_bf16 v[8:11], v[212:215], v[178:181], v[24:27]
	v_mfma_f32_16x16x32_bf16 v[56:59], v[220:223], v[182:185], v[8:11]
	v_mfma_f32_16x16x32_bf16 v[8:11], v[224:227], v[178:181], v[28:31]
	v_mfma_f32_16x16x32_bf16 v[60:63], v[228:231], v[182:185], v[8:11]
	v_mfma_f32_16x16x32_bf16 v[8:11], v[212:215], v[216:219], v[186:189]
	v_mfma_f32_16x16x32_bf16 v[24:27], v[220:223], v[232:235], v[8:11]
	v_mfma_f32_16x16x32_bf16 v[8:11], v[224:227], v[216:219], v[196:199]
	v_mfma_f32_16x16x32_bf16 v[28:31], v[228:231], v[232:235], v[8:11]
	v_mfma_f32_16x16x32_bf16 v[8:11], v[212:215], v[236:239], v[200:203]
	v_mfma_f32_16x16x32_bf16 v[12:15], v[224:227], v[236:239], v[170:173]
	v_mfma_f32_16x16x32_bf16 v[8:11], v[220:223], v[240:243], v[8:11]
	v_mfma_f32_16x16x32_bf16 v[12:15], v[228:231], v[240:243], v[12:15]
	s_barrier
	s_andn2_b64 vcc, exec, s[18:19]
	s_cbranch_vccnz .LBB0_236
	s_barrier

; #define PG8_STAGE(bufoff, gbase, voff) do { _Pragma("unroll") for (int _i = 0; _i < 2; ++_i) \
;         __builtin_amdgcn_global_load_lds((const unsigned*)((const char*)(gbase) + (voff)[_i]), (PG8_LAS unsigned*)(lds + (bufoff) + ldsw + _i * 8192), 16, 0, 0); } while (0)
; #define PG8_LDA(dst, b, h) do { _Pragma("unroll") for (int m = 0; m < 4; ++m) _Pragma("unroll") for (int k = 0; k < 2; ++k) dst[m][k] = *(const PG8_LAS bf16x8*)(lds + PG8_SA(b, h) + aoff + m * 2048 + k * 1024); } while (0)
; #define PG8_LDB(dst, b, h) do { _Pragma("unroll") for (int n = 0; n < 2; ++n) _Pragma("unroll") for (int k = 0; k < 2; ++k) dst[n][k] = *(const PG8_LAS bf16x8*)(lds + PG8_SB(b, h) + boff + n * 2048 + k * 1024); } while (0)
; #define PG8_MMA(ai, bj, At, Bt) do { __builtin_amdgcn_s_setprio(1); _Pragma("unroll") for (int m = 0; m < 4; ++m) _Pragma("unroll") for (int n = 0; n < 2; ++n) _Pragma("unroll") for (int k = 0; k < 2; ++k) \
;         acc[ai][bj][m][n] = __builtin_amdgcn_mfma_f32_16x16x32_bf16(Bt[n][k], At[m][k], acc[ai][bj][m][n], 0, 0, 0); __builtin_amdgcn_s_setprio(0); } while (0)
; #define PG8_WAIT_V(n) asm volatile("s_waitcnt vmcnt(" #n ")" ::: "memory")
; #define PG8_WAIT_L(n) asm volatile("s_waitcnt lgkmcnt(" #n ")" ::: "memory")
; #define PG8_BAR __builtin_amdgcn_s_barrier()
; template <class Epi, class Sched, bool ALIGN_EPI = false, bool SP2 = false>
; __device__ __forceinline__ void gemm_phase(PG8_LAS unsigned char* lds, const Gemm g, const Sched& S, const Epi& E) {
;     ...
;             const char* a1 = cA + (size_t)(t + 1) * kstep;
;             const char* a2 = last ? nA : cA + (size_t)(t + 2) * kstep; const char* b2 = last ? nB : cB + (size_t)(t + 2) * kstep;
;             const char* a3 = a2 + kstep; const char* b3 = b2 + kstep;
;             if (last && has_next) S.a_ready(nxt);
;             if constexpr (SP2) {
;             PG8_LDB(B0, 0, 0); PG8_LDB(B1, 0, 1); PG8_SCHED; PG8_LDA(At, 0, 0); PG8_STAGE(PG8_SA(1, 1), a1 + hstepA, voffA);
;             PG8_WAIT_V(8); PG8_WAIT_L(0); PG8_BAR; PG8_MMA(0, 0, At, B0); PG8_MMA(0, 1, At, B1); PG8_BAR; PG8_SCHED;
;             PG8_LDA(At, 0, 1); PG8_STAGE(PG8_SB(0, 0), b2, voffB); PG8_STAGE(PG8_SB(0, 1), b2 + hstepB, voffB); PG8_STAGE(PG8_SA(0, 0), a2, voffA);
;             PG8_WAIT_V(8); PG8_WAIT_L(0); PG8_BAR; PG8_MMA(1, 0, At, B0); PG8_MMA(1, 1, At, B1); PG8_BAR; PG8_SCHED;
.LBB0_303:
	ds_read_b128 v[150:153], v147
	ds_read_b128 v[154:157], v147 offset:1024
	ds_read_b128 v[158:161], v147 offset:2048
	ds_read_b128 v[162:165], v147 offset:3072
	ds_read_b128 v[166:169], v148
	ds_read_b128 v[170:173], v148 offset:1024
	ds_read_b128 v[174:177], v148 offset:2048
	ds_read_b128 v[178:181], v148 offset:3072
	s_add_u32 s28, s0, 0xfff80080
	s_addc_u32 s29, s1, -1
	s_cmp_eq_u32 s53, 2
	s_cselect_b32 s31, s23, s29
	s_cselect_b32 s30, s50, s28
	s_cselect_b32 s29, s25, s52
	s_cselect_b32 s28, s24, s51
	s_add_i32 m0, s8, 0xc000
	ds_read_b128 v[182:185], v149
	ds_read_b128 v[186:189], v149 offset:1024
	ds_read_b128 v[196:199], v149 offset:2048
	ds_read_b128 v[200:203], v149 offset:3072
	ds_read_b128 v[204:207], v149 offset:4096
	ds_read_b128 v[208:211], v149 offset:5120
	ds_read_b128 v[212:215], v149 offset:6144
	ds_read_b128 v[216:219], v149 offset:7168
	global_load_lds_dwordx4 v136, s[0:1]
	s_add_i32 m0, s8, 0xe000
	s_nop 0
	global_load_lds_dwordx4 v138, s[0:1]
	s_waitcnt vmcnt(8)
	s_waitcnt lgkmcnt(0)
	s_barrier
	v_mfma_f32_16x16x32_bf16 v[124:127], v[150:153], v[182:185], v[124:127]
	v_mfma_f32_16x16x32_bf16 v[120:123], v[158:161], v[182:185], v[120:123]
	v_mfma_f32_16x16x32_bf16 v[116:119], v[150:153], v[196:199], v[116:119]
	v_mfma_f32_16x16x32_bf16 v[112:115], v[158:161], v[196:199], v[112:115]
	v_mfma_f32_16x16x32_bf16 v[100:103], v[150:153], v[204:207], v[100:103]
	v_mfma_f32_16x16x32_bf16 v[96:99], v[158:161], v[204:207], v[96:99]
	v_mfma_f32_16x16x32_bf16 v[84:87], v[150:153], v[212:215], v[84:87]
	v_mfma_f32_16x16x32_bf16 v[80:83], v[158:161], v[212:215], v[80:83]
	v_mfma_f32_16x16x32_bf16 v[124:127], v[154:157], v[186:189], v[124:127]
	v_mfma_f32_16x16x32_bf16 v[120:123], v[162:165], v[186:189], v[120:123]
	v_mfma_f32_16x16x32_bf16 v[116:119], v[154:157], v[200:203], v[116:119]
	v_mfma_f32_16x16x32_bf16 v[112:115], v[162:165], v[200:203], v[112:115]
	v_mfma_f32_16x16x32_bf16 v[100:103], v[154:157], v[208:211], v[100:103]
	v_mfma_f32_16x16x32_bf16 v[96:99], v[162:165], v[208:211], v[96:99]
	v_mfma_f32_16x16x32_bf16 v[84:87], v[154:157], v[216:219], v[84:87]
	v_mfma_f32_16x16x32_bf16 v[80:83], v[162:165], v[216:219], v[80:83]
	v_mfma_f32_16x16x32_bf16 v[108:111], v[166:169], v[182:185], v[108:111]
	v_mfma_f32_16x16x32_bf16 v[104:107], v[174:177], v[182:185], v[104:107]
	v_mfma_f32_16x16x32_bf16 v[92:95], v[166:169], v[196:199], v[92:95]
	v_mfma_f32_16x16x32_bf16 v[88:91], v[174:177], v[196:199], v[88:91]
	v_mfma_f32_16x16x32_bf16 v[76:79], v[166:169], v[204:207], v[76:79]
	v_mfma_f32_16x16x32_bf16 v[72:75], v[174:177], v[204:207], v[72:75]
	v_mfma_f32_16x16x32_bf16 v[68:71], v[166:169], v[212:215], v[68:71]
	v_mfma_f32_16x16x32_bf16 v[64:67], v[174:177], v[212:215], v[64:67]
	v_mfma_f32_16x16x32_bf16 v[108:111], v[170:173], v[186:189], v[108:111]
	v_mfma_f32_16x16x32_bf16 v[104:107], v[178:181], v[186:189], v[104:107]
	v_mfma_f32_16x16x32_bf16 v[92:95], v[170:173], v[200:203], v[92:95]
	v_mfma_f32_16x16x32_bf16 v[88:91], v[178:181], v[200:203], v[88:91]
	v_mfma_f32_16x16x32_bf16 v[76:79], v[170:173], v[208:211], v[76:79]
	v_mfma_f32_16x16x32_bf16 v[72:75], v[178:181], v[208:211], v[72:75]
	v_mfma_f32_16x16x32_bf16 v[68:71], v[170:173], v[216:219], v[68:71]
	v_mfma_f32_16x16x32_bf16 v[64:67], v[178:181], v[216:219], v[64:67]
	s_barrier
	s_add_i32 s44, s39, s2
	s_add_u32 s98, s28, s16
	s_addc_u32 s99, s29, s17
	s_mov_b32 m0, s44
	ds_read_b128 v[182:185], v149 offset:16384
	ds_read_b128 v[186:189], v149 offset:17408
	ds_read_b128 v[196:199], v149 offset:18432
	ds_read_b128 v[200:203], v149 offset:19456
	ds_read_b128 v[204:207], v149 offset:20480
	ds_read_b128 v[208:211], v149 offset:21504
	ds_read_b128 v[212:215], v149 offset:22528
	ds_read_b128 v[216:219], v149 offset:23552
	global_load_lds_dwordx4 v132, s[28:29]
	s_add_i32 m0, s44, 0x2000
	s_add_u32 s44, s28, 0x18000
	s_addc_u32 s45, s29, 0
	s_add_u32 s98, s28, s16
	s_addc_u32 s99, s29, s17
	s_add_i32 s48, s40, s2
	global_load_lds_dwordx4 v128, s[28:29]
	s_mov_b32 m0, s48
	v_lshl_add_u64 v[220:221], s[30:31], 0, v[130:131]
	global_load_lds_dwordx4 v132, s[44:45]
	s_add_i32 m0, s48, 0x2000
	s_nop 0
	global_load_lds_dwordx4 v128, s[44:45]
	s_add_u32 s100, s30, s16
	s_addc_u32 s101, s31, s17
	s_mov_b32 m0, s8
	s_nop 0
	global_load_lds_dwordx4 v134, s[30:31]
	s_mov_b32 m0, s9
	s_nop 0
	global_load_lds_dwordx4 v[220:221], off
	s_waitcnt vmcnt(8)
	s_waitcnt lgkmcnt(0)
	s_barrier
	v_mfma_f32_16x16x32_bf16 v[60:63], v[150:153], v[182:185], v[60:63]
	v_mfma_f32_16x16x32_bf16 v[56:59], v[158:161], v[182:185], v[56:59]
	v_mfma_f32_16x16x32_bf16 v[52:55], v[150:153], v[196:199], v[52:55]
	v_mfma_f32_16x16x32_bf16 v[48:51], v[158:161], v[196:199], v[48:51]
	v_mfma_f32_16x16x32_bf16 v[36:39], v[150:153], v[204:207], v[36:39]
	v_mfma_f32_16x16x32_bf16 v[32:35], v[158:161], v[204:207], v[32:35]
	v_mfma_f32_16x16x32_bf16 v[20:23], v[150:153], v[212:215], v[20:23]
	v_mfma_f32_16x16x32_bf16 v[16:19], v[158:161], v[212:215], v[16:19]
	v_mfma_f32_16x16x32_bf16 v[60:63], v[154:157], v[186:189], v[60:63]
	v_mfma_f32_16x16x32_bf16 v[56:59], v[162:165], v[186:189], v[56:59]
	v_mfma_f32_16x16x32_bf16 v[52:55], v[154:157], v[200:203], v[52:55]
	v_mfma_f32_16x16x32_bf16 v[48:51], v[162:165], v[200:203], v[48:51]
	v_mfma_f32_16x16x32_bf16 v[36:39], v[154:157], v[208:211], v[36:39]
	v_mfma_f32_16x16x32_bf16 v[32:35], v[162:165], v[208:211], v[32:35]
	v_mfma_f32_16x16x32_bf16 v[20:23], v[154:157], v[216:219], v[20:23]
	v_mfma_f32_16x16x32_bf16 v[16:19], v[162:165], v[216:219], v[16:19]
	v_mfma_f32_16x16x32_bf16 v[44:47], v[166:169], v[182:185], v[44:47]
	v_mfma_f32_16x16x32_bf16 v[40:43], v[174:177], v[182:185], v[40:43]
	v_mfma_f32_16x16x32_bf16 v[28:31], v[166:169], v[196:199], v[28:31]
	v_mfma_f32_16x16x32_bf16 v[24:27], v[174:177], v[196:199], v[24:27]
	v_mfma_f32_16x16x32_bf16 v[12:15], v[166:169], v[204:207], v[12:15]
	v_mfma_f32_16x16x32_bf16 v[8:11], v[174:177], v[204:207], v[8:11]
	v_mfma_f32_16x16x32_bf16 v[4:7], v[166:169], v[212:215], v[4:7]
	v_mfma_f32_16x16x32_bf16 v[0:3], v[174:177], v[212:215], v[0:3]
	v_mfma_f32_16x16x32_bf16 v[44:47], v[170:173], v[186:189], v[44:47]
	v_mfma_f32_16x16x32_bf16 v[40:43], v[178:181], v[186:189], v[40:43]
	v_mfma_f32_16x16x32_bf16 v[28:31], v[170:173], v[200:203], v[28:31]
	v_mfma_f32_16x16x32_bf16 v[24:27], v[178:181], v[200:203], v[24:27]
	v_mfma_f32_16x16x32_bf16 v[12:15], v[170:173], v[208:211], v[12:15]
	v_mfma_f32_16x16x32_bf16 v[8:11], v[178:181], v[208:211], v[8:11]
	v_mfma_f32_16x16x32_bf16 v[4:7], v[170:173], v[216:219], v[4:7]
	v_mfma_f32_16x16x32_bf16 v[0:3], v[178:181], v[216:219], v[0:3]
	s_barrier
; #define PG8_STAGE(bufoff, gbase, voff) do { _Pragma("unroll") for (int _i = 0; _i < 2; ++_i) \
;         __builtin_amdgcn_global_load_lds((const unsigned*)((const char*)(gbase) + (voff)[_i]), (PG8_LAS unsigned*)(lds + (bufoff) + ldsw + _i * 8192), 16, 0, 0); } while (0)
; #define PG8_LDA(dst, b, h) do { _Pragma("unroll") for (int m = 0; m < 4; ++m) _Pragma("unroll") for (int k = 0; k < 2; ++k) dst[m][k] = *(const PG8_LAS bf16x8*)(lds + PG8_SA(b, h) + aoff + m * 2048 + k * 1024); } while (0)
; #define PG8_LDB(dst, b, h) do { _Pragma("unroll") for (int n = 0; n < 2; ++n) _Pragma("unroll") for (int k = 0; k < 2; ++k) dst[n][k] = *(const PG8_LAS bf16x8*)(lds + PG8_SB(b, h) + boff + n * 2048 + k * 1024); } while (0)
; #define PG8_MMA(ai, bj, At, Bt) do { __builtin_amdgcn_s_setprio(1); _Pragma("unroll") for (int m = 0; m < 4; ++m) _Pragma("unroll") for (int n = 0; n < 2; ++n) _Pragma("unroll") for (int k = 0; k < 2; ++k) \
;         acc[ai][bj][m][n] = __builtin_amdgcn_mfma_f32_16x16x32_bf16(Bt[n][k], At[m][k], acc[ai][bj][m][n], 0, 0, 0); __builtin_amdgcn_s_setprio(0); } while (0)
; #define PG8_WAIT_V(n) asm volatile("s_waitcnt vmcnt(" #n ")" ::: "memory")
; #define PG8_WAIT_L(n) asm volatile("s_waitcnt lgkmcnt(" #n ")" ::: "memory")
; #define PG8_BAR __builtin_amdgcn_s_barrier()
; #define PG8_SCHED __builtin_amdgcn_sched_barrier(0)
; template <class Epi, class Sched, bool ALIGN_EPI = false, bool SP2 = false>
; __device__ __forceinline__ void gemm_phase(PG8_LAS unsigned char* lds, const Gemm g, const Sched& S, const Epi& E) {
;     ...
;         for (int t = 0; t < nt; t += 2) {
;             const bool last = (t == nt - 2);
;     ...
;             PG8_LDB(B0, 1, 0); PG8_LDB(B1, 1, 1); PG8_SCHED; PG8_LDA(At, 1, 0); PG8_STAGE(PG8_SA(0, 1), a2 + hstepA, voffA);
;             PG8_WAIT_V(8); PG8_WAIT_L(0); PG8_BAR; PG8_MMA(0, 0, At, B0); PG8_MMA(0, 1, At, B1); PG8_BAR; PG8_SCHED;
;             PG8_LDA(At, 1, 1); PG8_STAGE(PG8_SB(1, 0), b3, voffB); PG8_STAGE(PG8_SB(1, 1), b3 + hstepB, voffB); PG8_STAGE(PG8_SA(1, 0), a3, voffA);
;             PG8_WAIT_V(8); PG8_WAIT_L(0); PG8_BAR; PG8_MMA(1, 0, At, B0); PG8_MMA(1, 1, At, B1); PG8_BAR; PG8_SCHED;
	s_add_i32 s44, 0, 0x18000
	s_add_i32 s45, 0, 0x1c000
	v_add_u32_e32 v162, s44, v146
	v_add_u32_e32 v178, s45, v146
	ds_read_b128 v[150:153], v162
	ds_read_b128 v[154:157], v162 offset:1024
	ds_read_b128 v[158:161], v162 offset:2048
	ds_read_b128 v[162:165], v162 offset:3072
	ds_read_b128 v[166:169], v178
	ds_read_b128 v[170:173], v178 offset:1024
	ds_read_b128 v[174:177], v178 offset:2048
	ds_read_b128 v[178:181], v178 offset:3072
	s_add_u32 s30, s30, 0x80000
	s_addc_u32 s31, s31, 0
	s_mov_b32 m0, s10
	ds_read_b128 v[182:185], v149 offset:32768
	ds_read_b128 v[186:189], v149 offset:33792
	ds_read_b128 v[196:199], v149 offset:34816
	ds_read_b128 v[200:203], v149 offset:35840
	ds_read_b128 v[204:207], v149 offset:36864
	ds_read_b128 v[208:211], v149 offset:37888
	ds_read_b128 v[212:215], v149 offset:38912
	ds_read_b128 v[216:219], v149 offset:39936
	global_load_lds_dwordx4 v134, s[30:31]
	s_mov_b32 m0, s11
	s_nop 0
	global_load_lds_dwordx4 v130, s[30:31]
	s_waitcnt vmcnt(8)
	s_waitcnt lgkmcnt(0)
	s_barrier
	v_mfma_f32_16x16x32_bf16 v[124:127], v[150:153], v[182:185], v[124:127]
	v_mfma_f32_16x16x32_bf16 v[120:123], v[158:161], v[182:185], v[120:123]
	v_mfma_f32_16x16x32_bf16 v[116:119], v[150:153], v[196:199], v[116:119]
	v_mfma_f32_16x16x32_bf16 v[112:115], v[158:161], v[196:199], v[112:115]
	v_mfma_f32_16x16x32_bf16 v[100:103], v[150:153], v[204:207], v[100:103]
	v_mfma_f32_16x16x32_bf16 v[96:99], v[158:161], v[204:207], v[96:99]
	v_mfma_f32_16x16x32_bf16 v[84:87], v[150:153], v[212:215], v[84:87]
	v_mfma_f32_16x16x32_bf16 v[80:83], v[158:161], v[212:215], v[80:83]
	v_mfma_f32_16x16x32_bf16 v[124:127], v[154:157], v[186:189], v[124:127]
	v_mfma_f32_16x16x32_bf16 v[120:123], v[162:165], v[186:189], v[120:123]
	v_mfma_f32_16x16x32_bf16 v[116:119], v[154:157], v[200:203], v[116:119]
	v_mfma_f32_16x16x32_bf16 v[112:115], v[162:165], v[200:203], v[112:115]
	v_mfma_f32_16x16x32_bf16 v[100:103], v[154:157], v[208:211], v[100:103]
	v_mfma_f32_16x16x32_bf16 v[96:99], v[162:165], v[208:211], v[96:99]
	v_mfma_f32_16x16x32_bf16 v[84:87], v[154:157], v[216:219], v[84:87]
	v_mfma_f32_16x16x32_bf16 v[80:83], v[162:165], v[216:219], v[80:83]
	v_mfma_f32_16x16x32_bf16 v[108:111], v[166:169], v[182:185], v[108:111]
	v_mfma_f32_16x16x32_bf16 v[104:107], v[174:177], v[182:185], v[104:107]
	v_mfma_f32_16x16x32_bf16 v[92:95], v[166:169], v[196:199], v[92:95]
	v_mfma_f32_16x16x32_bf16 v[88:91], v[174:177], v[196:199], v[88:91]
	v_mfma_f32_16x16x32_bf16 v[76:79], v[166:169], v[204:207], v[76:79]
	v_mfma_f32_16x16x32_bf16 v[72:75], v[174:177], v[204:207], v[72:75]
	v_mfma_f32_16x16x32_bf16 v[68:71], v[166:169], v[212:215], v[68:71]
	v_mfma_f32_16x16x32_bf16 v[64:67], v[174:177], v[212:215], v[64:67]
	v_mfma_f32_16x16x32_bf16 v[108:111], v[170:173], v[186:189], v[108:111]
	v_mfma_f32_16x16x32_bf16 v[104:107], v[178:181], v[186:189], v[104:107]
	v_mfma_f32_16x16x32_bf16 v[92:95], v[170:173], v[200:203], v[92:95]
	v_mfma_f32_16x16x32_bf16 v[88:91], v[178:181], v[200:203], v[88:91]
	v_mfma_f32_16x16x32_bf16 v[76:79], v[170:173], v[208:211], v[76:79]
	v_mfma_f32_16x16x32_bf16 v[72:75], v[178:181], v[208:211], v[72:75]
	v_mfma_f32_16x16x32_bf16 v[68:71], v[170:173], v[216:219], v[68:71]
	v_mfma_f32_16x16x32_bf16 v[64:67], v[178:181], v[216:219], v[64:67]
	s_barrier
	s_add_i32 s30, s44, s2
	s_mov_b32 m0, s30
	ds_read_b128 v[182:185], v149 offset:49152
	ds_read_b128 v[186:189], v149 offset:50176
	ds_read_b128 v[196:199], v149 offset:51200
	ds_read_b128 v[200:203], v149 offset:52224
	ds_read_b128 v[204:207], v149 offset:53248
	ds_read_b128 v[208:211], v149 offset:54272
	ds_read_b128 v[212:215], v149 offset:55296
	ds_read_b128 v[216:219], v149 offset:56320
	global_load_lds_dwordx4 v132, s[98:99]
	s_add_i32 m0, s30, 0x2000
	s_add_u32 s28, s28, 0x18080
	s_addc_u32 s29, s29, 0
	s_add_i32 s30, s45, s2
	global_load_lds_dwordx4 v128, s[98:99]
	s_mov_b32 m0, s30
	s_nop 0
	global_load_lds_dwordx4 v132, s[28:29]
	s_add_i32 m0, s30, 0x2000
	s_nop 0
	global_load_lds_dwordx4 v128, s[28:29]
	s_mov_b32 m0, s35
	s_nop 0
	global_load_lds_dwordx4 v134, s[100:101]
	v_lshl_add_u64 v[190:191], v[220:221], 0, s[16:17]
	s_mov_b32 m0, s36
	s_nop 0
	global_load_lds_dwordx4 v[190:191], off
	s_waitcnt vmcnt(8)
	s_waitcnt lgkmcnt(0)
	s_barrier
	v_mfma_f32_16x16x32_bf16 v[60:63], v[150:153], v[182:185], v[60:63]
	v_mfma_f32_16x16x32_bf16 v[56:59], v[158:161], v[182:185], v[56:59]
	v_mfma_f32_16x16x32_bf16 v[52:55], v[150:153], v[196:199], v[52:55]
	v_mfma_f32_16x16x32_bf16 v[48:51], v[158:161], v[196:199], v[48:51]
	v_mfma_f32_16x16x32_bf16 v[36:39], v[150:153], v[204:207], v[36:39]
	v_mfma_f32_16x16x32_bf16 v[32:35], v[158:161], v[204:207], v[32:35]
	v_mfma_f32_16x16x32_bf16 v[20:23], v[150:153], v[212:215], v[20:23]
	v_mfma_f32_16x16x32_bf16 v[16:19], v[158:161], v[212:215], v[16:19]
	v_mfma_f32_16x16x32_bf16 v[60:63], v[154:157], v[186:189], v[60:63]
	v_mfma_f32_16x16x32_bf16 v[56:59], v[162:165], v[186:189], v[56:59]
	v_mfma_f32_16x16x32_bf16 v[52:55], v[154:157], v[200:203], v[52:55]
	v_mfma_f32_16x16x32_bf16 v[48:51], v[162:165], v[200:203], v[48:51]
	v_mfma_f32_16x16x32_bf16 v[36:39], v[154:157], v[208:211], v[36:39]
	v_mfma_f32_16x16x32_bf16 v[32:35], v[162:165], v[208:211], v[32:35]
	v_mfma_f32_16x16x32_bf16 v[20:23], v[154:157], v[216:219], v[20:23]
	v_mfma_f32_16x16x32_bf16 v[16:19], v[162:165], v[216:219], v[16:19]
	v_mfma_f32_16x16x32_bf16 v[44:47], v[166:169], v[182:185], v[44:47]
	v_mfma_f32_16x16x32_bf16 v[40:43], v[174:177], v[182:185], v[40:43]
	v_mfma_f32_16x16x32_bf16 v[28:31], v[166:169], v[196:199], v[28:31]
	v_mfma_f32_16x16x32_bf16 v[24:27], v[174:177], v[196:199], v[24:27]
	v_mfma_f32_16x16x32_bf16 v[12:15], v[166:169], v[204:207], v[12:15]
	v_mfma_f32_16x16x32_bf16 v[8:11], v[174:177], v[204:207], v[8:11]
	v_mfma_f32_16x16x32_bf16 v[4:7], v[166:169], v[212:215], v[4:7]
	v_mfma_f32_16x16x32_bf16 v[0:3], v[174:177], v[212:215], v[0:3]
	v_mfma_f32_16x16x32_bf16 v[44:47], v[170:173], v[186:189], v[44:47]
	v_mfma_f32_16x16x32_bf16 v[40:43], v[178:181], v[186:189], v[40:43]
	v_mfma_f32_16x16x32_bf16 v[28:31], v[170:173], v[200:203], v[28:31]
	v_mfma_f32_16x16x32_bf16 v[24:27], v[178:181], v[200:203], v[24:27]
	v_mfma_f32_16x16x32_bf16 v[12:15], v[170:173], v[208:211], v[12:15]
	v_mfma_f32_16x16x32_bf16 v[8:11], v[178:181], v[208:211], v[8:11]
	v_mfma_f32_16x16x32_bf16 v[4:7], v[170:173], v[216:219], v[4:7]
	v_mfma_f32_16x16x32_bf16 v[0:3], v[178:181], v[216:219], v[0:3]
	s_barrier
	s_add_i32 s53, s53, 2
	s_add_u32 s0, s0, 0x100
	s_addc_u32 s1, s1, 0
	s_add_u32 s51, s51, 0x100
	s_addc_u32 s52, s52, 0
	s_cmp_gt_u32 s53, 3
	s_cbranch_scc0 .LBB0_303
	s_and_b64 vcc, exec, s[18:19]
	s_cbranch_vccz .LBB0_306
	s_barrier

; #define PG8_STAGE(bufoff, gbase, voff) do { _Pragma("unroll") for (int _i = 0; _i < 2; ++_i) \
;         __builtin_amdgcn_global_load_lds((const unsigned*)((const char*)(gbase) + (voff)[_i]), (PG8_LAS unsigned*)(lds + (bufoff) + ldsw + _i * 8192), 16, 0, 0); } while (0)
; #define PG8_LDA(dst, b, h) do { _Pragma("unroll") for (int m = 0; m < 4; ++m) _Pragma("unroll") for (int k = 0; k < 2; ++k) dst[m][k] = *(const PG8_LAS bf16x8*)(lds + PG8_SA(b, h) + aoff + m * 2048 + k * 1024); } while (0)
; #define PG8_LDB(dst, b, h) do { _Pragma("unroll") for (int n = 0; n < 2; ++n) _Pragma("unroll") for (int k = 0; k < 2; ++k) dst[n][k] = *(const PG8_LAS bf16x8*)(lds + PG8_SB(b, h) + boff + n * 2048 + k * 1024); } while (0)
; #define PG8_MMA(ai, bj, At, Bt) do { __builtin_amdgcn_s_setprio(1); _Pragma("unroll") for (int m = 0; m < 4; ++m) _Pragma("unroll") for (int n = 0; n < 2; ++n) _Pragma("unroll") for (int k = 0; k < 2; ++k) \
;         acc[ai][bj][m][n] = __builtin_amdgcn_mfma_f32_16x16x32_bf16(Bt[n][k], At[m][k], acc[ai][bj][m][n], 0, 0, 0); __builtin_amdgcn_s_setprio(0); } while (0)
; #define PG8_WAIT_V(n) asm volatile("s_waitcnt vmcnt(" #n ")" ::: "memory")
; #define PG8_WAIT_L(n) asm volatile("s_waitcnt lgkmcnt(" #n ")" ::: "memory")
; template <class Epi, class Sched, bool ALIGN_EPI = false, bool SP2 = false>
; __device__ __forceinline__ void gemm_phase(PG8_LAS unsigned char* lds, const Gemm g, const Sched& S, const Epi& E) {
;     ...
;             const bool last = (t == nt - 2);
;             const char* a1 = cA + (size_t)(t + 1) * kstep;
;             const char* a2 = last ? nA : cA + (size_t)(t + 2) * kstep; const char* b2 = last ? nB : cB + (size_t)(t + 2) * kstep;
;             const char* a3 = a2 + kstep; const char* b3 = b2 + kstep;
;             if (last && has_next) S.a_ready(nxt);
;             if constexpr (SP2) {
;             PG8_LDB(B0, 0, 0); PG8_LDB(B1, 0, 1); PG8_SCHED; PG8_LDA(At, 0, 0); PG8_STAGE(PG8_SA(1, 1), a1 + hstepA, voffA);
;             PG8_WAIT_V(8); PG8_WAIT_L(0); PG8_BAR; PG8_MMA(0, 0, At, B0); PG8_MMA(0, 1, At, B1); PG8_BAR; PG8_SCHED;
;             PG8_LDA(At, 0, 1); PG8_STAGE(PG8_SB(0, 0), b2, voffB); PG8_STAGE(PG8_SB(0, 1), b2 + hstepB, voffB); PG8_STAGE(PG8_SA(0, 0), a2, voffA);
;             PG8_WAIT_V(8); PG8_WAIT_L(0); PG8_BAR; PG8_MMA(1, 0, At, B0); PG8_MMA(1, 1, At, B1); PG8_BAR; PG8_SCHED;
.LBB0_632:
	ds_read_b128 v[144:147], v151
	ds_read_b128 v[156:159], v151 offset:1024
	ds_read_b128 v[160:163], v151 offset:2048
	ds_read_b128 v[164:167], v151 offset:3072
	ds_read_b128 v[168:171], v152
	ds_read_b128 v[172:175], v152 offset:1024
	ds_read_b128 v[176:179], v152 offset:2048
	ds_read_b128 v[180:183], v152 offset:3072
	s_add_u32 s28, s26, 0xfffc0080
	s_addc_u32 s29, s27, -1
	s_cmp_eq_u32 s50, 12
	s_cselect_b32 s31, s17, s29
	s_cselect_b32 s30, s23, s28
	s_cselect_b32 s29, s15, s49
	s_cselect_b32 s28, s43, s48
	s_add_i32 m0, s9, 0xc000
	ds_read_b128 v[184:187], v153
	ds_read_b128 v[188:191], v153 offset:1024
	ds_read_b128 v[194:197], v153 offset:2048
	ds_read_b128 v[198:201], v153 offset:3072
	ds_read_b128 v[202:205], v153 offset:4096
	ds_read_b128 v[206:209], v153 offset:5120
	ds_read_b128 v[210:213], v153 offset:6144
	ds_read_b128 v[214:217], v153 offset:7168
	global_load_lds_dwordx4 v136, s[26:27]
	s_add_i32 m0, s9, 0xe000
	s_nop 0
	global_load_lds_dwordx4 v138, s[26:27]
	s_waitcnt vmcnt(8)
	s_waitcnt lgkmcnt(0)
	s_barrier
	v_mfma_f32_16x16x32_bf16 v[124:127], v[144:147], v[184:187], v[124:127]
	v_mfma_f32_16x16x32_bf16 v[120:123], v[160:163], v[184:187], v[120:123]
	v_mfma_f32_16x16x32_bf16 v[108:111], v[144:147], v[194:197], v[108:111]
	v_mfma_f32_16x16x32_bf16 v[104:107], v[160:163], v[194:197], v[104:107]
	v_mfma_f32_16x16x32_bf16 v[92:95], v[144:147], v[202:205], v[92:95]
	v_mfma_f32_16x16x32_bf16 v[88:91], v[160:163], v[202:205], v[88:91]
	v_mfma_f32_16x16x32_bf16 v[76:79], v[144:147], v[210:213], v[76:79]
	v_mfma_f32_16x16x32_bf16 v[72:75], v[160:163], v[210:213], v[72:75]
	v_mfma_f32_16x16x32_bf16 v[124:127], v[156:159], v[188:191], v[124:127]
	v_mfma_f32_16x16x32_bf16 v[120:123], v[164:167], v[188:191], v[120:123]
	v_mfma_f32_16x16x32_bf16 v[108:111], v[156:159], v[198:201], v[108:111]
	v_mfma_f32_16x16x32_bf16 v[104:107], v[164:167], v[198:201], v[104:107]
	v_mfma_f32_16x16x32_bf16 v[92:95], v[156:159], v[206:209], v[92:95]
	v_mfma_f32_16x16x32_bf16 v[88:91], v[164:167], v[206:209], v[88:91]
	v_mfma_f32_16x16x32_bf16 v[76:79], v[156:159], v[214:217], v[76:79]
	v_mfma_f32_16x16x32_bf16 v[72:75], v[164:167], v[214:217], v[72:75]
	v_mfma_f32_16x16x32_bf16 v[116:119], v[168:171], v[184:187], v[116:119]
	v_mfma_f32_16x16x32_bf16 v[112:115], v[176:179], v[184:187], v[112:115]
	v_mfma_f32_16x16x32_bf16 v[100:103], v[168:171], v[194:197], v[100:103]
	v_mfma_f32_16x16x32_bf16 v[96:99], v[176:179], v[194:197], v[96:99]
	v_mfma_f32_16x16x32_bf16 v[84:87], v[168:171], v[202:205], v[84:87]
	v_mfma_f32_16x16x32_bf16 v[80:83], v[176:179], v[202:205], v[80:83]
	v_mfma_f32_16x16x32_bf16 v[68:71], v[168:171], v[210:213], v[68:71]
	v_mfma_f32_16x16x32_bf16 v[64:67], v[176:179], v[210:213], v[64:67]
	v_mfma_f32_16x16x32_bf16 v[116:119], v[172:175], v[188:191], v[116:119]
	v_mfma_f32_16x16x32_bf16 v[112:115], v[180:183], v[188:191], v[112:115]
	v_mfma_f32_16x16x32_bf16 v[100:103], v[172:175], v[198:201], v[100:103]
	v_mfma_f32_16x16x32_bf16 v[96:99], v[180:183], v[198:201], v[96:99]
	v_mfma_f32_16x16x32_bf16 v[84:87], v[172:175], v[206:209], v[84:87]
	v_mfma_f32_16x16x32_bf16 v[80:83], v[180:183], v[206:209], v[80:83]
	v_mfma_f32_16x16x32_bf16 v[68:71], v[172:175], v[214:217], v[68:71]
	v_mfma_f32_16x16x32_bf16 v[64:67], v[180:183], v[214:217], v[64:67]
	s_barrier
	s_add_i32 s44, s41, s8
	s_add_u32 s98, s28, s6
	s_addc_u32 s99, s29, s7
	s_mov_b32 m0, s44
	ds_read_b128 v[184:187], v153 offset:16384
	ds_read_b128 v[188:191], v153 offset:17408
	ds_read_b128 v[194:197], v153 offset:18432
	ds_read_b128 v[198:201], v153 offset:19456
	ds_read_b128 v[202:205], v153 offset:20480
	ds_read_b128 v[206:209], v153 offset:21504
	ds_read_b128 v[210:213], v153 offset:22528
	ds_read_b128 v[214:217], v153 offset:23552
	global_load_lds_dwordx4 v130, s[28:29]
	s_add_i32 m0, s44, 0x2000
	s_add_u32 s44, s28, 0x40000
	s_addc_u32 s45, s29, 0
	s_add_u32 s98, s28, s6
	s_addc_u32 s99, s29, s7
	s_add_i32 s51, s42, s8
	global_load_lds_dwordx4 v134, s[28:29]
	s_mov_b32 m0, s51
	v_lshl_add_u64 v[222:223], s[30:31], 0, v[132:133]
	global_load_lds_dwordx4 v130, s[44:45]
	s_add_i32 m0, s51, 0x2000
	s_nop 0
	global_load_lds_dwordx4 v134, s[44:45]
	s_add_u32 s100, s30, s6
	s_addc_u32 s101, s31, s7
	s_mov_b32 m0, s9
	s_nop 0
	global_load_lds_dwordx4 v128, s[30:31]
	s_mov_b32 m0, s10
	s_nop 0
	global_load_lds_dwordx4 v[222:223], off
	s_waitcnt vmcnt(8)
	s_waitcnt lgkmcnt(0)
	s_barrier
	v_mfma_f32_16x16x32_bf16 v[60:63], v[144:147], v[184:187], v[60:63]
	v_mfma_f32_16x16x32_bf16 v[56:59], v[160:163], v[184:187], v[56:59]
	v_mfma_f32_16x16x32_bf16 v[44:47], v[144:147], v[194:197], v[44:47]
	v_mfma_f32_16x16x32_bf16 v[40:43], v[160:163], v[194:197], v[40:43]
	v_mfma_f32_16x16x32_bf16 v[28:31], v[144:147], v[202:205], v[28:31]
	v_mfma_f32_16x16x32_bf16 v[24:27], v[160:163], v[202:205], v[24:27]
	v_mfma_f32_16x16x32_bf16 v[12:15], v[144:147], v[210:213], v[12:15]
	v_mfma_f32_16x16x32_bf16 v[8:11], v[160:163], v[210:213], v[8:11]
	v_mfma_f32_16x16x32_bf16 v[60:63], v[156:159], v[188:191], v[60:63]
	v_mfma_f32_16x16x32_bf16 v[56:59], v[164:167], v[188:191], v[56:59]
	v_mfma_f32_16x16x32_bf16 v[44:47], v[156:159], v[198:201], v[44:47]
	v_mfma_f32_16x16x32_bf16 v[40:43], v[164:167], v[198:201], v[40:43]
	v_mfma_f32_16x16x32_bf16 v[28:31], v[156:159], v[206:209], v[28:31]
	v_mfma_f32_16x16x32_bf16 v[24:27], v[164:167], v[206:209], v[24:27]
	v_mfma_f32_16x16x32_bf16 v[12:15], v[156:159], v[214:217], v[12:15]
	v_mfma_f32_16x16x32_bf16 v[8:11], v[164:167], v[214:217], v[8:11]
	v_mfma_f32_16x16x32_bf16 v[52:55], v[168:171], v[184:187], v[52:55]
	v_mfma_f32_16x16x32_bf16 v[48:51], v[176:179], v[184:187], v[48:51]
	v_mfma_f32_16x16x32_bf16 v[36:39], v[168:171], v[194:197], v[36:39]
	v_mfma_f32_16x16x32_bf16 v[32:35], v[176:179], v[194:197], v[32:35]
	v_mfma_f32_16x16x32_bf16 v[20:23], v[168:171], v[202:205], v[20:23]
	v_mfma_f32_16x16x32_bf16 v[16:19], v[176:179], v[202:205], v[16:19]
	v_mfma_f32_16x16x32_bf16 v[4:7], v[168:171], v[210:213], v[4:7]
	v_mfma_f32_16x16x32_bf16 v[0:3], v[176:179], v[210:213], v[0:3]
	v_mfma_f32_16x16x32_bf16 v[52:55], v[172:175], v[188:191], v[52:55]
	v_mfma_f32_16x16x32_bf16 v[48:51], v[180:183], v[188:191], v[48:51]
	v_mfma_f32_16x16x32_bf16 v[36:39], v[172:175], v[198:201], v[36:39]
	v_mfma_f32_16x16x32_bf16 v[32:35], v[180:183], v[198:201], v[32:35]
	v_mfma_f32_16x16x32_bf16 v[20:23], v[172:175], v[206:209], v[20:23]
	v_mfma_f32_16x16x32_bf16 v[16:19], v[180:183], v[206:209], v[16:19]
	v_mfma_f32_16x16x32_bf16 v[4:7], v[172:175], v[214:217], v[4:7]
	v_mfma_f32_16x16x32_bf16 v[0:3], v[180:183], v[214:217], v[0:3]
	s_barrier
; #define PG8_STAGE(bufoff, gbase, voff) do { _Pragma("unroll") for (int _i = 0; _i < 2; ++_i) \
;         __builtin_amdgcn_global_load_lds((const unsigned*)((const char*)(gbase) + (voff)[_i]), (PG8_LAS unsigned*)(lds + (bufoff) + ldsw + _i * 8192), 16, 0, 0); } while (0)
; #define PG8_LDA(dst, b, h) do { _Pragma("unroll") for (int m = 0; m < 4; ++m) _Pragma("unroll") for (int k = 0; k < 2; ++k) dst[m][k] = *(const PG8_LAS bf16x8*)(lds + PG8_SA(b, h) + aoff + m * 2048 + k * 1024); } while (0)
; #define PG8_LDB(dst, b, h) do { _Pragma("unroll") for (int n = 0; n < 2; ++n) _Pragma("unroll") for (int k = 0; k < 2; ++k) dst[n][k] = *(const PG8_LAS bf16x8*)(lds + PG8_SB(b, h) + boff + n * 2048 + k * 1024); } while (0)
; #define PG8_MMA(ai, bj, At, Bt) do { __builtin_amdgcn_s_setprio(1); _Pragma("unroll") for (int m = 0; m < 4; ++m) _Pragma("unroll") for (int n = 0; n < 2; ++n) _Pragma("unroll") for (int k = 0; k < 2; ++k) \
;         acc[ai][bj][m][n] = __builtin_amdgcn_mfma_f32_16x16x32_bf16(Bt[n][k], At[m][k], acc[ai][bj][m][n], 0, 0, 0); __builtin_amdgcn_s_setprio(0); } while (0)
; #define PG8_WAIT_V(n) asm volatile("s_waitcnt vmcnt(" #n ")" ::: "memory")
; #define PG8_WAIT_L(n) asm volatile("s_waitcnt lgkmcnt(" #n ")" ::: "memory")
; #define PG8_BAR __builtin_amdgcn_s_barrier()
; #define PG8_SCHED __builtin_amdgcn_sched_barrier(0)
; template <class Epi, class Sched, bool ALIGN_EPI = false, bool SP2 = false>
; __device__ __forceinline__ void gemm_phase(PG8_LAS unsigned char* lds, const Gemm g, const Sched& S, const Epi& E) {
;     ...
;             PG8_LDB(B0, 1, 0); PG8_LDB(B1, 1, 1); PG8_SCHED; PG8_LDA(At, 1, 0); PG8_STAGE(PG8_SA(0, 1), a2 + hstepA, voffA);
;             PG8_WAIT_V(8); PG8_WAIT_L(0); PG8_BAR; PG8_MMA(0, 0, At, B0); PG8_MMA(0, 1, At, B1); PG8_BAR; PG8_SCHED;
;             PG8_LDA(At, 1, 1); PG8_STAGE(PG8_SB(1, 0), b3, voffB); PG8_STAGE(PG8_SB(1, 1), b3 + hstepB, voffB); PG8_STAGE(PG8_SA(1, 0), a3, voffA);
;             PG8_WAIT_V(8); PG8_WAIT_L(0); PG8_BAR; PG8_MMA(1, 0, At, B0); PG8_MMA(1, 1, At, B1); PG8_BAR; PG8_SCHED;
	s_add_i32 s44, 0, 0x18000
	v_add_u32_e32 v155, s44, v150
	s_add_i32 s45, 0, 0x1c000
	ds_read_b128 v[144:147], v155
	ds_read_b128 v[156:159], v155 offset:1024
	ds_read_b128 v[160:163], v155 offset:2048
	ds_read_b128 v[164:167], v155 offset:3072
	v_add_u32_e32 v155, s45, v150
	ds_read_b128 v[168:171], v155
	ds_read_b128 v[172:175], v155 offset:1024
	ds_read_b128 v[176:179], v155 offset:2048
	ds_read_b128 v[180:183], v155 offset:3072
	s_add_u32 s30, s30, 0x40000
	s_addc_u32 s31, s31, 0
	s_mov_b32 m0, s11
	ds_read_b128 v[184:187], v153 offset:32768
	ds_read_b128 v[188:191], v153 offset:33792
	ds_read_b128 v[194:197], v153 offset:34816
	ds_read_b128 v[198:201], v153 offset:35840
	ds_read_b128 v[202:205], v153 offset:36864
	ds_read_b128 v[206:209], v153 offset:37888
	ds_read_b128 v[210:213], v153 offset:38912
	ds_read_b128 v[214:217], v153 offset:39936
	global_load_lds_dwordx4 v128, s[30:31]
	s_mov_b32 m0, s25
	s_nop 0
	global_load_lds_dwordx4 v132, s[30:31]
	s_waitcnt vmcnt(8)
	s_waitcnt lgkmcnt(0)
	s_barrier
	v_mfma_f32_16x16x32_bf16 v[124:127], v[144:147], v[184:187], v[124:127]
	v_mfma_f32_16x16x32_bf16 v[120:123], v[160:163], v[184:187], v[120:123]
	v_mfma_f32_16x16x32_bf16 v[108:111], v[144:147], v[194:197], v[108:111]
	v_mfma_f32_16x16x32_bf16 v[104:107], v[160:163], v[194:197], v[104:107]
	v_mfma_f32_16x16x32_bf16 v[92:95], v[144:147], v[202:205], v[92:95]
	v_mfma_f32_16x16x32_bf16 v[88:91], v[160:163], v[202:205], v[88:91]
	v_mfma_f32_16x16x32_bf16 v[76:79], v[144:147], v[210:213], v[76:79]
	v_mfma_f32_16x16x32_bf16 v[72:75], v[160:163], v[210:213], v[72:75]
	v_mfma_f32_16x16x32_bf16 v[124:127], v[156:159], v[188:191], v[124:127]
	v_mfma_f32_16x16x32_bf16 v[120:123], v[164:167], v[188:191], v[120:123]
	v_mfma_f32_16x16x32_bf16 v[108:111], v[156:159], v[198:201], v[108:111]
	v_mfma_f32_16x16x32_bf16 v[104:107], v[164:167], v[198:201], v[104:107]
	v_mfma_f32_16x16x32_bf16 v[92:95], v[156:159], v[206:209], v[92:95]
	v_mfma_f32_16x16x32_bf16 v[88:91], v[164:167], v[206:209], v[88:91]
	v_mfma_f32_16x16x32_bf16 v[76:79], v[156:159], v[214:217], v[76:79]
	v_mfma_f32_16x16x32_bf16 v[72:75], v[164:167], v[214:217], v[72:75]
	v_mfma_f32_16x16x32_bf16 v[116:119], v[168:171], v[184:187], v[116:119]
	v_mfma_f32_16x16x32_bf16 v[112:115], v[176:179], v[184:187], v[112:115]
	v_mfma_f32_16x16x32_bf16 v[100:103], v[168:171], v[194:197], v[100:103]
	v_mfma_f32_16x16x32_bf16 v[96:99], v[176:179], v[194:197], v[96:99]
	v_mfma_f32_16x16x32_bf16 v[84:87], v[168:171], v[202:205], v[84:87]
	v_mfma_f32_16x16x32_bf16 v[80:83], v[176:179], v[202:205], v[80:83]
	v_mfma_f32_16x16x32_bf16 v[68:71], v[168:171], v[210:213], v[68:71]
	v_mfma_f32_16x16x32_bf16 v[64:67], v[176:179], v[210:213], v[64:67]
	v_mfma_f32_16x16x32_bf16 v[116:119], v[172:175], v[188:191], v[116:119]
	v_mfma_f32_16x16x32_bf16 v[112:115], v[180:183], v[188:191], v[112:115]
	v_mfma_f32_16x16x32_bf16 v[100:103], v[172:175], v[198:201], v[100:103]
	v_mfma_f32_16x16x32_bf16 v[96:99], v[180:183], v[198:201], v[96:99]
	v_mfma_f32_16x16x32_bf16 v[84:87], v[172:175], v[206:209], v[84:87]
	v_mfma_f32_16x16x32_bf16 v[80:83], v[180:183], v[206:209], v[80:83]
	v_mfma_f32_16x16x32_bf16 v[68:71], v[172:175], v[214:217], v[68:71]
	v_mfma_f32_16x16x32_bf16 v[64:67], v[180:183], v[214:217], v[64:67]
	s_barrier
	s_add_i32 s30, s44, s8
	s_mov_b32 m0, s30
	ds_read_b128 v[184:187], v153 offset:49152
	ds_read_b128 v[188:191], v153 offset:50176
	ds_read_b128 v[194:197], v153 offset:51200
	ds_read_b128 v[198:201], v153 offset:52224
	ds_read_b128 v[202:205], v153 offset:53248
	ds_read_b128 v[206:209], v153 offset:54272
	ds_read_b128 v[210:213], v153 offset:55296
	ds_read_b128 v[214:217], v153 offset:56320
	global_load_lds_dwordx4 v130, s[98:99]
	s_add_i32 m0, s30, 0x2000
	s_add_u32 s28, s28, 0x40080
	s_addc_u32 s29, s29, 0
	s_add_i32 s30, s45, s8
	global_load_lds_dwordx4 v134, s[98:99]
	s_mov_b32 m0, s30
	s_nop 0
	global_load_lds_dwordx4 v130, s[28:29]
	s_add_i32 m0, s30, 0x2000
	s_nop 0
	global_load_lds_dwordx4 v134, s[28:29]
	s_mov_b32 m0, s36
	s_nop 0
	global_load_lds_dwordx4 v128, s[100:101]
	v_lshl_add_u64 v[192:193], v[222:223], 0, s[6:7]
	s_mov_b32 m0, s37
	s_nop 0
	global_load_lds_dwordx4 v[192:193], off
	s_waitcnt vmcnt(8)
	s_waitcnt lgkmcnt(0)
	s_barrier
	v_mfma_f32_16x16x32_bf16 v[60:63], v[144:147], v[184:187], v[60:63]
	v_mfma_f32_16x16x32_bf16 v[56:59], v[160:163], v[184:187], v[56:59]
	v_mfma_f32_16x16x32_bf16 v[44:47], v[144:147], v[194:197], v[44:47]
	v_mfma_f32_16x16x32_bf16 v[40:43], v[160:163], v[194:197], v[40:43]
	v_mfma_f32_16x16x32_bf16 v[28:31], v[144:147], v[202:205], v[28:31]
	v_mfma_f32_16x16x32_bf16 v[24:27], v[160:163], v[202:205], v[24:27]
	v_mfma_f32_16x16x32_bf16 v[12:15], v[144:147], v[210:213], v[12:15]
	v_mfma_f32_16x16x32_bf16 v[8:11], v[160:163], v[210:213], v[8:11]
	v_mfma_f32_16x16x32_bf16 v[60:63], v[156:159], v[188:191], v[60:63]
	v_mfma_f32_16x16x32_bf16 v[56:59], v[164:167], v[188:191], v[56:59]
	v_mfma_f32_16x16x32_bf16 v[44:47], v[156:159], v[198:201], v[44:47]
	v_mfma_f32_16x16x32_bf16 v[40:43], v[164:167], v[198:201], v[40:43]
	v_mfma_f32_16x16x32_bf16 v[28:31], v[156:159], v[206:209], v[28:31]
	v_mfma_f32_16x16x32_bf16 v[24:27], v[164:167], v[206:209], v[24:27]
	v_mfma_f32_16x16x32_bf16 v[12:15], v[156:159], v[214:217], v[12:15]
	v_mfma_f32_16x16x32_bf16 v[8:11], v[164:167], v[214:217], v[8:11]
	v_mfma_f32_16x16x32_bf16 v[52:55], v[168:171], v[184:187], v[52:55]
	v_mfma_f32_16x16x32_bf16 v[48:51], v[176:179], v[184:187], v[48:51]
	v_mfma_f32_16x16x32_bf16 v[36:39], v[168:171], v[194:197], v[36:39]
	v_mfma_f32_16x16x32_bf16 v[32:35], v[176:179], v[194:197], v[32:35]
	v_mfma_f32_16x16x32_bf16 v[20:23], v[168:171], v[202:205], v[20:23]
	v_mfma_f32_16x16x32_bf16 v[16:19], v[176:179], v[202:205], v[16:19]
	v_mfma_f32_16x16x32_bf16 v[4:7], v[168:171], v[210:213], v[4:7]
	v_mfma_f32_16x16x32_bf16 v[0:3], v[176:179], v[210:213], v[0:3]
	v_mfma_f32_16x16x32_bf16 v[52:55], v[172:175], v[188:191], v[52:55]
	v_mfma_f32_16x16x32_bf16 v[48:51], v[180:183], v[188:191], v[48:51]
	v_mfma_f32_16x16x32_bf16 v[36:39], v[172:175], v[198:201], v[36:39]
	v_mfma_f32_16x16x32_bf16 v[32:35], v[180:183], v[198:201], v[32:35]
	v_mfma_f32_16x16x32_bf16 v[20:23], v[172:175], v[206:209], v[20:23]
	v_mfma_f32_16x16x32_bf16 v[16:19], v[180:183], v[206:209], v[16:19]
	v_mfma_f32_16x16x32_bf16 v[4:7], v[172:175], v[214:217], v[4:7]
	v_mfma_f32_16x16x32_bf16 v[0:3], v[180:183], v[214:217], v[0:3]
	s_barrier
	s_add_i32 s50, s50, 2
	s_add_u32 s26, s26, 0x100
	s_addc_u32 s27, s27, 0
	s_add_u32 s48, s48, 0x100
	s_addc_u32 s49, s49, 0
	s_cmp_gt_u32 s50, 13
	s_cbranch_scc0 .LBB0_632
	s_and_b64 vcc, exec, s[12:13]
	s_cbranch_vccz .LBB0_635
	s_barrier

; #define PG8_STAGE(bufoff, gbase, voff) do { _Pragma("unroll") for (int _i = 0; _i < 2; ++_i) \
;         __builtin_amdgcn_global_load_lds((const unsigned*)((const char*)(gbase) + (voff)[_i]), (PG8_LAS unsigned*)(lds + (bufoff) + ldsw + _i * 8192), 16, 0, 0); } while (0)
; #define PG8_LDA(dst, b, h) do { _Pragma("unroll") for (int m = 0; m < 4; ++m) _Pragma("unroll") for (int k = 0; k < 2; ++k) dst[m][k] = *(const PG8_LAS bf16x8*)(lds + PG8_SA(b, h) + aoff + m * 2048 + k * 1024); } while (0)
; #define PG8_LDB(dst, b, h) do { _Pragma("unroll") for (int n = 0; n < 2; ++n) _Pragma("unroll") for (int k = 0; k < 2; ++k) dst[n][k] = *(const PG8_LAS bf16x8*)(lds + PG8_SB(b, h) + boff + n * 2048 + k * 1024); } while (0)
; #define PG8_MMA(ai, bj, At, Bt) do { __builtin_amdgcn_s_setprio(1); _Pragma("unroll") for (int m = 0; m < 4; ++m) _Pragma("unroll") for (int n = 0; n < 2; ++n) _Pragma("unroll") for (int k = 0; k < 2; ++k) \
;         acc[ai][bj][m][n] = __builtin_amdgcn_mfma_f32_16x16x32_bf16(Bt[n][k], At[m][k], acc[ai][bj][m][n], 0, 0, 0); __builtin_amdgcn_s_setprio(0); } while (0)
; #define PG8_WAIT_V(n) asm volatile("s_waitcnt vmcnt(" #n ")" ::: "memory")
; #define PG8_WAIT_L(n) asm volatile("s_waitcnt lgkmcnt(" #n ")" ::: "memory")
; template <class Epi, class Sched, bool ALIGN_EPI = false, bool SP2 = false>
; __device__ __forceinline__ void gemm_phase(PG8_LAS unsigned char* lds, const Gemm g, const Sched& S, const Epi& E) {
;     ...
;             const bool last = (t == nt - 2);
;             const char* a1 = cA + (size_t)(t + 1) * kstep;
;             const char* a2 = last ? nA : cA + (size_t)(t + 2) * kstep; const char* b2 = last ? nB : cB + (size_t)(t + 2) * kstep;
;             const char* a3 = a2 + kstep; const char* b3 = b2 + kstep;
;             if (last && has_next) S.a_ready(nxt);
;             if constexpr (SP2) {
;             PG8_LDB(B0, 0, 0); PG8_LDB(B1, 0, 1); PG8_SCHED; PG8_LDA(At, 0, 0); PG8_STAGE(PG8_SA(1, 1), a1 + hstepA, voffA);
;             PG8_WAIT_V(8); PG8_WAIT_L(0); PG8_BAR; PG8_MMA(0, 0, At, B0); PG8_MMA(0, 1, At, B1); PG8_BAR; PG8_SCHED;
;             PG8_LDA(At, 0, 1); PG8_STAGE(PG8_SB(0, 0), b2, voffB); PG8_STAGE(PG8_SB(0, 1), b2 + hstepB, voffB); PG8_STAGE(PG8_SA(0, 0), a2, voffA);
;             PG8_WAIT_V(8); PG8_WAIT_L(0); PG8_BAR; PG8_MMA(1, 0, At, B0); PG8_MMA(1, 1, At, B1); PG8_BAR; PG8_SCHED;
.LBB0_724:
	ds_read_b128 v[144:147], v151
	ds_read_b128 v[156:159], v151 offset:1024
	ds_read_b128 v[160:163], v151 offset:2048
	ds_read_b128 v[164:167], v151 offset:3072
	ds_read_b128 v[168:171], v152
	ds_read_b128 v[172:175], v152 offset:1024
	ds_read_b128 v[176:179], v152 offset:2048
	ds_read_b128 v[180:183], v152 offset:3072
	s_add_u32 s44, s40, 0xfffc0080
	s_addc_u32 s45, s41, -1
	s_cmp_eq_u32 s63, 12
	s_cselect_b32 s49, s8, s45
	s_cselect_b32 s48, s9, s44
	s_cselect_b32 s45, s29, s62
	s_cselect_b32 s44, s31, s42
	s_add_i32 m0, s39, 0xc000
	ds_read_b128 v[184:187], v153
	ds_read_b128 v[188:191], v153 offset:1024
	ds_read_b128 v[194:197], v153 offset:2048
	ds_read_b128 v[198:201], v153 offset:3072
	ds_read_b128 v[202:205], v153 offset:4096
	ds_read_b128 v[206:209], v153 offset:5120
	ds_read_b128 v[210:213], v153 offset:6144
	ds_read_b128 v[214:217], v153 offset:7168
	global_load_lds_dwordx4 v136, s[40:41]
	s_add_i32 m0, s39, 0xe000
	s_nop 0
	global_load_lds_dwordx4 v138, s[40:41]
	s_waitcnt vmcnt(8)
	s_waitcnt lgkmcnt(0)
	s_barrier
	v_mfma_f32_16x16x32_bf16 v[124:127], v[144:147], v[184:187], v[124:127]
	v_mfma_f32_16x16x32_bf16 v[120:123], v[160:163], v[184:187], v[120:123]
	v_mfma_f32_16x16x32_bf16 v[108:111], v[144:147], v[194:197], v[108:111]
	v_mfma_f32_16x16x32_bf16 v[104:107], v[160:163], v[194:197], v[104:107]
	v_mfma_f32_16x16x32_bf16 v[92:95], v[144:147], v[202:205], v[92:95]
	v_mfma_f32_16x16x32_bf16 v[88:91], v[160:163], v[202:205], v[88:91]
	v_mfma_f32_16x16x32_bf16 v[76:79], v[144:147], v[210:213], v[76:79]
	v_mfma_f32_16x16x32_bf16 v[72:75], v[160:163], v[210:213], v[72:75]
	v_mfma_f32_16x16x32_bf16 v[124:127], v[156:159], v[188:191], v[124:127]
	v_mfma_f32_16x16x32_bf16 v[120:123], v[164:167], v[188:191], v[120:123]
	v_mfma_f32_16x16x32_bf16 v[108:111], v[156:159], v[198:201], v[108:111]
	v_mfma_f32_16x16x32_bf16 v[104:107], v[164:167], v[198:201], v[104:107]
	v_mfma_f32_16x16x32_bf16 v[92:95], v[156:159], v[206:209], v[92:95]
	v_mfma_f32_16x16x32_bf16 v[88:91], v[164:167], v[206:209], v[88:91]
	v_mfma_f32_16x16x32_bf16 v[76:79], v[156:159], v[214:217], v[76:79]
	v_mfma_f32_16x16x32_bf16 v[72:75], v[164:167], v[214:217], v[72:75]
	v_mfma_f32_16x16x32_bf16 v[116:119], v[168:171], v[184:187], v[116:119]
	v_mfma_f32_16x16x32_bf16 v[112:115], v[176:179], v[184:187], v[112:115]
	v_mfma_f32_16x16x32_bf16 v[100:103], v[168:171], v[194:197], v[100:103]
	v_mfma_f32_16x16x32_bf16 v[96:99], v[176:179], v[194:197], v[96:99]
	v_mfma_f32_16x16x32_bf16 v[84:87], v[168:171], v[202:205], v[84:87]
	v_mfma_f32_16x16x32_bf16 v[80:83], v[176:179], v[202:205], v[80:83]
	v_mfma_f32_16x16x32_bf16 v[68:71], v[168:171], v[210:213], v[68:71]
	v_mfma_f32_16x16x32_bf16 v[64:67], v[176:179], v[210:213], v[64:67]
	v_mfma_f32_16x16x32_bf16 v[116:119], v[172:175], v[188:191], v[116:119]
	v_mfma_f32_16x16x32_bf16 v[112:115], v[180:183], v[188:191], v[112:115]
	v_mfma_f32_16x16x32_bf16 v[100:103], v[172:175], v[198:201], v[100:103]
	v_mfma_f32_16x16x32_bf16 v[96:99], v[180:183], v[198:201], v[96:99]
	v_mfma_f32_16x16x32_bf16 v[84:87], v[172:175], v[206:209], v[84:87]
	v_mfma_f32_16x16x32_bf16 v[80:83], v[180:183], v[206:209], v[80:83]
	v_mfma_f32_16x16x32_bf16 v[68:71], v[172:175], v[214:217], v[68:71]
	v_mfma_f32_16x16x32_bf16 v[64:67], v[180:183], v[214:217], v[64:67]
	s_barrier
	s_add_i32 s64, s60, s50
	s_add_u32 s98, s44, s10
	s_addc_u32 s99, s45, s11
	s_mov_b32 m0, s64
	ds_read_b128 v[184:187], v153 offset:16384
	ds_read_b128 v[188:191], v153 offset:17408
	ds_read_b128 v[194:197], v153 offset:18432
	ds_read_b128 v[198:201], v153 offset:19456
	ds_read_b128 v[202:205], v153 offset:20480
	ds_read_b128 v[206:209], v153 offset:21504
	ds_read_b128 v[210:213], v153 offset:22528
	ds_read_b128 v[214:217], v153 offset:23552
	global_load_lds_dwordx4 v130, s[44:45]
	s_add_i32 m0, s64, 0x2000
	s_add_u32 s64, s44, 0x40000
	s_addc_u32 s65, s45, 0
	s_add_u32 s98, s44, s10
	s_addc_u32 s99, s45, s11
	s_add_i32 s66, s61, s50
	global_load_lds_dwordx4 v134, s[44:45]
	s_mov_b32 m0, s66
	s_add_u32 s100, s48, s10
	s_addc_u32 s101, s49, s11
	global_load_lds_dwordx4 v130, s[64:65]
	s_add_i32 m0, s66, 0x2000
	s_nop 0
	global_load_lds_dwordx4 v134, s[64:65]
	s_add_u32 s100, s48, s10
	s_addc_u32 s101, s49, s11
	s_mov_b32 m0, s39
	s_nop 0
	global_load_lds_dwordx4 v128, s[48:49]
	s_mov_b32 m0, s51
	s_nop 0
	global_load_lds_dwordx4 v132, s[48:49]
	s_waitcnt vmcnt(8)
	s_waitcnt lgkmcnt(0)
	s_barrier
	v_mfma_f32_16x16x32_bf16 v[60:63], v[144:147], v[184:187], v[60:63]
	v_mfma_f32_16x16x32_bf16 v[56:59], v[160:163], v[184:187], v[56:59]
	v_mfma_f32_16x16x32_bf16 v[44:47], v[144:147], v[194:197], v[44:47]
	v_mfma_f32_16x16x32_bf16 v[40:43], v[160:163], v[194:197], v[40:43]
	v_mfma_f32_16x16x32_bf16 v[28:31], v[144:147], v[202:205], v[28:31]
	v_mfma_f32_16x16x32_bf16 v[24:27], v[160:163], v[202:205], v[24:27]
	v_mfma_f32_16x16x32_bf16 v[12:15], v[144:147], v[210:213], v[12:15]
	v_mfma_f32_16x16x32_bf16 v[8:11], v[160:163], v[210:213], v[8:11]
	v_mfma_f32_16x16x32_bf16 v[60:63], v[156:159], v[188:191], v[60:63]
	v_mfma_f32_16x16x32_bf16 v[56:59], v[164:167], v[188:191], v[56:59]
	v_mfma_f32_16x16x32_bf16 v[44:47], v[156:159], v[198:201], v[44:47]
	v_mfma_f32_16x16x32_bf16 v[40:43], v[164:167], v[198:201], v[40:43]
	v_mfma_f32_16x16x32_bf16 v[28:31], v[156:159], v[206:209], v[28:31]
	v_mfma_f32_16x16x32_bf16 v[24:27], v[164:167], v[206:209], v[24:27]
	v_mfma_f32_16x16x32_bf16 v[12:15], v[156:159], v[214:217], v[12:15]
	v_mfma_f32_16x16x32_bf16 v[8:11], v[164:167], v[214:217], v[8:11]
	v_mfma_f32_16x16x32_bf16 v[52:55], v[168:171], v[184:187], v[52:55]
	v_mfma_f32_16x16x32_bf16 v[48:51], v[176:179], v[184:187], v[48:51]
	v_mfma_f32_16x16x32_bf16 v[36:39], v[168:171], v[194:197], v[36:39]
	v_mfma_f32_16x16x32_bf16 v[32:35], v[176:179], v[194:197], v[32:35]
	v_mfma_f32_16x16x32_bf16 v[20:23], v[168:171], v[202:205], v[20:23]
	v_mfma_f32_16x16x32_bf16 v[16:19], v[176:179], v[202:205], v[16:19]
	v_mfma_f32_16x16x32_bf16 v[4:7], v[168:171], v[210:213], v[4:7]
	v_mfma_f32_16x16x32_bf16 v[0:3], v[176:179], v[210:213], v[0:3]
	v_mfma_f32_16x16x32_bf16 v[52:55], v[172:175], v[188:191], v[52:55]
	v_mfma_f32_16x16x32_bf16 v[48:51], v[180:183], v[188:191], v[48:51]
	v_mfma_f32_16x16x32_bf16 v[36:39], v[172:175], v[198:201], v[36:39]
	v_mfma_f32_16x16x32_bf16 v[32:35], v[180:183], v[198:201], v[32:35]
	v_mfma_f32_16x16x32_bf16 v[20:23], v[172:175], v[206:209], v[20:23]
	v_mfma_f32_16x16x32_bf16 v[16:19], v[180:183], v[206:209], v[16:19]
	v_mfma_f32_16x16x32_bf16 v[4:7], v[172:175], v[214:217], v[4:7]
	v_mfma_f32_16x16x32_bf16 v[0:3], v[180:183], v[214:217], v[0:3]
	s_barrier
; #define PG8_STAGE(bufoff, gbase, voff) do { _Pragma("unroll") for (int _i = 0; _i < 2; ++_i) \
;         __builtin_amdgcn_global_load_lds((const unsigned*)((const char*)(gbase) + (voff)[_i]), (PG8_LAS unsigned*)(lds + (bufoff) + ldsw + _i * 8192), 16, 0, 0); } while (0)
; #define PG8_LDA(dst, b, h) do { _Pragma("unroll") for (int m = 0; m < 4; ++m) _Pragma("unroll") for (int k = 0; k < 2; ++k) dst[m][k] = *(const PG8_LAS bf16x8*)(lds + PG8_SA(b, h) + aoff + m * 2048 + k * 1024); } while (0)
; #define PG8_LDB(dst, b, h) do { _Pragma("unroll") for (int n = 0; n < 2; ++n) _Pragma("unroll") for (int k = 0; k < 2; ++k) dst[n][k] = *(const PG8_LAS bf16x8*)(lds + PG8_SB(b, h) + boff + n * 2048 + k * 1024); } while (0)
; #define PG8_MMA(ai, bj, At, Bt) do { __builtin_amdgcn_s_setprio(1); _Pragma("unroll") for (int m = 0; m < 4; ++m) _Pragma("unroll") for (int n = 0; n < 2; ++n) _Pragma("unroll") for (int k = 0; k < 2; ++k) \
;         acc[ai][bj][m][n] = __builtin_amdgcn_mfma_f32_16x16x32_bf16(Bt[n][k], At[m][k], acc[ai][bj][m][n], 0, 0, 0); __builtin_amdgcn_s_setprio(0); } while (0)
; #define PG8_WAIT_V(n) asm volatile("s_waitcnt vmcnt(" #n ")" ::: "memory")
; #define PG8_WAIT_L(n) asm volatile("s_waitcnt lgkmcnt(" #n ")" ::: "memory")
; #define PG8_BAR __builtin_amdgcn_s_barrier()
; #define PG8_SCHED __builtin_amdgcn_sched_barrier(0)
; template <class Epi, class Sched, bool ALIGN_EPI = false, bool SP2 = false>
; __device__ __forceinline__ void gemm_phase(PG8_LAS unsigned char* lds, const Gemm g, const Sched& S, const Epi& E) {
;     ...
;             PG8_LDB(B0, 1, 0); PG8_LDB(B1, 1, 1); PG8_SCHED; PG8_LDA(At, 1, 0); PG8_STAGE(PG8_SA(0, 1), a2 + hstepA, voffA);
;             PG8_WAIT_V(8); PG8_WAIT_L(0); PG8_BAR; PG8_MMA(0, 0, At, B0); PG8_MMA(0, 1, At, B1); PG8_BAR; PG8_SCHED;
;             PG8_LDA(At, 1, 1); PG8_STAGE(PG8_SB(1, 0), b3, voffB); PG8_STAGE(PG8_SB(1, 1), b3 + hstepB, voffB); PG8_STAGE(PG8_SA(1, 0), a3, voffA);
;             PG8_WAIT_V(8); PG8_WAIT_L(0); PG8_BAR; PG8_MMA(1, 0, At, B0); PG8_MMA(1, 1, At, B1); PG8_BAR; PG8_SCHED;
	s_add_i32 s64, 0, 0x18000
	v_add_u32_e32 v155, s64, v150
	s_add_i32 s65, 0, 0x1c000
	ds_read_b128 v[144:147], v155
	ds_read_b128 v[156:159], v155 offset:1024
	ds_read_b128 v[160:163], v155 offset:2048
	ds_read_b128 v[164:167], v155 offset:3072
	v_add_u32_e32 v155, s65, v150
	ds_read_b128 v[168:171], v155
	ds_read_b128 v[172:175], v155 offset:1024
	ds_read_b128 v[176:179], v155 offset:2048
	ds_read_b128 v[180:183], v155 offset:3072
	s_add_u32 s48, s48, 0x40000
	s_addc_u32 s49, s49, 0
	s_mov_b32 m0, s52
	ds_read_b128 v[184:187], v153 offset:32768
	ds_read_b128 v[188:191], v153 offset:33792
	ds_read_b128 v[194:197], v153 offset:34816
	ds_read_b128 v[198:201], v153 offset:35840
	ds_read_b128 v[202:205], v153 offset:36864
	ds_read_b128 v[206:209], v153 offset:37888
	ds_read_b128 v[210:213], v153 offset:38912
	ds_read_b128 v[214:217], v153 offset:39936
	global_load_lds_dwordx4 v128, s[48:49]
	s_mov_b32 m0, s53
	s_nop 0
	global_load_lds_dwordx4 v132, s[48:49]
	s_waitcnt vmcnt(8)
	s_waitcnt lgkmcnt(0)
	s_barrier
	v_mfma_f32_16x16x32_bf16 v[124:127], v[144:147], v[184:187], v[124:127]
	v_mfma_f32_16x16x32_bf16 v[120:123], v[160:163], v[184:187], v[120:123]
	v_mfma_f32_16x16x32_bf16 v[108:111], v[144:147], v[194:197], v[108:111]
	v_mfma_f32_16x16x32_bf16 v[104:107], v[160:163], v[194:197], v[104:107]
	v_mfma_f32_16x16x32_bf16 v[92:95], v[144:147], v[202:205], v[92:95]
	v_mfma_f32_16x16x32_bf16 v[88:91], v[160:163], v[202:205], v[88:91]
	v_mfma_f32_16x16x32_bf16 v[76:79], v[144:147], v[210:213], v[76:79]
	v_mfma_f32_16x16x32_bf16 v[72:75], v[160:163], v[210:213], v[72:75]
	v_mfma_f32_16x16x32_bf16 v[124:127], v[156:159], v[188:191], v[124:127]
	v_mfma_f32_16x16x32_bf16 v[120:123], v[164:167], v[188:191], v[120:123]
	v_mfma_f32_16x16x32_bf16 v[108:111], v[156:159], v[198:201], v[108:111]
	v_mfma_f32_16x16x32_bf16 v[104:107], v[164:167], v[198:201], v[104:107]
	v_mfma_f32_16x16x32_bf16 v[92:95], v[156:159], v[206:209], v[92:95]
	v_mfma_f32_16x16x32_bf16 v[88:91], v[164:167], v[206:209], v[88:91]
	v_mfma_f32_16x16x32_bf16 v[76:79], v[156:159], v[214:217], v[76:79]
	v_mfma_f32_16x16x32_bf16 v[72:75], v[164:167], v[214:217], v[72:75]
	v_mfma_f32_16x16x32_bf16 v[116:119], v[168:171], v[184:187], v[116:119]
	v_mfma_f32_16x16x32_bf16 v[112:115], v[176:179], v[184:187], v[112:115]
	v_mfma_f32_16x16x32_bf16 v[100:103], v[168:171], v[194:197], v[100:103]
	v_mfma_f32_16x16x32_bf16 v[96:99], v[176:179], v[194:197], v[96:99]
	v_mfma_f32_16x16x32_bf16 v[84:87], v[168:171], v[202:205], v[84:87]
	v_mfma_f32_16x16x32_bf16 v[80:83], v[176:179], v[202:205], v[80:83]
	v_mfma_f32_16x16x32_bf16 v[68:71], v[168:171], v[210:213], v[68:71]
	v_mfma_f32_16x16x32_bf16 v[64:67], v[176:179], v[210:213], v[64:67]
	v_mfma_f32_16x16x32_bf16 v[116:119], v[172:175], v[188:191], v[116:119]
	v_mfma_f32_16x16x32_bf16 v[112:115], v[180:183], v[188:191], v[112:115]
	v_mfma_f32_16x16x32_bf16 v[100:103], v[172:175], v[198:201], v[100:103]
	v_mfma_f32_16x16x32_bf16 v[96:99], v[180:183], v[198:201], v[96:99]
	v_mfma_f32_16x16x32_bf16 v[84:87], v[172:175], v[206:209], v[84:87]
	v_mfma_f32_16x16x32_bf16 v[80:83], v[180:183], v[206:209], v[80:83]
	v_mfma_f32_16x16x32_bf16 v[68:71], v[172:175], v[214:217], v[68:71]
	v_mfma_f32_16x16x32_bf16 v[64:67], v[180:183], v[214:217], v[64:67]
	s_barrier
	s_add_i32 s48, s64, s50
	s_mov_b32 m0, s48
	ds_read_b128 v[184:187], v153 offset:49152
	ds_read_b128 v[188:191], v153 offset:50176
	ds_read_b128 v[194:197], v153 offset:51200
	ds_read_b128 v[198:201], v153 offset:52224
	ds_read_b128 v[202:205], v153 offset:53248
	ds_read_b128 v[206:209], v153 offset:54272
	ds_read_b128 v[210:213], v153 offset:55296
	ds_read_b128 v[214:217], v153 offset:56320
	global_load_lds_dwordx4 v130, s[98:99]
	s_add_i32 m0, s48, 0x2000
	s_add_u32 s44, s44, 0x40080
	s_addc_u32 s45, s45, 0
	s_add_i32 s48, s65, s50
	global_load_lds_dwordx4 v134, s[98:99]
	s_mov_b32 m0, s48
	s_nop 0
	global_load_lds_dwordx4 v130, s[44:45]
	s_add_i32 m0, s48, 0x2000
	s_nop 0
	global_load_lds_dwordx4 v134, s[44:45]
	s_mov_b32 m0, s57
	s_nop 0
	global_load_lds_dwordx4 v128, s[100:101]
	s_mov_b32 m0, s58
	s_nop 0
	global_load_lds_dwordx4 v132, s[100:101]
	s_waitcnt vmcnt(8)
	s_waitcnt lgkmcnt(0)
	s_barrier
	v_mfma_f32_16x16x32_bf16 v[60:63], v[144:147], v[184:187], v[60:63]
	v_mfma_f32_16x16x32_bf16 v[56:59], v[160:163], v[184:187], v[56:59]
	v_mfma_f32_16x16x32_bf16 v[44:47], v[144:147], v[194:197], v[44:47]
	v_mfma_f32_16x16x32_bf16 v[40:43], v[160:163], v[194:197], v[40:43]
	v_mfma_f32_16x16x32_bf16 v[28:31], v[144:147], v[202:205], v[28:31]
	v_mfma_f32_16x16x32_bf16 v[24:27], v[160:163], v[202:205], v[24:27]
	v_mfma_f32_16x16x32_bf16 v[12:15], v[144:147], v[210:213], v[12:15]
	v_mfma_f32_16x16x32_bf16 v[8:11], v[160:163], v[210:213], v[8:11]
	v_mfma_f32_16x16x32_bf16 v[60:63], v[156:159], v[188:191], v[60:63]
	v_mfma_f32_16x16x32_bf16 v[56:59], v[164:167], v[188:191], v[56:59]
	v_mfma_f32_16x16x32_bf16 v[44:47], v[156:159], v[198:201], v[44:47]
	v_mfma_f32_16x16x32_bf16 v[40:43], v[164:167], v[198:201], v[40:43]
	v_mfma_f32_16x16x32_bf16 v[28:31], v[156:159], v[206:209], v[28:31]
	v_mfma_f32_16x16x32_bf16 v[24:27], v[164:167], v[206:209], v[24:27]
	v_mfma_f32_16x16x32_bf16 v[12:15], v[156:159], v[214:217], v[12:15]
	v_mfma_f32_16x16x32_bf16 v[8:11], v[164:167], v[214:217], v[8:11]
	v_mfma_f32_16x16x32_bf16 v[52:55], v[168:171], v[184:187], v[52:55]
	v_mfma_f32_16x16x32_bf16 v[48:51], v[176:179], v[184:187], v[48:51]
	v_mfma_f32_16x16x32_bf16 v[36:39], v[168:171], v[194:197], v[36:39]
	v_mfma_f32_16x16x32_bf16 v[32:35], v[176:179], v[194:197], v[32:35]
	v_mfma_f32_16x16x32_bf16 v[20:23], v[168:171], v[202:205], v[20:23]
	v_mfma_f32_16x16x32_bf16 v[16:19], v[176:179], v[202:205], v[16:19]
	v_mfma_f32_16x16x32_bf16 v[4:7], v[168:171], v[210:213], v[4:7]
	v_mfma_f32_16x16x32_bf16 v[0:3], v[176:179], v[210:213], v[0:3]
	v_mfma_f32_16x16x32_bf16 v[52:55], v[172:175], v[188:191], v[52:55]
	v_mfma_f32_16x16x32_bf16 v[48:51], v[180:183], v[188:191], v[48:51]
	v_mfma_f32_16x16x32_bf16 v[36:39], v[172:175], v[198:201], v[36:39]
	v_mfma_f32_16x16x32_bf16 v[32:35], v[180:183], v[198:201], v[32:35]
	v_mfma_f32_16x16x32_bf16 v[20:23], v[172:175], v[206:209], v[20:23]
	v_mfma_f32_16x16x32_bf16 v[16:19], v[180:183], v[206:209], v[16:19]
	v_mfma_f32_16x16x32_bf16 v[4:7], v[172:175], v[214:217], v[4:7]
	v_mfma_f32_16x16x32_bf16 v[0:3], v[180:183], v[214:217], v[0:3]
	s_barrier
	s_add_i32 s63, s63, 2
	s_add_u32 s40, s40, 0x100
	s_addc_u32 s41, s41, 0
	s_add_u32 s42, s42, 0x100
	s_addc_u32 s62, s62, 0
	s_cmp_gt_u32 s63, 13
	s_cbranch_scc0 .LBB0_724
	s_and_b64 vcc, exec, s[12:13]
	s_cbranch_vccz .LBB0_727
	s_barrier
